# epilogue residual-load prefetch in gm_out, ffn_down L0/L1, s5_out (x-form loads hoisted before ALIGN barrier)
# baseline (speedup 1.0000x reference)
.LBB0_337:
	ds_read_b128 v[144:147], v151
	ds_read_b128 v[156:159], v151 offset:1024
	ds_read_b128 v[160:163], v151 offset:2048
	ds_read_b128 v[164:167], v151 offset:3072
	ds_read_b128 v[168:171], v152
	ds_read_b128 v[172:175], v152 offset:1024
	ds_read_b128 v[176:179], v152 offset:2048
	ds_read_b128 v[180:183], v152 offset:3072
	s_add_u32 s50, s48, 0xfff80080
	s_addc_u32 s51, s49, -1
	s_cmp_eq_u32 s75, 28
	s_cselect_b32 s53, s31, s51
	s_cselect_b32 s52, s47, s50
	s_cselect_b32 s51, s27, s74
	s_cselect_b32 s50, s71, s72
	v_lshl_add_u64 v[216:217], s[48:49], 0, v[138:139]
	s_add_i32 m0, s57, 0xc000
	ds_read_b128 v[184:187], v153
	ds_read_b128 v[188:191], v153 offset:1024
	ds_read_b128 v[192:195], v153 offset:2048
	ds_read_b128 v[196:199], v153 offset:3072
	ds_read_b128 v[200:203], v153 offset:4096
	ds_read_b128 v[204:207], v153 offset:5120
	ds_read_b128 v[208:211], v153 offset:6144
	ds_read_b128 v[212:215], v153 offset:7168
	global_load_lds_dwordx4 v[216:217], off
	v_lshl_add_u64 v[216:217], s[48:49], 0, v[136:137]
	s_add_i32 m0, s57, 0xe000
	s_nop 0
	global_load_lds_dwordx4 v[216:217], off
	s_waitcnt vmcnt(8)
	s_waitcnt lgkmcnt(0)
	s_barrier
	s_setprio 1
	s_waitcnt lgkmcnt(0)
	v_mfma_f32_16x16x32_bf16 v[124:127], v[144:147], v[184:187], v[124:127]
	v_mfma_f32_16x16x32_bf16 v[120:123], v[160:163], v[184:187], v[120:123]
	v_mfma_f32_16x16x32_bf16 v[108:111], v[144:147], v[192:195], v[108:111]
	v_mfma_f32_16x16x32_bf16 v[104:107], v[160:163], v[192:195], v[104:107]
	v_mfma_f32_16x16x32_bf16 v[92:95], v[144:147], v[200:203], v[92:95]
	v_mfma_f32_16x16x32_bf16 v[88:91], v[160:163], v[200:203], v[88:91]
	v_mfma_f32_16x16x32_bf16 v[76:79], v[144:147], v[208:211], v[76:79]
	v_mfma_f32_16x16x32_bf16 v[72:75], v[160:163], v[208:211], v[72:75]
	v_mfma_f32_16x16x32_bf16 v[124:127], v[156:159], v[188:191], v[124:127]
	v_mfma_f32_16x16x32_bf16 v[120:123], v[164:167], v[188:191], v[120:123]
	v_mfma_f32_16x16x32_bf16 v[108:111], v[156:159], v[196:199], v[108:111]
	v_mfma_f32_16x16x32_bf16 v[104:107], v[164:167], v[196:199], v[104:107]
	v_mfma_f32_16x16x32_bf16 v[92:95], v[156:159], v[204:207], v[92:95]
	v_mfma_f32_16x16x32_bf16 v[88:91], v[164:167], v[204:207], v[88:91]
	v_mfma_f32_16x16x32_bf16 v[76:79], v[156:159], v[212:215], v[76:79]
	v_mfma_f32_16x16x32_bf16 v[72:75], v[164:167], v[212:215], v[72:75]
	s_setprio 0
	s_setprio 1
	v_mfma_f32_16x16x32_bf16 v[116:119], v[168:171], v[184:187], v[116:119]
	v_mfma_f32_16x16x32_bf16 v[112:115], v[176:179], v[184:187], v[112:115]
	v_mfma_f32_16x16x32_bf16 v[100:103], v[168:171], v[192:195], v[100:103]
	v_mfma_f32_16x16x32_bf16 v[96:99], v[176:179], v[192:195], v[96:99]
	v_mfma_f32_16x16x32_bf16 v[84:87], v[168:171], v[200:203], v[84:87]
	v_mfma_f32_16x16x32_bf16 v[80:83], v[176:179], v[200:203], v[80:83]
	v_mfma_f32_16x16x32_bf16 v[68:71], v[168:171], v[208:211], v[68:71]
	v_mfma_f32_16x16x32_bf16 v[64:67], v[176:179], v[208:211], v[64:67]
	v_mfma_f32_16x16x32_bf16 v[116:119], v[172:175], v[188:191], v[116:119]
	v_mfma_f32_16x16x32_bf16 v[112:115], v[180:183], v[188:191], v[112:115]
	v_mfma_f32_16x16x32_bf16 v[100:103], v[172:175], v[196:199], v[100:103]
	v_mfma_f32_16x16x32_bf16 v[96:99], v[180:183], v[196:199], v[96:99]
	v_mfma_f32_16x16x32_bf16 v[84:87], v[172:175], v[204:207], v[84:87]
	v_mfma_f32_16x16x32_bf16 v[80:83], v[180:183], v[204:207], v[80:83]
	v_mfma_f32_16x16x32_bf16 v[68:71], v[172:175], v[212:215], v[68:71]
	v_mfma_f32_16x16x32_bf16 v[64:67], v[180:183], v[212:215], v[64:67]
	s_setprio 0
	s_barrier
	s_add_i32 s76, s66, s56
	v_lshl_add_u64 v[216:217], s[50:51], 0, v[130:131]
	s_mov_b32 m0, s76
	ds_read_b128 v[184:187], v153 offset:16384
	ds_read_b128 v[188:191], v153 offset:17408
	ds_read_b128 v[192:195], v153 offset:18432
	ds_read_b128 v[196:199], v153 offset:19456
	ds_read_b128 v[200:203], v153 offset:20480
	ds_read_b128 v[204:207], v153 offset:21504
	ds_read_b128 v[208:211], v153 offset:22528
	ds_read_b128 v[212:215], v153 offset:23552
	global_load_lds_dwordx4 v[216:217], off
	s_add_i32 m0, s76, 0x2000
	s_add_u32 s76, s50, 0x80000
	v_lshl_add_u64 v[218:219], s[50:51], 0, v[134:135]
	s_addc_u32 s77, s51, 0
	s_add_i32 s78, s67, s56
	global_load_lds_dwordx4 v[218:219], off
	v_lshl_add_u64 v[220:221], s[76:77], 0, v[130:131]
	s_mov_b32 m0, s78
	v_lshl_add_u64 v[222:223], s[52:53], 0, v[132:133]
	global_load_lds_dwordx4 v[220:221], off
	v_lshl_add_u64 v[220:221], s[76:77], 0, v[134:135]
	s_add_i32 m0, s78, 0x2000
	s_nop 0
	global_load_lds_dwordx4 v[220:221], off
	v_lshl_add_u64 v[220:221], s[52:53], 0, v[128:129]
	s_mov_b32 m0, s57
	s_nop 0
	global_load_lds_dwordx4 v[220:221], off
	s_mov_b32 m0, s58
	s_nop 0
	global_load_lds_dwordx4 v[222:223], off
	s_waitcnt vmcnt(8)
	s_waitcnt lgkmcnt(0)
	s_barrier
	s_setprio 1
	s_waitcnt lgkmcnt(0)
	v_mfma_f32_16x16x32_bf16 v[60:63], v[144:147], v[184:187], v[60:63]
	v_mfma_f32_16x16x32_bf16 v[56:59], v[160:163], v[184:187], v[56:59]
	v_mfma_f32_16x16x32_bf16 v[44:47], v[144:147], v[192:195], v[44:47]
	v_mfma_f32_16x16x32_bf16 v[40:43], v[160:163], v[192:195], v[40:43]
	v_mfma_f32_16x16x32_bf16 v[28:31], v[144:147], v[200:203], v[28:31]
	v_mfma_f32_16x16x32_bf16 v[24:27], v[160:163], v[200:203], v[24:27]
	v_mfma_f32_16x16x32_bf16 v[12:15], v[144:147], v[208:211], v[12:15]
	v_mfma_f32_16x16x32_bf16 v[8:11], v[160:163], v[208:211], v[8:11]
	v_mfma_f32_16x16x32_bf16 v[60:63], v[156:159], v[188:191], v[60:63]
	v_mfma_f32_16x16x32_bf16 v[56:59], v[164:167], v[188:191], v[56:59]
	v_mfma_f32_16x16x32_bf16 v[44:47], v[156:159], v[196:199], v[44:47]
	v_mfma_f32_16x16x32_bf16 v[40:43], v[164:167], v[196:199], v[40:43]
	v_mfma_f32_16x16x32_bf16 v[28:31], v[156:159], v[204:207], v[28:31]
	v_mfma_f32_16x16x32_bf16 v[24:27], v[164:167], v[204:207], v[24:27]
	v_mfma_f32_16x16x32_bf16 v[12:15], v[156:159], v[212:215], v[12:15]
	v_mfma_f32_16x16x32_bf16 v[8:11], v[164:167], v[212:215], v[8:11]
	s_setprio 0
	s_setprio 1
	v_mfma_f32_16x16x32_bf16 v[52:55], v[168:171], v[184:187], v[52:55]
	v_mfma_f32_16x16x32_bf16 v[48:51], v[176:179], v[184:187], v[48:51]
	v_mfma_f32_16x16x32_bf16 v[36:39], v[168:171], v[192:195], v[36:39]
	v_mfma_f32_16x16x32_bf16 v[32:35], v[176:179], v[192:195], v[32:35]
	v_mfma_f32_16x16x32_bf16 v[20:23], v[168:171], v[200:203], v[20:23]
	v_mfma_f32_16x16x32_bf16 v[16:19], v[176:179], v[200:203], v[16:19]
	v_mfma_f32_16x16x32_bf16 v[4:7], v[168:171], v[208:211], v[4:7]
	v_mfma_f32_16x16x32_bf16 v[0:3], v[176:179], v[208:211], v[0:3]
	v_mfma_f32_16x16x32_bf16 v[52:55], v[172:175], v[188:191], v[52:55]
	v_mfma_f32_16x16x32_bf16 v[48:51], v[180:183], v[188:191], v[48:51]
	v_mfma_f32_16x16x32_bf16 v[36:39], v[172:175], v[196:199], v[36:39]
	v_mfma_f32_16x16x32_bf16 v[32:35], v[180:183], v[196:199], v[32:35]
	v_mfma_f32_16x16x32_bf16 v[20:23], v[172:175], v[204:207], v[20:23]
	v_mfma_f32_16x16x32_bf16 v[16:19], v[180:183], v[204:207], v[16:19]
	v_mfma_f32_16x16x32_bf16 v[4:7], v[172:175], v[212:215], v[4:7]
	v_mfma_f32_16x16x32_bf16 v[0:3], v[180:183], v[212:215], v[0:3]
	s_setprio 0
	s_barrier
	s_add_i32 s76, 0, 0x18000
	v_add_u32_e32 v155, s76, v149
	s_add_i32 s77, 0, 0x1c000
	ds_read_b128 v[144:147], v155
	ds_read_b128 v[156:159], v155 offset:1024
	ds_read_b128 v[160:163], v155 offset:2048
	ds_read_b128 v[164:167], v155 offset:3072
	v_add_u32_e32 v155, s77, v149
	ds_read_b128 v[168:171], v155
	ds_read_b128 v[172:175], v155 offset:1024
	ds_read_b128 v[176:179], v155 offset:2048
	ds_read_b128 v[180:183], v155 offset:3072
	s_add_u32 s52, s52, 0x80000
	s_addc_u32 s53, s53, 0
	s_mov_b32 m0, s59
	v_lshl_add_u64 v[224:225], s[52:53], 0, v[128:129]
	ds_read_b128 v[184:187], v153 offset:32768
	ds_read_b128 v[188:191], v153 offset:33792
	ds_read_b128 v[192:195], v153 offset:34816
	ds_read_b128 v[196:199], v153 offset:35840
	ds_read_b128 v[200:203], v153 offset:36864
	ds_read_b128 v[204:207], v153 offset:37888
	ds_read_b128 v[208:211], v153 offset:38912
	ds_read_b128 v[212:215], v153 offset:39936
	global_load_lds_dwordx4 v[224:225], off
	v_lshl_add_u64 v[224:225], s[52:53], 0, v[132:133]
	s_mov_b32 m0, s60
	s_nop 0
	global_load_lds_dwordx4 v[224:225], off
	s_waitcnt vmcnt(8)
	s_waitcnt lgkmcnt(0)
	s_barrier
	s_setprio 1
	s_waitcnt lgkmcnt(0)
	v_mfma_f32_16x16x32_bf16 v[124:127], v[144:147], v[184:187], v[124:127]
	v_mfma_f32_16x16x32_bf16 v[120:123], v[160:163], v[184:187], v[120:123]
	v_mfma_f32_16x16x32_bf16 v[108:111], v[144:147], v[192:195], v[108:111]
	v_mfma_f32_16x16x32_bf16 v[104:107], v[160:163], v[192:195], v[104:107]
	v_mfma_f32_16x16x32_bf16 v[92:95], v[144:147], v[200:203], v[92:95]
	v_mfma_f32_16x16x32_bf16 v[88:91], v[160:163], v[200:203], v[88:91]
	v_mfma_f32_16x16x32_bf16 v[76:79], v[144:147], v[208:211], v[76:79]
	v_mfma_f32_16x16x32_bf16 v[72:75], v[160:163], v[208:211], v[72:75]
	v_mfma_f32_16x16x32_bf16 v[124:127], v[156:159], v[188:191], v[124:127]
	v_mfma_f32_16x16x32_bf16 v[120:123], v[164:167], v[188:191], v[120:123]
	v_mfma_f32_16x16x32_bf16 v[108:111], v[156:159], v[196:199], v[108:111]
	v_mfma_f32_16x16x32_bf16 v[104:107], v[164:167], v[196:199], v[104:107]
	v_mfma_f32_16x16x32_bf16 v[92:95], v[156:159], v[204:207], v[92:95]
	v_mfma_f32_16x16x32_bf16 v[88:91], v[164:167], v[204:207], v[88:91]
	v_mfma_f32_16x16x32_bf16 v[76:79], v[156:159], v[212:215], v[76:79]
	v_mfma_f32_16x16x32_bf16 v[72:75], v[164:167], v[212:215], v[72:75]
	s_setprio 0
	s_setprio 1
	v_mfma_f32_16x16x32_bf16 v[116:119], v[168:171], v[184:187], v[116:119]
	v_mfma_f32_16x16x32_bf16 v[112:115], v[176:179], v[184:187], v[112:115]
	v_mfma_f32_16x16x32_bf16 v[100:103], v[168:171], v[192:195], v[100:103]
	v_mfma_f32_16x16x32_bf16 v[96:99], v[176:179], v[192:195], v[96:99]
	v_mfma_f32_16x16x32_bf16 v[84:87], v[168:171], v[200:203], v[84:87]
	v_mfma_f32_16x16x32_bf16 v[80:83], v[176:179], v[200:203], v[80:83]
	v_mfma_f32_16x16x32_bf16 v[68:71], v[168:171], v[208:211], v[68:71]
	v_mfma_f32_16x16x32_bf16 v[64:67], v[176:179], v[208:211], v[64:67]
	v_mfma_f32_16x16x32_bf16 v[116:119], v[172:175], v[188:191], v[116:119]
	v_mfma_f32_16x16x32_bf16 v[112:115], v[180:183], v[188:191], v[112:115]
	v_mfma_f32_16x16x32_bf16 v[100:103], v[172:175], v[196:199], v[100:103]
	v_mfma_f32_16x16x32_bf16 v[96:99], v[180:183], v[196:199], v[96:99]
	v_mfma_f32_16x16x32_bf16 v[84:87], v[172:175], v[204:207], v[84:87]
	v_mfma_f32_16x16x32_bf16 v[80:83], v[180:183], v[204:207], v[80:83]
	v_mfma_f32_16x16x32_bf16 v[68:71], v[172:175], v[212:215], v[68:71]
	v_mfma_f32_16x16x32_bf16 v[64:67], v[180:183], v[212:215], v[64:67]
	s_setprio 0
	s_barrier
	s_add_i32 s52, s76, s56
	v_lshl_add_u64 v[216:217], v[216:217], 0, s[22:23]
	s_mov_b32 m0, s52
	ds_read_b128 v[184:187], v153 offset:49152
	ds_read_b128 v[188:191], v153 offset:50176
	ds_read_b128 v[192:195], v153 offset:51200
	ds_read_b128 v[196:199], v153 offset:52224
	ds_read_b128 v[200:203], v153 offset:53248
	ds_read_b128 v[204:207], v153 offset:54272
	ds_read_b128 v[208:211], v153 offset:55296
	ds_read_b128 v[212:215], v153 offset:56320
	global_load_lds_dwordx4 v[216:217], off
	s_add_i32 m0, s52, 0x2000
	s_add_u32 s50, s50, 0x80080
	v_lshl_add_u64 v[216:217], v[218:219], 0, s[22:23]
	s_addc_u32 s51, s51, 0
	s_add_i32 s52, s77, s56
	global_load_lds_dwordx4 v[216:217], off
	v_lshl_add_u64 v[216:217], s[50:51], 0, v[130:131]
	s_mov_b32 m0, s52
	s_nop 0
	global_load_lds_dwordx4 v[216:217], off
	v_lshl_add_u64 v[216:217], s[50:51], 0, v[134:135]
	s_add_i32 m0, s52, 0x2000
	s_nop 0
	global_load_lds_dwordx4 v[216:217], off
	v_lshl_add_u64 v[216:217], v[220:221], 0, s[22:23]
	s_mov_b32 m0, s62
	s_nop 0
	global_load_lds_dwordx4 v[216:217], off
	v_lshl_add_u64 v[216:217], v[222:223], 0, s[22:23]
	s_mov_b32 m0, s63
	s_nop 0
	global_load_lds_dwordx4 v[216:217], off
	s_waitcnt vmcnt(8)
	s_waitcnt lgkmcnt(0)
	s_barrier
	s_setprio 1
	s_waitcnt lgkmcnt(0)
	v_mfma_f32_16x16x32_bf16 v[60:63], v[144:147], v[184:187], v[60:63]
	v_mfma_f32_16x16x32_bf16 v[56:59], v[160:163], v[184:187], v[56:59]
	v_mfma_f32_16x16x32_bf16 v[44:47], v[144:147], v[192:195], v[44:47]
	v_mfma_f32_16x16x32_bf16 v[40:43], v[160:163], v[192:195], v[40:43]
	v_mfma_f32_16x16x32_bf16 v[28:31], v[144:147], v[200:203], v[28:31]
	v_mfma_f32_16x16x32_bf16 v[24:27], v[160:163], v[200:203], v[24:27]
	v_mfma_f32_16x16x32_bf16 v[12:15], v[144:147], v[208:211], v[12:15]
	v_mfma_f32_16x16x32_bf16 v[8:11], v[160:163], v[208:211], v[8:11]
	v_mfma_f32_16x16x32_bf16 v[60:63], v[156:159], v[188:191], v[60:63]
	v_mfma_f32_16x16x32_bf16 v[56:59], v[164:167], v[188:191], v[56:59]
	v_mfma_f32_16x16x32_bf16 v[44:47], v[156:159], v[196:199], v[44:47]
	v_mfma_f32_16x16x32_bf16 v[40:43], v[164:167], v[196:199], v[40:43]
	v_mfma_f32_16x16x32_bf16 v[28:31], v[156:159], v[204:207], v[28:31]
	v_mfma_f32_16x16x32_bf16 v[24:27], v[164:167], v[204:207], v[24:27]
	v_mfma_f32_16x16x32_bf16 v[12:15], v[156:159], v[212:215], v[12:15]
	v_mfma_f32_16x16x32_bf16 v[8:11], v[164:167], v[212:215], v[8:11]
	s_setprio 0
	s_setprio 1
	v_mfma_f32_16x16x32_bf16 v[52:55], v[168:171], v[184:187], v[52:55]
	v_mfma_f32_16x16x32_bf16 v[48:51], v[176:179], v[184:187], v[48:51]
	v_mfma_f32_16x16x32_bf16 v[36:39], v[168:171], v[192:195], v[36:39]
	v_mfma_f32_16x16x32_bf16 v[32:35], v[176:179], v[192:195], v[32:35]
	v_mfma_f32_16x16x32_bf16 v[20:23], v[168:171], v[200:203], v[20:23]
	v_mfma_f32_16x16x32_bf16 v[16:19], v[176:179], v[200:203], v[16:19]
	v_mfma_f32_16x16x32_bf16 v[4:7], v[168:171], v[208:211], v[4:7]
	v_mfma_f32_16x16x32_bf16 v[0:3], v[176:179], v[208:211], v[0:3]
	v_mfma_f32_16x16x32_bf16 v[52:55], v[172:175], v[188:191], v[52:55]
	v_mfma_f32_16x16x32_bf16 v[48:51], v[180:183], v[188:191], v[48:51]
	v_mfma_f32_16x16x32_bf16 v[36:39], v[172:175], v[196:199], v[36:39]
	v_mfma_f32_16x16x32_bf16 v[32:35], v[180:183], v[196:199], v[32:35]
	v_mfma_f32_16x16x32_bf16 v[20:23], v[172:175], v[204:207], v[20:23]
	v_mfma_f32_16x16x32_bf16 v[16:19], v[180:183], v[204:207], v[16:19]
	v_mfma_f32_16x16x32_bf16 v[4:7], v[172:175], v[212:215], v[4:7]
	v_mfma_f32_16x16x32_bf16 v[0:3], v[180:183], v[212:215], v[0:3]
	s_setprio 0
	s_barrier
	s_add_i32 s75, s75, 2
	s_add_u32 s72, s72, 0x100
	s_addc_u32 s74, s74, 0
	s_add_u32 s48, s48, 0x100
	s_addc_u32 s49, s49, 0
	s_cmp_gt_u32 s75, 29
	s_cbranch_scc0 .LBB0_337
	v_lshl_add_u32 v172, s46, 8, v148
	v_mov_b32_e32 v175, 0
	v_lshl_or_b32 v178, s12, 8, v150
	v_lshlrev_b32_e32 v178, 1, v178
	v_lshl_add_u32 v178, v172, 12, v178
	v_mov_b32_e32 v179, v178
	global_load_dwordx4 v[180:183], v179, s[16:17]
	global_load_dwordx4 v[184:187], v179, s[16:17] offset:256
	v_add_u32_e32 v179, 0x10000, v178
	global_load_dwordx4 v[188:191], v179, s[16:17]
	global_load_dwordx4 v[192:195], v179, s[16:17] offset:256
	v_add_u32_e32 v179, 0x20000, v178
	global_load_dwordx4 v[196:199], v179, s[16:17]
	global_load_dwordx4 v[200:203], v179, s[16:17] offset:256
	v_add_u32_e32 v179, 0x30000, v178
	global_load_dwordx4 v[204:207], v179, s[16:17]
	global_load_dwordx4 v[208:211], v179, s[16:17] offset:256
	v_add_u32_e32 v179, 0x80000, v178
	global_load_dwordx4 v[212:215], v179, s[16:17]
	s_and_b64 vcc, exec, s[24:25]
	s_cbranch_vccz .LBB0_340
	s_barrier
.LBB0_340:
	v_lshl_add_u32 v146, s46, 8, v148
	v_lshl_or_b32 v144, s12, 8, v150
	v_ashrrev_i32_e32 v147, 31, v146
	v_ashrrev_i32_e32 v145, 31, v144
	v_lshlrev_b64 v[156:157], 11, v[146:147]
	v_lshl_add_u64 v[156:157], v[156:157], 0, v[144:145]
	v_lshlrev_b64 v[160:161], 1, v[156:157]
	v_lshl_add_u64 v[156:157], s[16:17], 0, v[160:161]
	v_lshl_add_u64 v[162:163], s[18:19], 0, v[160:161]
	v_or_b32_e32 v160, 0x100, v160
	v_lshl_add_u64 v[164:165], s[16:17], 0, v[160:161]
	v_xor_b32_e32 v155, 32, v154
	s_lshl_b32 s46, s12, 2
	s_ashr_i32 s47, s46, 31
	s_waitcnt vmcnt(8)
	v_mov_b64_e32 v[156:157], v[180:181]
	v_mov_b64_e32 v[158:159], v[182:183]
	global_load_dwordx4 v[180:183], v179, s[16:17] offset:256
	v_lshlrev_b32_e32 v166, 16, v156
	v_and_b32_e32 v167, 0xffff0000, v156
	v_lshlrev_b32_e32 v156, 16, v157
	v_and_b32_e32 v157, 0xffff0000, v157
	v_lshlrev_b32_e32 v168, 16, v158
	v_and_b32_e32 v169, 0xffff0000, v158
	v_lshlrev_b32_e32 v158, 16, v159
	v_and_b32_e32 v159, 0xffff0000, v159
	v_pk_add_f32 v[126:127], v[126:127], v[156:157]
	v_pk_add_f32 v[166:167], v[124:125], v[166:167]
	v_pk_add_f32 v[170:171], v[122:123], v[158:159]
	v_pk_add_f32 v[168:169], v[120:121], v[168:169]
	v_cvt_pk_bf16_f32 v122, v166, v167
	v_cvt_pk_bf16_f32 v123, v126, v127
	v_mul_f32_e32 v127, v127, v127
	v_cvt_pk_bf16_f32 v124, v168, v169
	v_cvt_pk_bf16_f32 v125, v170, v171
	v_mul_f32_e32 v164, v167, v167
	v_mul_f32_e32 v165, v169, v169
	v_mul_f32_e32 v167, v171, v171
	v_fmac_f32_e32 v164, v166, v166
	v_fmac_f32_e32 v127, v126, v126
	v_fmac_f32_e32 v165, v168, v168
	v_fmac_f32_e32 v167, v170, v170
	v_add_f32_e32 v126, v164, v127
	v_add_f32_e32 v127, v165, v167
	v_add_f32_e32 v166, v126, v127
	v_and_b32_e32 v121, 64, v154
	v_xor_b32_e32 v120, 16, v154
	v_add_u32_e32 v121, 64, v121
	v_cmp_lt_i32_e32 vcc, v120, v121
	global_store_dwordx4 v[162:163], v[122:125], off
	s_waitcnt vmcnt(9)
	v_mov_b64_e32 v[156:157], v[184:185]
	v_mov_b64_e32 v[158:159], v[186:187]
	v_add_u32_e32 v179, 0x90000, v178
	global_load_dwordx4 v[184:187], v179, s[16:17]
	v_lshlrev_b32_e32 v126, 16, v156
	v_and_b32_e32 v127, 0xffff0000, v156
	v_lshlrev_b32_e32 v156, 16, v157
	v_and_b32_e32 v157, 0xffff0000, v157
	v_lshlrev_b32_e32 v164, 16, v158
	v_and_b32_e32 v165, 0xffff0000, v158
	v_lshlrev_b32_e32 v158, 16, v159
	v_and_b32_e32 v159, 0xffff0000, v159
	v_pk_add_f32 v[118:119], v[118:119], v[156:157]
	v_pk_add_f32 v[116:117], v[116:117], v[126:127]
	v_pk_add_f32 v[126:127], v[114:115], v[158:159]
	v_pk_add_f32 v[156:157], v[112:113], v[164:165]
	v_mul_f32_e32 v112, v117, v117
	v_mul_f32_e32 v113, v119, v119
	v_mul_f32_e32 v114, v157, v157
	v_mul_f32_e32 v115, v127, v127
	v_fmac_f32_e32 v112, v116, v116
	v_fmac_f32_e32 v113, v118, v118
	v_fmac_f32_e32 v114, v156, v156
	v_fmac_f32_e32 v115, v126, v126
	v_add_f32_e32 v112, v112, v113
	v_add_f32_e32 v113, v114, v115
	v_cndmask_b32_e32 v120, v154, v120, vcc
	v_add_f32_e32 v112, v112, v113
	v_lshlrev_b32_e32 v120, 2, v120
	v_add_f32_e32 v112, v166, v112
	ds_bpermute_b32 v113, v120, v112
	v_cmp_lt_i32_e32 vcc, v155, v121
	v_lshl_add_u64 v[122:123], s[18:19], 0, v[160:161]
	v_cvt_pk_bf16_f32 v116, v116, v117
	v_cvt_pk_bf16_f32 v117, v118, v119
	s_waitcnt lgkmcnt(0)
	v_add_f32_e32 v112, v112, v113
	v_cndmask_b32_e32 v114, v154, v155, vcc
	v_lshlrev_b32_e32 v114, 2, v114
	ds_bpermute_b32 v113, v114, v112
	v_cvt_pk_bf16_f32 v118, v156, v157
	v_cvt_pk_bf16_f32 v119, v126, v127
	global_store_dwordx4 v[122:123], v[116:119], off
	s_and_saveexec_b64 s[48:49], s[8:9]
	s_cbranch_execz .LBB0_342
	s_waitcnt lgkmcnt(0)
	v_add_f32_e32 v115, v112, v113
	v_lshlrev_b64 v[112:113], 7, v[146:147]
	v_lshl_add_u64 v[112:113], s[20:21], 0, v[112:113]
	v_lshl_add_u64 v[112:113], s[46:47], 2, v[112:113]
	s_lshl_b32 s12, s61, 2
	v_lshl_add_u64 v[112:113], v[112:113], 0, s[12:13]
	global_store_dword v[112:113], v115, off
.LBB0_342:
	s_or_b64 exec, exec, s[48:49]
	v_or_b32_e32 v112, 16, v146
	s_waitcnt lgkmcnt(0)
	v_ashrrev_i32_e32 v113, 31, v112
	v_lshlrev_b64 v[116:117], 11, v[112:113]
	v_lshl_add_u64 v[116:117], v[116:117], 0, v[144:145]
	v_lshlrev_b64 v[122:123], 1, v[116:117]
	v_lshl_add_u64 v[116:117], s[16:17], 0, v[122:123]
	v_lshl_add_u64 v[124:125], s[18:19], 0, v[122:123]
	v_or_b32_e32 v122, 0x100, v122
	v_lshl_add_u64 v[126:127], s[16:17], 0, v[122:123]
	s_waitcnt vmcnt(10)
	v_mov_b64_e32 v[116:117], v[188:189]
	v_mov_b64_e32 v[118:119], v[190:191]
	global_load_dwordx4 v[188:191], v179, s[16:17] offset:256
	v_lshlrev_b32_e32 v156, 16, v116
	v_and_b32_e32 v157, 0xffff0000, v116
	v_lshlrev_b32_e32 v116, 16, v117
	v_and_b32_e32 v117, 0xffff0000, v117
	v_lshlrev_b32_e32 v158, 16, v118
	v_and_b32_e32 v159, 0xffff0000, v118
	v_lshlrev_b32_e32 v118, 16, v119
	v_and_b32_e32 v119, 0xffff0000, v119
	v_pk_add_f32 v[116:117], v[110:111], v[116:117]
	v_pk_add_f32 v[156:157], v[108:109], v[156:157]
	v_pk_add_f32 v[118:119], v[106:107], v[118:119]
	v_pk_add_f32 v[158:159], v[104:105], v[158:159]
	v_cvt_pk_bf16_f32 v104, v156, v157
	v_cvt_pk_bf16_f32 v105, v116, v117
	v_mul_f32_e32 v115, v157, v157
	v_cvt_pk_bf16_f32 v106, v158, v159
	v_cvt_pk_bf16_f32 v107, v118, v119
	v_mul_f32_e32 v117, v117, v117
	v_mul_f32_e32 v121, v159, v159
	v_mul_f32_e32 v119, v119, v119
	v_fmac_f32_e32 v115, v156, v156
	v_fmac_f32_e32 v117, v116, v116
	v_fmac_f32_e32 v121, v158, v158
	v_fmac_f32_e32 v119, v118, v118
	v_add_f32_e32 v115, v115, v117
	v_add_f32_e32 v116, v121, v119
	v_add_f32_e32 v115, v115, v116
	global_store_dwordx4 v[124:125], v[104:107], off
	s_waitcnt vmcnt(11)
	v_mov_b64_e32 v[108:109], v[192:193]
	v_mov_b64_e32 v[110:111], v[194:195]
	v_add_u32_e32 v179, 0xa0000, v178
	global_load_dwordx4 v[192:195], v179, s[16:17]
	v_lshlrev_b32_e32 v116, 16, v108
	v_and_b32_e32 v117, 0xffff0000, v108
	v_lshlrev_b32_e32 v108, 16, v109
	v_and_b32_e32 v109, 0xffff0000, v109
	v_lshlrev_b32_e32 v118, 16, v110
	v_and_b32_e32 v119, 0xffff0000, v110
	v_lshlrev_b32_e32 v110, 16, v111
	v_and_b32_e32 v111, 0xffff0000, v111
	v_pk_add_f32 v[102:103], v[102:103], v[108:109]
	v_pk_add_f32 v[100:101], v[100:101], v[116:117]
	v_pk_add_f32 v[108:109], v[98:99], v[110:111]
	v_pk_add_f32 v[110:111], v[96:97], v[118:119]
	v_mul_f32_e32 v96, v101, v101
	v_mul_f32_e32 v97, v103, v103
	v_mul_f32_e32 v98, v111, v111
	v_mul_f32_e32 v99, v109, v109
	v_fmac_f32_e32 v96, v100, v100
	v_fmac_f32_e32 v97, v102, v102
	v_fmac_f32_e32 v98, v110, v110
	v_fmac_f32_e32 v99, v108, v108
	v_add_f32_e32 v96, v96, v97
	v_add_f32_e32 v97, v98, v99
	v_add_f32_e32 v96, v96, v97
	v_add_f32_e32 v96, v115, v96
	ds_bpermute_b32 v97, v120, v96
	v_cvt_pk_bf16_f32 v98, v100, v101
	v_cvt_pk_bf16_f32 v99, v102, v103
	v_lshl_add_u64 v[102:103], s[18:19], 0, v[122:123]
	v_cvt_pk_bf16_f32 v100, v110, v111
	s_waitcnt lgkmcnt(0)
	v_add_f32_e32 v96, v96, v97
	ds_bpermute_b32 v97, v114, v96
	v_cvt_pk_bf16_f32 v101, v108, v109
	global_store_dwordx4 v[102:103], v[98:101], off
	s_and_saveexec_b64 s[48:49], s[8:9]
	s_cbranch_execz .LBB0_344
	s_waitcnt lgkmcnt(0)
	v_add_f32_e32 v98, v96, v97
	v_lshlrev_b64 v[96:97], 7, v[112:113]
	v_lshl_add_u64 v[96:97], s[20:21], 0, v[96:97]
	v_lshl_add_u64 v[96:97], s[46:47], 2, v[96:97]
	s_lshl_b32 s12, s61, 2
	v_lshl_add_u64 v[96:97], v[96:97], 0, s[12:13]
	global_store_dword v[96:97], v98, off
.LBB0_344:
	s_or_b64 exec, exec, s[48:49]
	v_or_b32_e32 v96, 32, v146
	s_waitcnt lgkmcnt(0)
	v_ashrrev_i32_e32 v97, 31, v96
	v_lshlrev_b64 v[98:99], 11, v[96:97]
	v_lshl_add_u64 v[98:99], v[98:99], 0, v[144:145]
	v_lshlrev_b64 v[102:103], 1, v[98:99]
	v_lshl_add_u64 v[98:99], s[16:17], 0, v[102:103]
	v_lshl_add_u64 v[104:105], s[18:19], 0, v[102:103]
	v_or_b32_e32 v102, 0x100, v102
	v_lshl_add_u64 v[106:107], s[16:17], 0, v[102:103]
	s_waitcnt vmcnt(12)
	v_mov_b64_e32 v[98:99], v[196:197]
	v_mov_b64_e32 v[100:101], v[198:199]
	global_load_dwordx4 v[196:199], v179, s[16:17] offset:256
	v_lshlrev_b32_e32 v108, 16, v98
	v_and_b32_e32 v109, 0xffff0000, v98
	v_lshlrev_b32_e32 v98, 16, v99
	v_and_b32_e32 v99, 0xffff0000, v99
	v_lshlrev_b32_e32 v110, 16, v100
	v_and_b32_e32 v111, 0xffff0000, v100
	v_lshlrev_b32_e32 v100, 16, v101
	v_and_b32_e32 v101, 0xffff0000, v101
	v_pk_add_f32 v[98:99], v[94:95], v[98:99]
	v_pk_add_f32 v[108:109], v[92:93], v[108:109]
	v_pk_add_f32 v[100:101], v[90:91], v[100:101]
	v_pk_add_f32 v[110:111], v[88:89], v[110:111]
	v_cvt_pk_bf16_f32 v88, v108, v109
	v_cvt_pk_bf16_f32 v89, v98, v99
	v_mul_f32_e32 v99, v99, v99
	v_cvt_pk_bf16_f32 v90, v110, v111
	v_cvt_pk_bf16_f32 v91, v100, v101
	v_mul_f32_e32 v106, v109, v109
	v_mul_f32_e32 v107, v111, v111
	v_mul_f32_e32 v101, v101, v101
	v_fmac_f32_e32 v106, v108, v108
	v_fmac_f32_e32 v99, v98, v98
	v_fmac_f32_e32 v107, v110, v110
	v_fmac_f32_e32 v101, v100, v100
	v_add_f32_e32 v98, v106, v99
	v_add_f32_e32 v99, v107, v101
	v_add_f32_e32 v106, v98, v99
	global_store_dwordx4 v[104:105], v[88:91], off
	s_waitcnt vmcnt(13)
	v_mov_b64_e32 v[92:93], v[200:201]
	v_mov_b64_e32 v[94:95], v[202:203]
	v_add_u32_e32 v179, 0xb0000, v178
	global_load_dwordx4 v[200:203], v179, s[16:17]
	v_lshlrev_b32_e32 v98, 16, v92
	v_and_b32_e32 v99, 0xffff0000, v92
	v_lshlrev_b32_e32 v92, 16, v93
	v_and_b32_e32 v93, 0xffff0000, v93
	v_lshlrev_b32_e32 v100, 16, v94
	v_and_b32_e32 v101, 0xffff0000, v94
	v_lshlrev_b32_e32 v94, 16, v95
	v_and_b32_e32 v95, 0xffff0000, v95
	v_pk_add_f32 v[86:87], v[86:87], v[92:93]
	v_pk_add_f32 v[84:85], v[84:85], v[98:99]
	v_pk_add_f32 v[92:93], v[82:83], v[94:95]
	v_pk_add_f32 v[94:95], v[80:81], v[100:101]
	v_mul_f32_e32 v80, v85, v85
	v_mul_f32_e32 v81, v87, v87
	v_mul_f32_e32 v82, v95, v95
	v_mul_f32_e32 v83, v93, v93
	v_fmac_f32_e32 v80, v84, v84
	v_fmac_f32_e32 v81, v86, v86
	v_fmac_f32_e32 v82, v94, v94
	v_fmac_f32_e32 v83, v92, v92
	v_add_f32_e32 v80, v80, v81
	v_add_f32_e32 v81, v82, v83
	v_add_f32_e32 v80, v80, v81
	v_add_f32_e32 v80, v106, v80
	ds_bpermute_b32 v81, v120, v80
	v_cvt_pk_bf16_f32 v82, v84, v85
	v_cvt_pk_bf16_f32 v83, v86, v87
	v_lshl_add_u64 v[86:87], s[18:19], 0, v[102:103]
	v_cvt_pk_bf16_f32 v84, v94, v95
	s_waitcnt lgkmcnt(0)
	v_add_f32_e32 v80, v80, v81
	ds_bpermute_b32 v81, v114, v80
	v_cvt_pk_bf16_f32 v85, v92, v93
	global_store_dwordx4 v[86:87], v[82:85], off
	s_and_saveexec_b64 s[48:49], s[8:9]
	s_cbranch_execz .LBB0_346
	s_waitcnt lgkmcnt(0)
	v_add_f32_e32 v82, v80, v81
	v_lshlrev_b64 v[80:81], 7, v[96:97]
	v_lshl_add_u64 v[80:81], s[20:21], 0, v[80:81]
	v_lshl_add_u64 v[80:81], s[46:47], 2, v[80:81]
	s_lshl_b32 s12, s61, 2
	v_lshl_add_u64 v[80:81], v[80:81], 0, s[12:13]
	global_store_dword v[80:81], v82, off
.LBB0_346:
	s_or_b64 exec, exec, s[48:49]
	v_or_b32_e32 v80, 48, v146
	s_waitcnt lgkmcnt(0)
	v_ashrrev_i32_e32 v81, 31, v80
	v_lshlrev_b64 v[82:83], 11, v[80:81]
	v_lshl_add_u64 v[82:83], v[82:83], 0, v[144:145]
	v_lshlrev_b64 v[86:87], 1, v[82:83]
	v_lshl_add_u64 v[82:83], s[16:17], 0, v[86:87]
	v_lshl_add_u64 v[88:89], s[18:19], 0, v[86:87]
	v_or_b32_e32 v86, 0x100, v86
	v_lshl_add_u64 v[90:91], s[16:17], 0, v[86:87]
	s_waitcnt vmcnt(14)
	v_mov_b64_e32 v[82:83], v[204:205]
	v_mov_b64_e32 v[84:85], v[206:207]
	global_load_dwordx4 v[204:207], v179, s[16:17] offset:256
	v_lshlrev_b32_e32 v92, 16, v82
	v_and_b32_e32 v93, 0xffff0000, v82
	v_lshlrev_b32_e32 v82, 16, v83
	v_and_b32_e32 v83, 0xffff0000, v83
	v_lshlrev_b32_e32 v94, 16, v84
	v_and_b32_e32 v95, 0xffff0000, v84
	v_lshlrev_b32_e32 v84, 16, v85
	v_and_b32_e32 v85, 0xffff0000, v85
	v_pk_add_f32 v[82:83], v[78:79], v[82:83]
	v_pk_add_f32 v[92:93], v[76:77], v[92:93]
	v_pk_add_f32 v[84:85], v[74:75], v[84:85]
	v_pk_add_f32 v[94:95], v[72:73], v[94:95]
	v_cvt_pk_bf16_f32 v72, v92, v93
	v_cvt_pk_bf16_f32 v73, v82, v83
	v_mul_f32_e32 v83, v83, v83
	v_cvt_pk_bf16_f32 v74, v94, v95
	v_cvt_pk_bf16_f32 v75, v84, v85
	v_mul_f32_e32 v90, v93, v93
	v_mul_f32_e32 v91, v95, v95
	v_mul_f32_e32 v85, v85, v85
	v_fmac_f32_e32 v90, v92, v92
	v_fmac_f32_e32 v83, v82, v82
	v_fmac_f32_e32 v91, v94, v94
	v_fmac_f32_e32 v85, v84, v84
	v_add_f32_e32 v82, v90, v83
	v_add_f32_e32 v83, v91, v85
	v_add_f32_e32 v90, v82, v83
	global_store_dwordx4 v[88:89], v[72:75], off
	s_waitcnt vmcnt(15)
	v_mov_b64_e32 v[76:77], v[208:209]
	v_mov_b64_e32 v[78:79], v[210:211]
	v_lshlrev_b32_e32 v82, 16, v76
	v_and_b32_e32 v83, 0xffff0000, v76
	v_lshlrev_b32_e32 v76, 16, v77
	v_and_b32_e32 v77, 0xffff0000, v77
	v_lshlrev_b32_e32 v84, 16, v78
	v_and_b32_e32 v85, 0xffff0000, v78
	v_lshlrev_b32_e32 v78, 16, v79
	v_and_b32_e32 v79, 0xffff0000, v79
	v_pk_add_f32 v[70:71], v[70:71], v[76:77]
	v_pk_add_f32 v[68:69], v[68:69], v[82:83]
	v_pk_add_f32 v[76:77], v[66:67], v[78:79]
	v_pk_add_f32 v[78:79], v[64:65], v[84:85]
	v_mul_f32_e32 v64, v69, v69
	v_mul_f32_e32 v65, v71, v71
	v_mul_f32_e32 v66, v79, v79
	v_mul_f32_e32 v67, v77, v77
	v_fmac_f32_e32 v64, v68, v68
	v_fmac_f32_e32 v65, v70, v70
	v_fmac_f32_e32 v66, v78, v78
	v_fmac_f32_e32 v67, v76, v76
	v_add_f32_e32 v64, v64, v65
	v_add_f32_e32 v65, v66, v67
	v_add_f32_e32 v64, v64, v65
	v_add_f32_e32 v64, v90, v64
	ds_bpermute_b32 v65, v120, v64
	v_cvt_pk_bf16_f32 v66, v68, v69
	v_cvt_pk_bf16_f32 v67, v70, v71
	v_lshl_add_u64 v[70:71], s[18:19], 0, v[86:87]
	v_cvt_pk_bf16_f32 v68, v78, v79
	s_waitcnt lgkmcnt(0)
	v_add_f32_e32 v64, v64, v65
	ds_bpermute_b32 v65, v114, v64
	v_cvt_pk_bf16_f32 v69, v76, v77
	global_store_dwordx4 v[70:71], v[66:69], off
	s_and_saveexec_b64 s[48:49], s[8:9]
	s_cbranch_execz .LBB0_348
	s_waitcnt lgkmcnt(0)
	v_add_f32_e32 v66, v64, v65
	v_lshlrev_b64 v[64:65], 7, v[80:81]
	v_lshl_add_u64 v[64:65], s[20:21], 0, v[64:65]
	v_lshl_add_u64 v[64:65], s[46:47], 2, v[64:65]
	s_lshl_b32 s12, s61, 2
	v_lshl_add_u64 v[64:65], v[64:65], 0, s[12:13]
	global_store_dword v[64:65], v66, off
.LBB0_348:
	s_or_b64 exec, exec, s[48:49]
	v_add_u32_e32 v64, 0x80, v146
	s_waitcnt lgkmcnt(0)
	v_ashrrev_i32_e32 v65, 31, v64
	v_lshlrev_b64 v[66:67], 11, v[64:65]
	v_lshl_add_u64 v[66:67], v[66:67], 0, v[144:145]
	v_lshlrev_b64 v[70:71], 1, v[66:67]
	v_lshl_add_u64 v[66:67], s[16:17], 0, v[70:71]
	v_lshl_add_u64 v[72:73], s[18:19], 0, v[70:71]
	v_or_b32_e32 v70, 0x100, v70
	v_lshl_add_u64 v[74:75], s[16:17], 0, v[70:71]
	s_waitcnt vmcnt(15)
	v_mov_b64_e32 v[66:67], v[212:213]
	v_mov_b64_e32 v[68:69], v[214:215]
	v_lshlrev_b32_e32 v76, 16, v66
	v_and_b32_e32 v77, 0xffff0000, v66
	v_lshlrev_b32_e32 v66, 16, v67
	v_and_b32_e32 v67, 0xffff0000, v67
	v_lshlrev_b32_e32 v78, 16, v68
	v_and_b32_e32 v79, 0xffff0000, v68
	v_lshlrev_b32_e32 v68, 16, v69
	v_and_b32_e32 v69, 0xffff0000, v69
	v_pk_add_f32 v[66:67], v[62:63], v[66:67]
	v_pk_add_f32 v[76:77], v[60:61], v[76:77]
	v_pk_add_f32 v[68:69], v[58:59], v[68:69]
	v_pk_add_f32 v[78:79], v[56:57], v[78:79]
	v_cvt_pk_bf16_f32 v56, v76, v77
	v_cvt_pk_bf16_f32 v57, v66, v67
	v_mul_f32_e32 v67, v67, v67
	v_cvt_pk_bf16_f32 v58, v78, v79
	v_cvt_pk_bf16_f32 v59, v68, v69
	v_mul_f32_e32 v74, v77, v77
	v_mul_f32_e32 v75, v79, v79
	v_mul_f32_e32 v69, v69, v69
	v_fmac_f32_e32 v74, v76, v76
	v_fmac_f32_e32 v67, v66, v66
	v_fmac_f32_e32 v75, v78, v78
	v_fmac_f32_e32 v69, v68, v68
	v_add_f32_e32 v66, v74, v67
	v_add_f32_e32 v67, v75, v69
	v_add_f32_e32 v74, v66, v67
	global_store_dwordx4 v[72:73], v[56:59], off
	s_waitcnt vmcnt(15)
	v_mov_b64_e32 v[60:61], v[180:181]
	v_mov_b64_e32 v[62:63], v[182:183]
	v_lshlrev_b32_e32 v66, 16, v60
	v_and_b32_e32 v67, 0xffff0000, v60
	v_lshlrev_b32_e32 v60, 16, v61
	v_and_b32_e32 v61, 0xffff0000, v61
	v_lshlrev_b32_e32 v68, 16, v62
	v_and_b32_e32 v69, 0xffff0000, v62
	v_lshlrev_b32_e32 v62, 16, v63
	v_and_b32_e32 v63, 0xffff0000, v63
	v_pk_add_f32 v[54:55], v[54:55], v[60:61]
	v_pk_add_f32 v[52:53], v[52:53], v[66:67]
	v_pk_add_f32 v[60:61], v[50:51], v[62:63]
	v_pk_add_f32 v[62:63], v[48:49], v[68:69]
	v_mul_f32_e32 v48, v53, v53
	v_mul_f32_e32 v49, v55, v55
	v_mul_f32_e32 v50, v63, v63
	v_mul_f32_e32 v51, v61, v61
	v_fmac_f32_e32 v48, v52, v52
	v_fmac_f32_e32 v49, v54, v54
	v_fmac_f32_e32 v50, v62, v62
	v_fmac_f32_e32 v51, v60, v60
	v_add_f32_e32 v48, v48, v49
	v_add_f32_e32 v49, v50, v51
	v_add_f32_e32 v48, v48, v49
	v_add_f32_e32 v48, v74, v48
	ds_bpermute_b32 v49, v120, v48
	v_cvt_pk_bf16_f32 v50, v52, v53
	v_cvt_pk_bf16_f32 v51, v54, v55
	v_lshl_add_u64 v[54:55], s[18:19], 0, v[70:71]
	v_cvt_pk_bf16_f32 v52, v62, v63
	s_waitcnt lgkmcnt(0)
	v_add_f32_e32 v48, v48, v49
	ds_bpermute_b32 v49, v114, v48
	v_cvt_pk_bf16_f32 v53, v60, v61
	global_store_dwordx4 v[54:55], v[50:53], off
	s_and_saveexec_b64 s[48:49], s[8:9]
	s_cbranch_execz .LBB0_350
	s_waitcnt lgkmcnt(0)
	v_add_f32_e32 v50, v48, v49
	v_lshlrev_b64 v[48:49], 7, v[64:65]
	v_lshl_add_u64 v[48:49], s[20:21], 0, v[48:49]
	v_lshl_add_u64 v[48:49], s[46:47], 2, v[48:49]
	s_lshl_b32 s12, s61, 2
	v_lshl_add_u64 v[48:49], v[48:49], 0, s[12:13]
	global_store_dword v[48:49], v50, off
.LBB0_350:
	s_or_b64 exec, exec, s[48:49]
	v_add_u32_e32 v48, 0x90, v146
	s_waitcnt lgkmcnt(0)
	v_ashrrev_i32_e32 v49, 31, v48
	v_lshlrev_b64 v[50:51], 11, v[48:49]
	v_lshl_add_u64 v[50:51], v[50:51], 0, v[144:145]
	v_lshlrev_b64 v[54:55], 1, v[50:51]
	v_lshl_add_u64 v[50:51], s[16:17], 0, v[54:55]
	v_lshl_add_u64 v[56:57], s[18:19], 0, v[54:55]
	v_or_b32_e32 v54, 0x100, v54
	v_lshl_add_u64 v[58:59], s[16:17], 0, v[54:55]
	s_waitcnt vmcnt(14)
	v_mov_b64_e32 v[50:51], v[184:185]
	v_mov_b64_e32 v[52:53], v[186:187]
	v_lshlrev_b32_e32 v60, 16, v50
	v_and_b32_e32 v61, 0xffff0000, v50
	v_lshlrev_b32_e32 v50, 16, v51
	v_and_b32_e32 v51, 0xffff0000, v51
	v_lshlrev_b32_e32 v62, 16, v52
	v_and_b32_e32 v63, 0xffff0000, v52
	v_lshlrev_b32_e32 v52, 16, v53
	v_and_b32_e32 v53, 0xffff0000, v53
	v_pk_add_f32 v[50:51], v[46:47], v[50:51]
	v_pk_add_f32 v[60:61], v[44:45], v[60:61]
	v_pk_add_f32 v[52:53], v[42:43], v[52:53]
	v_pk_add_f32 v[62:63], v[40:41], v[62:63]
	v_cvt_pk_bf16_f32 v40, v60, v61
	v_cvt_pk_bf16_f32 v41, v50, v51
	v_mul_f32_e32 v51, v51, v51
	v_cvt_pk_bf16_f32 v42, v62, v63
	v_cvt_pk_bf16_f32 v43, v52, v53
	v_mul_f32_e32 v58, v61, v61
	v_mul_f32_e32 v59, v63, v63
	v_mul_f32_e32 v53, v53, v53
	v_fmac_f32_e32 v58, v60, v60
	v_fmac_f32_e32 v51, v50, v50
	v_fmac_f32_e32 v59, v62, v62
	v_fmac_f32_e32 v53, v52, v52
	v_add_f32_e32 v50, v58, v51
	v_add_f32_e32 v51, v59, v53
	v_add_f32_e32 v58, v50, v51
	global_store_dwordx4 v[56:57], v[40:43], off
	s_waitcnt vmcnt(13)
	v_mov_b64_e32 v[44:45], v[188:189]
	v_mov_b64_e32 v[46:47], v[190:191]
	v_lshlrev_b32_e32 v50, 16, v44
	v_and_b32_e32 v51, 0xffff0000, v44
	v_lshlrev_b32_e32 v44, 16, v45
	v_and_b32_e32 v45, 0xffff0000, v45
	v_lshlrev_b32_e32 v52, 16, v46
	v_and_b32_e32 v53, 0xffff0000, v46
	v_lshlrev_b32_e32 v46, 16, v47
	v_and_b32_e32 v47, 0xffff0000, v47
	v_pk_add_f32 v[38:39], v[38:39], v[44:45]
	v_pk_add_f32 v[36:37], v[36:37], v[50:51]
	v_pk_add_f32 v[44:45], v[34:35], v[46:47]
	v_pk_add_f32 v[46:47], v[32:33], v[52:53]
	v_mul_f32_e32 v32, v37, v37
	v_mul_f32_e32 v33, v39, v39
	v_mul_f32_e32 v34, v47, v47
	v_mul_f32_e32 v35, v45, v45
	v_fmac_f32_e32 v32, v36, v36
	v_fmac_f32_e32 v33, v38, v38
	v_fmac_f32_e32 v34, v46, v46
	v_fmac_f32_e32 v35, v44, v44
	v_add_f32_e32 v32, v32, v33
	v_add_f32_e32 v33, v34, v35
	v_add_f32_e32 v32, v32, v33
	v_add_f32_e32 v32, v58, v32
	ds_bpermute_b32 v33, v120, v32
	v_cvt_pk_bf16_f32 v34, v36, v37
	v_cvt_pk_bf16_f32 v35, v38, v39
	v_lshl_add_u64 v[38:39], s[18:19], 0, v[54:55]
	v_cvt_pk_bf16_f32 v36, v46, v47
	s_waitcnt lgkmcnt(0)
	v_add_f32_e32 v32, v32, v33
	ds_bpermute_b32 v33, v114, v32
	v_cvt_pk_bf16_f32 v37, v44, v45
	global_store_dwordx4 v[38:39], v[34:37], off
	s_and_saveexec_b64 s[48:49], s[8:9]
	s_cbranch_execz .LBB0_352
	s_waitcnt lgkmcnt(0)
	v_add_f32_e32 v34, v32, v33
	v_lshlrev_b64 v[32:33], 7, v[48:49]
	v_lshl_add_u64 v[32:33], s[20:21], 0, v[32:33]
	v_lshl_add_u64 v[32:33], s[46:47], 2, v[32:33]
	s_lshl_b32 s12, s61, 2
	v_lshl_add_u64 v[32:33], v[32:33], 0, s[12:13]
	global_store_dword v[32:33], v34, off
.LBB0_352:
	s_or_b64 exec, exec, s[48:49]
	v_add_u32_e32 v32, 0xa0, v146
	s_waitcnt lgkmcnt(0)
	v_ashrrev_i32_e32 v33, 31, v32
	v_lshlrev_b64 v[34:35], 11, v[32:33]
	v_lshl_add_u64 v[34:35], v[34:35], 0, v[144:145]
	v_lshlrev_b64 v[38:39], 1, v[34:35]
	v_lshl_add_u64 v[34:35], s[16:17], 0, v[38:39]
	v_lshl_add_u64 v[40:41], s[18:19], 0, v[38:39]
	v_or_b32_e32 v38, 0x100, v38
	v_lshl_add_u64 v[42:43], s[16:17], 0, v[38:39]
	s_waitcnt vmcnt(12)
	v_mov_b64_e32 v[34:35], v[192:193]
	v_mov_b64_e32 v[36:37], v[194:195]
	v_lshlrev_b32_e32 v44, 16, v34
	v_and_b32_e32 v45, 0xffff0000, v34
	v_lshlrev_b32_e32 v34, 16, v35
	v_and_b32_e32 v35, 0xffff0000, v35
	v_lshlrev_b32_e32 v46, 16, v36
	v_and_b32_e32 v47, 0xffff0000, v36
	v_lshlrev_b32_e32 v36, 16, v37
	v_and_b32_e32 v37, 0xffff0000, v37
	v_pk_add_f32 v[34:35], v[30:31], v[34:35]
	v_pk_add_f32 v[44:45], v[28:29], v[44:45]
	v_pk_add_f32 v[36:37], v[26:27], v[36:37]
	v_pk_add_f32 v[46:47], v[24:25], v[46:47]
	v_cvt_pk_bf16_f32 v24, v44, v45
	v_cvt_pk_bf16_f32 v25, v34, v35
	v_mul_f32_e32 v35, v35, v35
	v_cvt_pk_bf16_f32 v26, v46, v47
	v_cvt_pk_bf16_f32 v27, v36, v37
	v_mul_f32_e32 v42, v45, v45
	v_mul_f32_e32 v43, v47, v47
	v_mul_f32_e32 v37, v37, v37
	v_fmac_f32_e32 v42, v44, v44
	v_fmac_f32_e32 v35, v34, v34
	v_fmac_f32_e32 v43, v46, v46
	v_fmac_f32_e32 v37, v36, v36
	v_add_f32_e32 v34, v42, v35
	v_add_f32_e32 v35, v43, v37
	v_add_f32_e32 v42, v34, v35
	global_store_dwordx4 v[40:41], v[24:27], off
	s_waitcnt vmcnt(11)
	v_mov_b64_e32 v[28:29], v[196:197]
	v_mov_b64_e32 v[30:31], v[198:199]
	v_lshlrev_b32_e32 v34, 16, v28
	v_and_b32_e32 v35, 0xffff0000, v28
	v_lshlrev_b32_e32 v28, 16, v29
	v_and_b32_e32 v29, 0xffff0000, v29
	v_lshlrev_b32_e32 v36, 16, v30
	v_and_b32_e32 v37, 0xffff0000, v30
	v_lshlrev_b32_e32 v30, 16, v31
	v_and_b32_e32 v31, 0xffff0000, v31
	v_pk_add_f32 v[22:23], v[22:23], v[28:29]
	v_pk_add_f32 v[20:21], v[20:21], v[34:35]
	v_pk_add_f32 v[28:29], v[18:19], v[30:31]
	v_pk_add_f32 v[30:31], v[16:17], v[36:37]
	v_mul_f32_e32 v16, v21, v21
	v_mul_f32_e32 v17, v23, v23
	v_mul_f32_e32 v18, v31, v31
	v_mul_f32_e32 v19, v29, v29
	v_fmac_f32_e32 v16, v20, v20
	v_fmac_f32_e32 v17, v22, v22
	v_fmac_f32_e32 v18, v30, v30
	v_fmac_f32_e32 v19, v28, v28
	v_add_f32_e32 v16, v16, v17
	v_add_f32_e32 v17, v18, v19
	v_add_f32_e32 v16, v16, v17
	v_add_f32_e32 v16, v42, v16
	ds_bpermute_b32 v17, v120, v16
	v_cvt_pk_bf16_f32 v18, v20, v21
	v_cvt_pk_bf16_f32 v19, v22, v23
	v_lshl_add_u64 v[22:23], s[18:19], 0, v[38:39]
	v_cvt_pk_bf16_f32 v20, v30, v31
	s_waitcnt lgkmcnt(0)
	v_add_f32_e32 v16, v16, v17
	ds_bpermute_b32 v17, v114, v16
	v_cvt_pk_bf16_f32 v21, v28, v29
	global_store_dwordx4 v[22:23], v[18:21], off
	s_and_saveexec_b64 s[48:49], s[8:9]
	s_cbranch_execz .LBB0_354
	s_waitcnt lgkmcnt(0)
	v_add_f32_e32 v18, v16, v17
	v_lshlrev_b64 v[16:17], 7, v[32:33]
	v_lshl_add_u64 v[16:17], s[20:21], 0, v[16:17]
	v_lshl_add_u64 v[16:17], s[46:47], 2, v[16:17]
	s_lshl_b32 s12, s61, 2
	v_lshl_add_u64 v[16:17], v[16:17], 0, s[12:13]
	global_store_dword v[16:17], v18, off
.LBB0_354:
	s_or_b64 exec, exec, s[48:49]
	v_add_u32_e32 v16, 0xb0, v146
	s_waitcnt lgkmcnt(0)
	v_ashrrev_i32_e32 v17, 31, v16
	v_lshlrev_b64 v[18:19], 11, v[16:17]
	v_lshl_add_u64 v[18:19], v[18:19], 0, v[144:145]
	v_lshlrev_b64 v[22:23], 1, v[18:19]
	v_lshl_add_u64 v[18:19], s[16:17], 0, v[22:23]
	v_lshl_add_u64 v[24:25], s[18:19], 0, v[22:23]
	v_or_b32_e32 v22, 0x100, v22
	v_lshl_add_u64 v[26:27], s[16:17], 0, v[22:23]
	s_waitcnt vmcnt(10)
	v_mov_b64_e32 v[18:19], v[200:201]
	v_mov_b64_e32 v[20:21], v[202:203]
	v_lshlrev_b32_e32 v28, 16, v18
	v_and_b32_e32 v29, 0xffff0000, v18
	v_lshlrev_b32_e32 v18, 16, v19
	v_and_b32_e32 v19, 0xffff0000, v19
	v_lshlrev_b32_e32 v30, 16, v20
	v_and_b32_e32 v31, 0xffff0000, v20
	v_lshlrev_b32_e32 v20, 16, v21
	v_and_b32_e32 v21, 0xffff0000, v21
	v_pk_add_f32 v[18:19], v[14:15], v[18:19]
	v_pk_add_f32 v[28:29], v[12:13], v[28:29]
	v_pk_add_f32 v[20:21], v[10:11], v[20:21]
	v_pk_add_f32 v[30:31], v[8:9], v[30:31]
	v_cvt_pk_bf16_f32 v8, v28, v29
	v_cvt_pk_bf16_f32 v9, v18, v19
	v_mul_f32_e32 v19, v19, v19
	v_cvt_pk_bf16_f32 v10, v30, v31
	v_cvt_pk_bf16_f32 v11, v20, v21
	v_mul_f32_e32 v26, v29, v29
	v_mul_f32_e32 v27, v31, v31
	v_mul_f32_e32 v21, v21, v21
	v_fmac_f32_e32 v26, v28, v28
	v_fmac_f32_e32 v19, v18, v18
	v_fmac_f32_e32 v27, v30, v30
	v_fmac_f32_e32 v21, v20, v20
	v_add_f32_e32 v18, v26, v19
	v_add_f32_e32 v19, v27, v21
	v_add_f32_e32 v26, v18, v19
	global_store_dwordx4 v[24:25], v[8:11], off
	s_waitcnt vmcnt(9)
	v_mov_b64_e32 v[12:13], v[204:205]
	v_mov_b64_e32 v[14:15], v[206:207]
	v_lshlrev_b32_e32 v18, 16, v12
	v_and_b32_e32 v19, 0xffff0000, v12
	v_lshlrev_b32_e32 v12, 16, v13
	v_and_b32_e32 v13, 0xffff0000, v13
	v_lshlrev_b32_e32 v20, 16, v14
	v_and_b32_e32 v21, 0xffff0000, v14
	v_lshlrev_b32_e32 v14, 16, v15
	v_and_b32_e32 v15, 0xffff0000, v15
	v_pk_add_f32 v[6:7], v[6:7], v[12:13]
	v_pk_add_f32 v[4:5], v[4:5], v[18:19]
	v_pk_add_f32 v[12:13], v[2:3], v[14:15]
	v_pk_add_f32 v[14:15], v[0:1], v[20:21]
	v_mul_f32_e32 v0, v5, v5
	v_mul_f32_e32 v1, v7, v7
	v_mul_f32_e32 v2, v15, v15
	v_mul_f32_e32 v3, v13, v13
	v_fmac_f32_e32 v0, v4, v4
	v_fmac_f32_e32 v1, v6, v6
	v_fmac_f32_e32 v2, v14, v14
	v_fmac_f32_e32 v3, v12, v12
	v_add_f32_e32 v0, v0, v1
	v_add_f32_e32 v1, v2, v3
	v_add_f32_e32 v0, v0, v1
	v_add_f32_e32 v0, v26, v0
	ds_bpermute_b32 v1, v120, v0
	v_cvt_pk_bf16_f32 v2, v4, v5
	v_cvt_pk_bf16_f32 v3, v6, v7
	v_lshl_add_u64 v[6:7], s[18:19], 0, v[22:23]
	v_cvt_pk_bf16_f32 v4, v14, v15
	s_waitcnt lgkmcnt(0)
	v_add_f32_e32 v0, v0, v1
	ds_bpermute_b32 v1, v114, v0
	v_cvt_pk_bf16_f32 v5, v12, v13
	global_store_dwordx4 v[6:7], v[2:5], off
	s_and_saveexec_b64 s[48:49], s[8:9]
	s_cbranch_execz .LBB0_356
	s_waitcnt lgkmcnt(0)
	v_add_f32_e32 v2, v0, v1
	v_lshlrev_b64 v[0:1], 7, v[16:17]
	v_lshl_add_u64 v[0:1], s[20:21], 0, v[0:1]
	v_lshl_add_u64 v[0:1], s[46:47], 2, v[0:1]
	s_lshl_b32 s12, s61, 2
	v_lshl_add_u64 v[0:1], v[0:1], 0, s[12:13]
	global_store_dword v[0:1], v2, off

.LBB0_523:
	ds_read_b128 v[144:147], v151
	ds_read_b128 v[156:159], v151 offset:1024
	ds_read_b128 v[160:163], v151 offset:2048
	ds_read_b128 v[164:167], v151 offset:3072
	ds_read_b128 v[168:171], v152
	ds_read_b128 v[172:175], v152 offset:1024
	ds_read_b128 v[176:179], v152 offset:2048
	ds_read_b128 v[180:183], v152 offset:3072
	s_add_u32 s36, s34, 0x100
	s_addc_u32 s37, s35, 0
	s_cmpk_eq_i32 s66, 0x54
	s_cselect_b32 s55, s13, s37
	s_cselect_b32 s54, s12, s36
	s_cselect_b32 s53, s31, s47
	s_cselect_b32 s52, s30, s46
	v_lshl_add_u64 v[216:217], s[34:35], 0, v[138:139]
	s_add_i32 m0, s49, 0xc000
	ds_read_b128 v[184:187], v153
	ds_read_b128 v[188:191], v153 offset:1024
	ds_read_b128 v[192:195], v153 offset:2048
	ds_read_b128 v[196:199], v153 offset:3072
	ds_read_b128 v[200:203], v153 offset:4096
	ds_read_b128 v[204:207], v153 offset:5120
	ds_read_b128 v[208:211], v153 offset:6144
	ds_read_b128 v[212:215], v153 offset:7168
	global_load_lds_dwordx4 v[216:217], off
	v_lshl_add_u64 v[216:217], s[34:35], 0, v[136:137]
	s_add_i32 m0, s49, 0xe000
	s_nop 0
	global_load_lds_dwordx4 v[216:217], off
	s_waitcnt vmcnt(8)
	s_waitcnt lgkmcnt(0)
	s_barrier
	s_setprio 1
	s_waitcnt lgkmcnt(0)
	v_mfma_f32_16x16x32_bf16 v[124:127], v[144:147], v[184:187], v[124:127]
	v_mfma_f32_16x16x32_bf16 v[120:123], v[160:163], v[184:187], v[120:123]
	v_mfma_f32_16x16x32_bf16 v[108:111], v[144:147], v[192:195], v[108:111]
	v_mfma_f32_16x16x32_bf16 v[104:107], v[160:163], v[192:195], v[104:107]
	v_mfma_f32_16x16x32_bf16 v[92:95], v[144:147], v[200:203], v[92:95]
	v_mfma_f32_16x16x32_bf16 v[88:91], v[160:163], v[200:203], v[88:91]
	v_mfma_f32_16x16x32_bf16 v[76:79], v[144:147], v[208:211], v[76:79]
	v_mfma_f32_16x16x32_bf16 v[72:75], v[160:163], v[208:211], v[72:75]
	v_mfma_f32_16x16x32_bf16 v[124:127], v[156:159], v[188:191], v[124:127]
	v_mfma_f32_16x16x32_bf16 v[120:123], v[164:167], v[188:191], v[120:123]
	v_mfma_f32_16x16x32_bf16 v[108:111], v[156:159], v[196:199], v[108:111]
	v_mfma_f32_16x16x32_bf16 v[104:107], v[164:167], v[196:199], v[104:107]
	v_mfma_f32_16x16x32_bf16 v[92:95], v[156:159], v[204:207], v[92:95]
	v_mfma_f32_16x16x32_bf16 v[88:91], v[164:167], v[204:207], v[88:91]
	v_mfma_f32_16x16x32_bf16 v[76:79], v[156:159], v[212:215], v[76:79]
	v_mfma_f32_16x16x32_bf16 v[72:75], v[164:167], v[212:215], v[72:75]
	s_setprio 0
	s_setprio 1
	v_mfma_f32_16x16x32_bf16 v[116:119], v[168:171], v[184:187], v[116:119]
	v_mfma_f32_16x16x32_bf16 v[112:115], v[176:179], v[184:187], v[112:115]
	v_mfma_f32_16x16x32_bf16 v[100:103], v[168:171], v[192:195], v[100:103]
	v_mfma_f32_16x16x32_bf16 v[96:99], v[176:179], v[192:195], v[96:99]
	v_mfma_f32_16x16x32_bf16 v[84:87], v[168:171], v[200:203], v[84:87]
	v_mfma_f32_16x16x32_bf16 v[80:83], v[176:179], v[200:203], v[80:83]
	v_mfma_f32_16x16x32_bf16 v[68:71], v[168:171], v[208:211], v[68:71]
	v_mfma_f32_16x16x32_bf16 v[64:67], v[176:179], v[208:211], v[64:67]
	v_mfma_f32_16x16x32_bf16 v[116:119], v[172:175], v[188:191], v[116:119]
	v_mfma_f32_16x16x32_bf16 v[112:115], v[180:183], v[188:191], v[112:115]
	v_mfma_f32_16x16x32_bf16 v[100:103], v[172:175], v[196:199], v[100:103]
	v_mfma_f32_16x16x32_bf16 v[96:99], v[180:183], v[196:199], v[96:99]
	v_mfma_f32_16x16x32_bf16 v[84:87], v[172:175], v[204:207], v[84:87]
	v_mfma_f32_16x16x32_bf16 v[80:83], v[180:183], v[204:207], v[80:83]
	v_mfma_f32_16x16x32_bf16 v[68:71], v[172:175], v[212:215], v[68:71]
	v_mfma_f32_16x16x32_bf16 v[64:67], v[180:183], v[212:215], v[64:67]
	s_setprio 0
	s_barrier
	s_add_i32 s34, s62, s48
	v_lshl_add_u64 v[216:217], s[52:53], 0, v[130:131]
	s_mov_b32 m0, s34
	ds_read_b128 v[184:187], v153 offset:16384
	ds_read_b128 v[188:191], v153 offset:17408
	ds_read_b128 v[192:195], v153 offset:18432
	ds_read_b128 v[196:199], v153 offset:19456
	ds_read_b128 v[200:203], v153 offset:20480
	ds_read_b128 v[204:207], v153 offset:21504
	ds_read_b128 v[208:211], v153 offset:22528
	ds_read_b128 v[212:215], v153 offset:23552
	global_load_lds_dwordx4 v[216:217], off
	s_add_i32 m0, s34, 0x2000
	s_add_u32 s34, s52, 0x160000
	v_lshl_add_u64 v[218:219], s[52:53], 0, v[134:135]
	s_addc_u32 s35, s53, 0
	s_add_i32 s67, s63, s48
	global_load_lds_dwordx4 v[218:219], off
	v_lshl_add_u64 v[220:221], s[34:35], 0, v[130:131]
	s_mov_b32 m0, s67
	v_lshl_add_u64 v[222:223], s[54:55], 0, v[132:133]
	global_load_lds_dwordx4 v[220:221], off
	v_lshl_add_u64 v[220:221], s[34:35], 0, v[134:135]
	s_add_i32 m0, s67, 0x2000
	s_nop 0
	global_load_lds_dwordx4 v[220:221], off
	v_lshl_add_u64 v[220:221], s[54:55], 0, v[128:129]
	s_mov_b32 m0, s49
	s_nop 0
	global_load_lds_dwordx4 v[220:221], off
	s_mov_b32 m0, s56
	s_nop 0
	global_load_lds_dwordx4 v[222:223], off
	s_waitcnt vmcnt(8)
	s_waitcnt lgkmcnt(0)
	s_barrier
	s_setprio 1
	s_waitcnt lgkmcnt(0)
	v_mfma_f32_16x16x32_bf16 v[60:63], v[144:147], v[184:187], v[60:63]
	v_mfma_f32_16x16x32_bf16 v[56:59], v[160:163], v[184:187], v[56:59]
	v_mfma_f32_16x16x32_bf16 v[44:47], v[144:147], v[192:195], v[44:47]
	v_mfma_f32_16x16x32_bf16 v[40:43], v[160:163], v[192:195], v[40:43]
	v_mfma_f32_16x16x32_bf16 v[28:31], v[144:147], v[200:203], v[28:31]
	v_mfma_f32_16x16x32_bf16 v[24:27], v[160:163], v[200:203], v[24:27]
	v_mfma_f32_16x16x32_bf16 v[12:15], v[144:147], v[208:211], v[12:15]
	v_mfma_f32_16x16x32_bf16 v[8:11], v[160:163], v[208:211], v[8:11]
	v_mfma_f32_16x16x32_bf16 v[60:63], v[156:159], v[188:191], v[60:63]
	v_mfma_f32_16x16x32_bf16 v[56:59], v[164:167], v[188:191], v[56:59]
	v_mfma_f32_16x16x32_bf16 v[44:47], v[156:159], v[196:199], v[44:47]
	v_mfma_f32_16x16x32_bf16 v[40:43], v[164:167], v[196:199], v[40:43]
	v_mfma_f32_16x16x32_bf16 v[28:31], v[156:159], v[204:207], v[28:31]
	v_mfma_f32_16x16x32_bf16 v[24:27], v[164:167], v[204:207], v[24:27]
	v_mfma_f32_16x16x32_bf16 v[12:15], v[156:159], v[212:215], v[12:15]
	v_mfma_f32_16x16x32_bf16 v[8:11], v[164:167], v[212:215], v[8:11]
	s_setprio 0
	s_setprio 1
	v_mfma_f32_16x16x32_bf16 v[52:55], v[168:171], v[184:187], v[52:55]
	v_mfma_f32_16x16x32_bf16 v[48:51], v[176:179], v[184:187], v[48:51]
	v_mfma_f32_16x16x32_bf16 v[36:39], v[168:171], v[192:195], v[36:39]
	v_mfma_f32_16x16x32_bf16 v[32:35], v[176:179], v[192:195], v[32:35]
	v_mfma_f32_16x16x32_bf16 v[20:23], v[168:171], v[200:203], v[20:23]
	v_mfma_f32_16x16x32_bf16 v[16:19], v[176:179], v[200:203], v[16:19]
	v_mfma_f32_16x16x32_bf16 v[4:7], v[168:171], v[208:211], v[4:7]
	v_mfma_f32_16x16x32_bf16 v[0:3], v[176:179], v[208:211], v[0:3]
	v_mfma_f32_16x16x32_bf16 v[52:55], v[172:175], v[188:191], v[52:55]
	v_mfma_f32_16x16x32_bf16 v[48:51], v[180:183], v[188:191], v[48:51]
	v_mfma_f32_16x16x32_bf16 v[36:39], v[172:175], v[196:199], v[36:39]
	v_mfma_f32_16x16x32_bf16 v[32:35], v[180:183], v[196:199], v[32:35]
	v_mfma_f32_16x16x32_bf16 v[20:23], v[172:175], v[204:207], v[20:23]
	v_mfma_f32_16x16x32_bf16 v[16:19], v[180:183], v[204:207], v[16:19]
	v_mfma_f32_16x16x32_bf16 v[4:7], v[172:175], v[212:215], v[4:7]
	v_mfma_f32_16x16x32_bf16 v[0:3], v[180:183], v[212:215], v[0:3]
	s_setprio 0
	s_barrier
	s_add_i32 s67, 0, 0x18000
	v_add_u32_e32 v155, s67, v149
	s_add_i32 s70, 0, 0x1c000
	ds_read_b128 v[144:147], v155
	ds_read_b128 v[156:159], v155 offset:1024
	ds_read_b128 v[160:163], v155 offset:2048
	ds_read_b128 v[164:167], v155 offset:3072
	v_add_u32_e32 v155, s70, v149
	ds_read_b128 v[168:171], v155
	ds_read_b128 v[172:175], v155 offset:1024
	ds_read_b128 v[176:179], v155 offset:2048
	ds_read_b128 v[180:183], v155 offset:3072
	s_add_u32 s34, s54, 0x160000
	s_addc_u32 s35, s55, 0
	s_mov_b32 m0, s57
	v_lshl_add_u64 v[224:225], s[34:35], 0, v[128:129]
	ds_read_b128 v[184:187], v153 offset:32768
	ds_read_b128 v[188:191], v153 offset:33792
	ds_read_b128 v[192:195], v153 offset:34816
	ds_read_b128 v[196:199], v153 offset:35840
	ds_read_b128 v[200:203], v153 offset:36864
	ds_read_b128 v[204:207], v153 offset:37888
	ds_read_b128 v[208:211], v153 offset:38912
	ds_read_b128 v[212:215], v153 offset:39936
	global_load_lds_dwordx4 v[224:225], off
	v_lshl_add_u64 v[224:225], s[34:35], 0, v[132:133]
	s_mov_b32 m0, s58
	s_nop 0
	global_load_lds_dwordx4 v[224:225], off
	s_waitcnt vmcnt(8)
	s_waitcnt lgkmcnt(0)
	s_barrier
	s_setprio 1
	s_waitcnt lgkmcnt(0)
	v_mfma_f32_16x16x32_bf16 v[124:127], v[144:147], v[184:187], v[124:127]
	v_mfma_f32_16x16x32_bf16 v[120:123], v[160:163], v[184:187], v[120:123]
	v_mfma_f32_16x16x32_bf16 v[108:111], v[144:147], v[192:195], v[108:111]
	v_mfma_f32_16x16x32_bf16 v[104:107], v[160:163], v[192:195], v[104:107]
	v_mfma_f32_16x16x32_bf16 v[92:95], v[144:147], v[200:203], v[92:95]
	v_mfma_f32_16x16x32_bf16 v[88:91], v[160:163], v[200:203], v[88:91]
	v_mfma_f32_16x16x32_bf16 v[76:79], v[144:147], v[208:211], v[76:79]
	v_mfma_f32_16x16x32_bf16 v[72:75], v[160:163], v[208:211], v[72:75]
	v_mfma_f32_16x16x32_bf16 v[124:127], v[156:159], v[188:191], v[124:127]
	v_mfma_f32_16x16x32_bf16 v[120:123], v[164:167], v[188:191], v[120:123]
	v_mfma_f32_16x16x32_bf16 v[108:111], v[156:159], v[196:199], v[108:111]
	v_mfma_f32_16x16x32_bf16 v[104:107], v[164:167], v[196:199], v[104:107]
	v_mfma_f32_16x16x32_bf16 v[92:95], v[156:159], v[204:207], v[92:95]
	v_mfma_f32_16x16x32_bf16 v[88:91], v[164:167], v[204:207], v[88:91]
	v_mfma_f32_16x16x32_bf16 v[76:79], v[156:159], v[212:215], v[76:79]
	v_mfma_f32_16x16x32_bf16 v[72:75], v[164:167], v[212:215], v[72:75]
	s_setprio 0
	s_setprio 1
	v_mfma_f32_16x16x32_bf16 v[116:119], v[168:171], v[184:187], v[116:119]
	v_mfma_f32_16x16x32_bf16 v[112:115], v[176:179], v[184:187], v[112:115]
	v_mfma_f32_16x16x32_bf16 v[100:103], v[168:171], v[192:195], v[100:103]
	v_mfma_f32_16x16x32_bf16 v[96:99], v[176:179], v[192:195], v[96:99]
	v_mfma_f32_16x16x32_bf16 v[84:87], v[168:171], v[200:203], v[84:87]
	v_mfma_f32_16x16x32_bf16 v[80:83], v[176:179], v[200:203], v[80:83]
	v_mfma_f32_16x16x32_bf16 v[68:71], v[168:171], v[208:211], v[68:71]
	v_mfma_f32_16x16x32_bf16 v[64:67], v[176:179], v[208:211], v[64:67]
	v_mfma_f32_16x16x32_bf16 v[116:119], v[172:175], v[188:191], v[116:119]
	v_mfma_f32_16x16x32_bf16 v[112:115], v[180:183], v[188:191], v[112:115]
	v_mfma_f32_16x16x32_bf16 v[100:103], v[172:175], v[196:199], v[100:103]
	v_mfma_f32_16x16x32_bf16 v[96:99], v[180:183], v[196:199], v[96:99]
	v_mfma_f32_16x16x32_bf16 v[84:87], v[172:175], v[204:207], v[84:87]
	v_mfma_f32_16x16x32_bf16 v[80:83], v[180:183], v[204:207], v[80:83]
	v_mfma_f32_16x16x32_bf16 v[68:71], v[172:175], v[212:215], v[68:71]
	v_mfma_f32_16x16x32_bf16 v[64:67], v[180:183], v[212:215], v[64:67]
	s_setprio 0
	s_barrier
	s_add_i32 s34, s67, s48
	v_lshl_add_u64 v[216:217], v[216:217], 0, s[24:25]
	s_mov_b32 m0, s34
	ds_read_b128 v[184:187], v153 offset:49152
	ds_read_b128 v[188:191], v153 offset:50176
	ds_read_b128 v[192:195], v153 offset:51200
	ds_read_b128 v[196:199], v153 offset:52224
	ds_read_b128 v[200:203], v153 offset:53248
	ds_read_b128 v[204:207], v153 offset:54272
	ds_read_b128 v[208:211], v153 offset:55296
	ds_read_b128 v[212:215], v153 offset:56320
	global_load_lds_dwordx4 v[216:217], off
	s_add_i32 m0, s34, 0x2000
	s_add_u32 s34, s52, 0x160080
	v_lshl_add_u64 v[216:217], v[218:219], 0, s[24:25]
	s_addc_u32 s35, s53, 0
	s_add_i32 s52, s70, s48
	global_load_lds_dwordx4 v[216:217], off
	v_lshl_add_u64 v[216:217], s[34:35], 0, v[130:131]
	s_mov_b32 m0, s52
	s_nop 0
	global_load_lds_dwordx4 v[216:217], off
	v_lshl_add_u64 v[216:217], s[34:35], 0, v[134:135]
	s_add_i32 m0, s52, 0x2000
	s_nop 0
	global_load_lds_dwordx4 v[216:217], off
	v_lshl_add_u64 v[216:217], v[220:221], 0, s[24:25]
	s_mov_b32 m0, s60
	s_nop 0
	global_load_lds_dwordx4 v[216:217], off
	v_lshl_add_u64 v[216:217], v[222:223], 0, s[24:25]
	s_mov_b32 m0, s61
	s_nop 0
	global_load_lds_dwordx4 v[216:217], off
	s_waitcnt vmcnt(8)
	s_waitcnt lgkmcnt(0)
	s_barrier
	s_setprio 1
	s_waitcnt lgkmcnt(0)
	v_mfma_f32_16x16x32_bf16 v[60:63], v[144:147], v[184:187], v[60:63]
	v_mfma_f32_16x16x32_bf16 v[56:59], v[160:163], v[184:187], v[56:59]
	v_mfma_f32_16x16x32_bf16 v[44:47], v[144:147], v[192:195], v[44:47]
	v_mfma_f32_16x16x32_bf16 v[40:43], v[160:163], v[192:195], v[40:43]
	v_mfma_f32_16x16x32_bf16 v[28:31], v[144:147], v[200:203], v[28:31]
	v_mfma_f32_16x16x32_bf16 v[24:27], v[160:163], v[200:203], v[24:27]
	v_mfma_f32_16x16x32_bf16 v[12:15], v[144:147], v[208:211], v[12:15]
	v_mfma_f32_16x16x32_bf16 v[8:11], v[160:163], v[208:211], v[8:11]
	v_mfma_f32_16x16x32_bf16 v[60:63], v[156:159], v[188:191], v[60:63]
	v_mfma_f32_16x16x32_bf16 v[56:59], v[164:167], v[188:191], v[56:59]
	v_mfma_f32_16x16x32_bf16 v[44:47], v[156:159], v[196:199], v[44:47]
	v_mfma_f32_16x16x32_bf16 v[40:43], v[164:167], v[196:199], v[40:43]
	v_mfma_f32_16x16x32_bf16 v[28:31], v[156:159], v[204:207], v[28:31]
	v_mfma_f32_16x16x32_bf16 v[24:27], v[164:167], v[204:207], v[24:27]
	v_mfma_f32_16x16x32_bf16 v[12:15], v[156:159], v[212:215], v[12:15]
	v_mfma_f32_16x16x32_bf16 v[8:11], v[164:167], v[212:215], v[8:11]
	s_setprio 0
	s_setprio 1
	v_mfma_f32_16x16x32_bf16 v[52:55], v[168:171], v[184:187], v[52:55]
	v_mfma_f32_16x16x32_bf16 v[48:51], v[176:179], v[184:187], v[48:51]
	v_mfma_f32_16x16x32_bf16 v[36:39], v[168:171], v[192:195], v[36:39]
	v_mfma_f32_16x16x32_bf16 v[32:35], v[176:179], v[192:195], v[32:35]
	v_mfma_f32_16x16x32_bf16 v[20:23], v[168:171], v[200:203], v[20:23]
	v_mfma_f32_16x16x32_bf16 v[16:19], v[176:179], v[200:203], v[16:19]
	v_mfma_f32_16x16x32_bf16 v[4:7], v[168:171], v[208:211], v[4:7]
	v_mfma_f32_16x16x32_bf16 v[0:3], v[176:179], v[208:211], v[0:3]
	v_mfma_f32_16x16x32_bf16 v[52:55], v[172:175], v[188:191], v[52:55]
	v_mfma_f32_16x16x32_bf16 v[48:51], v[180:183], v[188:191], v[48:51]
	v_mfma_f32_16x16x32_bf16 v[36:39], v[172:175], v[196:199], v[36:39]
	v_mfma_f32_16x16x32_bf16 v[32:35], v[180:183], v[196:199], v[32:35]
	v_mfma_f32_16x16x32_bf16 v[20:23], v[172:175], v[204:207], v[20:23]
	v_mfma_f32_16x16x32_bf16 v[16:19], v[180:183], v[204:207], v[16:19]
	v_mfma_f32_16x16x32_bf16 v[4:7], v[172:175], v[212:215], v[4:7]
	v_mfma_f32_16x16x32_bf16 v[0:3], v[180:183], v[212:215], v[0:3]
	s_setprio 0
	s_barrier
	s_add_i32 s66, s66, 2
	s_add_u32 s46, s46, 0x100
	s_addc_u32 s47, s47, 0
	s_cmpk_gt_u32 s66, 0x55
	s_mov_b64 s[34:35], s[36:37]
	s_cbranch_scc0 .LBB0_523
	v_lshl_add_u32 v172, s51, 8, v148
	v_mov_b32_e32 v175, 0
	v_lshl_or_b32 v178, s16, 8, v150
	v_lshlrev_b32_e32 v178, 1, v178
	v_lshl_add_u32 v178, v172, 12, v178
	v_mov_b32_e32 v179, v178
	global_load_dwordx4 v[180:183], v179, s[22:23]
	global_load_dwordx4 v[184:187], v179, s[22:23] offset:256
	v_add_u32_e32 v179, 0x10000, v178
	global_load_dwordx4 v[188:191], v179, s[22:23]
	global_load_dwordx4 v[192:195], v179, s[22:23] offset:256
	v_add_u32_e32 v179, 0x20000, v178
	global_load_dwordx4 v[196:199], v179, s[22:23]
	global_load_dwordx4 v[200:203], v179, s[22:23] offset:256
	v_add_u32_e32 v179, 0x30000, v178
	global_load_dwordx4 v[204:207], v179, s[22:23]
	global_load_dwordx4 v[208:211], v179, s[22:23] offset:256
	v_add_u32_e32 v179, 0x80000, v178
	global_load_dwordx4 v[212:215], v179, s[22:23]
	s_and_b64 vcc, exec, s[26:27]
	s_cbranch_vccz .LBB0_526
	s_barrier
.LBB0_526:
	v_lshl_add_u32 v146, s51, 8, v148
	v_lshl_or_b32 v144, s16, 8, v150
	v_ashrrev_i32_e32 v147, 31, v146
	v_ashrrev_i32_e32 v145, 31, v144
	v_lshlrev_b64 v[156:157], 11, v[146:147]
	v_lshl_add_u64 v[156:157], v[156:157], 0, v[144:145]
	v_lshlrev_b64 v[160:161], 1, v[156:157]
	v_lshl_add_u64 v[156:157], s[22:23], 0, v[160:161]
	v_lshl_add_u64 v[162:163], s[20:21], 0, v[160:161]
	v_or_b32_e32 v160, 0x100, v160
	v_lshl_add_u64 v[164:165], s[22:23], 0, v[160:161]
	v_xor_b32_e32 v155, 32, v154
	s_lshl_b32 s34, s16, 2
	s_ashr_i32 s35, s34, 31
	s_waitcnt vmcnt(8)
	v_mov_b64_e32 v[156:157], v[180:181]
	v_mov_b64_e32 v[158:159], v[182:183]
	global_load_dwordx4 v[180:183], v179, s[22:23] offset:256
	v_lshlrev_b32_e32 v166, 16, v156
	v_and_b32_e32 v167, 0xffff0000, v156
	v_lshlrev_b32_e32 v156, 16, v157
	v_and_b32_e32 v157, 0xffff0000, v157
	v_lshlrev_b32_e32 v168, 16, v158
	v_and_b32_e32 v169, 0xffff0000, v158
	v_lshlrev_b32_e32 v158, 16, v159
	v_and_b32_e32 v159, 0xffff0000, v159
	v_pk_add_f32 v[126:127], v[126:127], v[156:157]
	v_pk_add_f32 v[166:167], v[124:125], v[166:167]
	v_pk_add_f32 v[170:171], v[122:123], v[158:159]
	v_pk_add_f32 v[168:169], v[120:121], v[168:169]
	v_cvt_pk_bf16_f32 v122, v166, v167
	v_cvt_pk_bf16_f32 v123, v126, v127
	v_mul_f32_e32 v127, v127, v127
	v_cvt_pk_bf16_f32 v124, v168, v169
	v_cvt_pk_bf16_f32 v125, v170, v171
	v_mul_f32_e32 v164, v167, v167
	v_mul_f32_e32 v165, v169, v169
	v_mul_f32_e32 v167, v171, v171
	v_fmac_f32_e32 v164, v166, v166
	v_fmac_f32_e32 v127, v126, v126
	v_fmac_f32_e32 v165, v168, v168
	v_fmac_f32_e32 v167, v170, v170
	v_add_f32_e32 v126, v164, v127
	v_add_f32_e32 v127, v165, v167
	v_add_f32_e32 v166, v126, v127
	v_and_b32_e32 v121, 64, v154
	v_xor_b32_e32 v120, 16, v154
	v_add_u32_e32 v121, 64, v121
	v_cmp_lt_i32_e32 vcc, v120, v121
	global_store_dwordx4 v[162:163], v[122:125], off
	s_waitcnt vmcnt(9)
	v_mov_b64_e32 v[156:157], v[184:185]
	v_mov_b64_e32 v[158:159], v[186:187]
	v_add_u32_e32 v179, 0x90000, v178
	global_load_dwordx4 v[184:187], v179, s[22:23]
	v_lshlrev_b32_e32 v126, 16, v156
	v_and_b32_e32 v127, 0xffff0000, v156
	v_lshlrev_b32_e32 v156, 16, v157
	v_and_b32_e32 v157, 0xffff0000, v157
	v_lshlrev_b32_e32 v164, 16, v158
	v_and_b32_e32 v165, 0xffff0000, v158
	v_lshlrev_b32_e32 v158, 16, v159
	v_and_b32_e32 v159, 0xffff0000, v159
	v_pk_add_f32 v[118:119], v[118:119], v[156:157]
	v_pk_add_f32 v[116:117], v[116:117], v[126:127]
	v_pk_add_f32 v[126:127], v[114:115], v[158:159]
	v_pk_add_f32 v[156:157], v[112:113], v[164:165]
	v_mul_f32_e32 v112, v117, v117
	v_mul_f32_e32 v113, v119, v119
	v_mul_f32_e32 v114, v157, v157
	v_mul_f32_e32 v115, v127, v127
	v_fmac_f32_e32 v112, v116, v116
	v_fmac_f32_e32 v113, v118, v118
	v_fmac_f32_e32 v114, v156, v156
	v_fmac_f32_e32 v115, v126, v126
	v_add_f32_e32 v112, v112, v113
	v_add_f32_e32 v113, v114, v115
	v_cndmask_b32_e32 v120, v154, v120, vcc
	v_add_f32_e32 v112, v112, v113
	v_lshlrev_b32_e32 v120, 2, v120
	v_add_f32_e32 v112, v166, v112
	ds_bpermute_b32 v113, v120, v112
	v_cmp_lt_i32_e32 vcc, v155, v121
	v_lshl_add_u64 v[122:123], s[20:21], 0, v[160:161]
	v_cvt_pk_bf16_f32 v116, v116, v117
	v_cvt_pk_bf16_f32 v117, v118, v119
	s_waitcnt lgkmcnt(0)
	v_add_f32_e32 v112, v112, v113
	v_cndmask_b32_e32 v114, v154, v155, vcc
	v_lshlrev_b32_e32 v114, 2, v114
	ds_bpermute_b32 v113, v114, v112
	v_cvt_pk_bf16_f32 v118, v156, v157
	v_cvt_pk_bf16_f32 v119, v126, v127
	global_store_dwordx4 v[122:123], v[116:119], off
	s_and_saveexec_b64 s[36:37], s[8:9]
	s_cbranch_execz .LBB0_528
	s_waitcnt lgkmcnt(0)
	v_add_f32_e32 v115, v112, v113
	v_lshlrev_b64 v[112:113], 7, v[146:147]
	v_lshl_add_u64 v[112:113], s[14:15], 0, v[112:113]
	v_lshl_add_u64 v[112:113], s[34:35], 2, v[112:113]
	s_lshl_b32 s16, s59, 2
	v_lshl_add_u64 v[112:113], v[112:113], 0, s[16:17]
	global_store_dword v[112:113], v115, off
.LBB0_528:
	s_or_b64 exec, exec, s[36:37]
	v_or_b32_e32 v112, 16, v146
	s_waitcnt lgkmcnt(0)
	v_ashrrev_i32_e32 v113, 31, v112
	v_lshlrev_b64 v[116:117], 11, v[112:113]
	v_lshl_add_u64 v[116:117], v[116:117], 0, v[144:145]
	v_lshlrev_b64 v[122:123], 1, v[116:117]
	v_lshl_add_u64 v[116:117], s[22:23], 0, v[122:123]
	v_lshl_add_u64 v[124:125], s[20:21], 0, v[122:123]
	v_or_b32_e32 v122, 0x100, v122
	v_lshl_add_u64 v[126:127], s[22:23], 0, v[122:123]
	s_waitcnt vmcnt(10)
	v_mov_b64_e32 v[116:117], v[188:189]
	v_mov_b64_e32 v[118:119], v[190:191]
	global_load_dwordx4 v[188:191], v179, s[22:23] offset:256
	v_lshlrev_b32_e32 v156, 16, v116
	v_and_b32_e32 v157, 0xffff0000, v116
	v_lshlrev_b32_e32 v116, 16, v117
	v_and_b32_e32 v117, 0xffff0000, v117
	v_lshlrev_b32_e32 v158, 16, v118
	v_and_b32_e32 v159, 0xffff0000, v118
	v_lshlrev_b32_e32 v118, 16, v119
	v_and_b32_e32 v119, 0xffff0000, v119
	v_pk_add_f32 v[116:117], v[110:111], v[116:117]
	v_pk_add_f32 v[156:157], v[108:109], v[156:157]
	v_pk_add_f32 v[118:119], v[106:107], v[118:119]
	v_pk_add_f32 v[158:159], v[104:105], v[158:159]
	v_cvt_pk_bf16_f32 v104, v156, v157
	v_cvt_pk_bf16_f32 v105, v116, v117
	v_mul_f32_e32 v115, v157, v157
	v_cvt_pk_bf16_f32 v106, v158, v159
	v_cvt_pk_bf16_f32 v107, v118, v119
	v_mul_f32_e32 v117, v117, v117
	v_mul_f32_e32 v121, v159, v159
	v_mul_f32_e32 v119, v119, v119
	v_fmac_f32_e32 v115, v156, v156
	v_fmac_f32_e32 v117, v116, v116
	v_fmac_f32_e32 v121, v158, v158
	v_fmac_f32_e32 v119, v118, v118
	v_add_f32_e32 v115, v115, v117
	v_add_f32_e32 v116, v121, v119
	v_add_f32_e32 v115, v115, v116
	global_store_dwordx4 v[124:125], v[104:107], off
	s_waitcnt vmcnt(11)
	v_mov_b64_e32 v[108:109], v[192:193]
	v_mov_b64_e32 v[110:111], v[194:195]
	v_add_u32_e32 v179, 0xa0000, v178
	global_load_dwordx4 v[192:195], v179, s[22:23]
	v_lshlrev_b32_e32 v116, 16, v108
	v_and_b32_e32 v117, 0xffff0000, v108
	v_lshlrev_b32_e32 v108, 16, v109
	v_and_b32_e32 v109, 0xffff0000, v109
	v_lshlrev_b32_e32 v118, 16, v110
	v_and_b32_e32 v119, 0xffff0000, v110
	v_lshlrev_b32_e32 v110, 16, v111
	v_and_b32_e32 v111, 0xffff0000, v111
	v_pk_add_f32 v[102:103], v[102:103], v[108:109]
	v_pk_add_f32 v[100:101], v[100:101], v[116:117]
	v_pk_add_f32 v[108:109], v[98:99], v[110:111]
	v_pk_add_f32 v[110:111], v[96:97], v[118:119]
	v_mul_f32_e32 v96, v101, v101
	v_mul_f32_e32 v97, v103, v103
	v_mul_f32_e32 v98, v111, v111
	v_mul_f32_e32 v99, v109, v109
	v_fmac_f32_e32 v96, v100, v100
	v_fmac_f32_e32 v97, v102, v102
	v_fmac_f32_e32 v98, v110, v110
	v_fmac_f32_e32 v99, v108, v108
	v_add_f32_e32 v96, v96, v97
	v_add_f32_e32 v97, v98, v99
	v_add_f32_e32 v96, v96, v97
	v_add_f32_e32 v96, v115, v96
	ds_bpermute_b32 v97, v120, v96
	v_cvt_pk_bf16_f32 v98, v100, v101
	v_cvt_pk_bf16_f32 v99, v102, v103
	v_lshl_add_u64 v[102:103], s[20:21], 0, v[122:123]
	v_cvt_pk_bf16_f32 v100, v110, v111
	s_waitcnt lgkmcnt(0)
	v_add_f32_e32 v96, v96, v97
	ds_bpermute_b32 v97, v114, v96
	v_cvt_pk_bf16_f32 v101, v108, v109
	global_store_dwordx4 v[102:103], v[98:101], off
	s_and_saveexec_b64 s[36:37], s[8:9]
	s_cbranch_execz .LBB0_530
	s_waitcnt lgkmcnt(0)
	v_add_f32_e32 v98, v96, v97
	v_lshlrev_b64 v[96:97], 7, v[112:113]
	v_lshl_add_u64 v[96:97], s[14:15], 0, v[96:97]
	v_lshl_add_u64 v[96:97], s[34:35], 2, v[96:97]
	s_lshl_b32 s16, s59, 2
	v_lshl_add_u64 v[96:97], v[96:97], 0, s[16:17]
	global_store_dword v[96:97], v98, off
.LBB0_530:
	s_or_b64 exec, exec, s[36:37]
	v_or_b32_e32 v96, 32, v146
	s_waitcnt lgkmcnt(0)
	v_ashrrev_i32_e32 v97, 31, v96
	v_lshlrev_b64 v[98:99], 11, v[96:97]
	v_lshl_add_u64 v[98:99], v[98:99], 0, v[144:145]
	v_lshlrev_b64 v[102:103], 1, v[98:99]
	v_lshl_add_u64 v[98:99], s[22:23], 0, v[102:103]
	v_lshl_add_u64 v[104:105], s[20:21], 0, v[102:103]
	v_or_b32_e32 v102, 0x100, v102
	v_lshl_add_u64 v[106:107], s[22:23], 0, v[102:103]
	s_waitcnt vmcnt(12)
	v_mov_b64_e32 v[98:99], v[196:197]
	v_mov_b64_e32 v[100:101], v[198:199]
	global_load_dwordx4 v[196:199], v179, s[22:23] offset:256
	v_lshlrev_b32_e32 v108, 16, v98
	v_and_b32_e32 v109, 0xffff0000, v98
	v_lshlrev_b32_e32 v98, 16, v99
	v_and_b32_e32 v99, 0xffff0000, v99
	v_lshlrev_b32_e32 v110, 16, v100
	v_and_b32_e32 v111, 0xffff0000, v100
	v_lshlrev_b32_e32 v100, 16, v101
	v_and_b32_e32 v101, 0xffff0000, v101
	v_pk_add_f32 v[98:99], v[94:95], v[98:99]
	v_pk_add_f32 v[108:109], v[92:93], v[108:109]
	v_pk_add_f32 v[100:101], v[90:91], v[100:101]
	v_pk_add_f32 v[110:111], v[88:89], v[110:111]
	v_cvt_pk_bf16_f32 v88, v108, v109
	v_cvt_pk_bf16_f32 v89, v98, v99
	v_mul_f32_e32 v99, v99, v99
	v_cvt_pk_bf16_f32 v90, v110, v111
	v_cvt_pk_bf16_f32 v91, v100, v101
	v_mul_f32_e32 v106, v109, v109
	v_mul_f32_e32 v107, v111, v111
	v_mul_f32_e32 v101, v101, v101
	v_fmac_f32_e32 v106, v108, v108
	v_fmac_f32_e32 v99, v98, v98
	v_fmac_f32_e32 v107, v110, v110
	v_fmac_f32_e32 v101, v100, v100
	v_add_f32_e32 v98, v106, v99
	v_add_f32_e32 v99, v107, v101
	v_add_f32_e32 v106, v98, v99
	global_store_dwordx4 v[104:105], v[88:91], off
	s_waitcnt vmcnt(13)
	v_mov_b64_e32 v[92:93], v[200:201]
	v_mov_b64_e32 v[94:95], v[202:203]
	v_add_u32_e32 v179, 0xb0000, v178
	global_load_dwordx4 v[200:203], v179, s[22:23]
	v_lshlrev_b32_e32 v98, 16, v92
	v_and_b32_e32 v99, 0xffff0000, v92
	v_lshlrev_b32_e32 v92, 16, v93
	v_and_b32_e32 v93, 0xffff0000, v93
	v_lshlrev_b32_e32 v100, 16, v94
	v_and_b32_e32 v101, 0xffff0000, v94
	v_lshlrev_b32_e32 v94, 16, v95
	v_and_b32_e32 v95, 0xffff0000, v95
	v_pk_add_f32 v[86:87], v[86:87], v[92:93]
	v_pk_add_f32 v[84:85], v[84:85], v[98:99]
	v_pk_add_f32 v[92:93], v[82:83], v[94:95]
	v_pk_add_f32 v[94:95], v[80:81], v[100:101]
	v_mul_f32_e32 v80, v85, v85
	v_mul_f32_e32 v81, v87, v87
	v_mul_f32_e32 v82, v95, v95
	v_mul_f32_e32 v83, v93, v93
	v_fmac_f32_e32 v80, v84, v84
	v_fmac_f32_e32 v81, v86, v86
	v_fmac_f32_e32 v82, v94, v94
	v_fmac_f32_e32 v83, v92, v92
	v_add_f32_e32 v80, v80, v81
	v_add_f32_e32 v81, v82, v83
	v_add_f32_e32 v80, v80, v81
	v_add_f32_e32 v80, v106, v80
	ds_bpermute_b32 v81, v120, v80
	v_cvt_pk_bf16_f32 v82, v84, v85
	v_cvt_pk_bf16_f32 v83, v86, v87
	v_lshl_add_u64 v[86:87], s[20:21], 0, v[102:103]
	v_cvt_pk_bf16_f32 v84, v94, v95
	s_waitcnt lgkmcnt(0)
	v_add_f32_e32 v80, v80, v81
	ds_bpermute_b32 v81, v114, v80
	v_cvt_pk_bf16_f32 v85, v92, v93
	global_store_dwordx4 v[86:87], v[82:85], off
	s_and_saveexec_b64 s[36:37], s[8:9]
	s_cbranch_execz .LBB0_532
	s_waitcnt lgkmcnt(0)
	v_add_f32_e32 v82, v80, v81
	v_lshlrev_b64 v[80:81], 7, v[96:97]
	v_lshl_add_u64 v[80:81], s[14:15], 0, v[80:81]
	v_lshl_add_u64 v[80:81], s[34:35], 2, v[80:81]
	s_lshl_b32 s16, s59, 2
	v_lshl_add_u64 v[80:81], v[80:81], 0, s[16:17]
	global_store_dword v[80:81], v82, off
.LBB0_532:
	s_or_b64 exec, exec, s[36:37]
	v_or_b32_e32 v80, 48, v146
	s_waitcnt lgkmcnt(0)
	v_ashrrev_i32_e32 v81, 31, v80
	v_lshlrev_b64 v[82:83], 11, v[80:81]
	v_lshl_add_u64 v[82:83], v[82:83], 0, v[144:145]
	v_lshlrev_b64 v[86:87], 1, v[82:83]
	v_lshl_add_u64 v[82:83], s[22:23], 0, v[86:87]
	v_lshl_add_u64 v[88:89], s[20:21], 0, v[86:87]
	v_or_b32_e32 v86, 0x100, v86
	v_lshl_add_u64 v[90:91], s[22:23], 0, v[86:87]
	s_waitcnt vmcnt(14)
	v_mov_b64_e32 v[82:83], v[204:205]
	v_mov_b64_e32 v[84:85], v[206:207]
	global_load_dwordx4 v[204:207], v179, s[22:23] offset:256
	v_lshlrev_b32_e32 v92, 16, v82
	v_and_b32_e32 v93, 0xffff0000, v82
	v_lshlrev_b32_e32 v82, 16, v83
	v_and_b32_e32 v83, 0xffff0000, v83
	v_lshlrev_b32_e32 v94, 16, v84
	v_and_b32_e32 v95, 0xffff0000, v84
	v_lshlrev_b32_e32 v84, 16, v85
	v_and_b32_e32 v85, 0xffff0000, v85
	v_pk_add_f32 v[82:83], v[78:79], v[82:83]
	v_pk_add_f32 v[92:93], v[76:77], v[92:93]
	v_pk_add_f32 v[84:85], v[74:75], v[84:85]
	v_pk_add_f32 v[94:95], v[72:73], v[94:95]
	v_cvt_pk_bf16_f32 v72, v92, v93
	v_cvt_pk_bf16_f32 v73, v82, v83
	v_mul_f32_e32 v83, v83, v83
	v_cvt_pk_bf16_f32 v74, v94, v95
	v_cvt_pk_bf16_f32 v75, v84, v85
	v_mul_f32_e32 v90, v93, v93
	v_mul_f32_e32 v91, v95, v95
	v_mul_f32_e32 v85, v85, v85
	v_fmac_f32_e32 v90, v92, v92
	v_fmac_f32_e32 v83, v82, v82
	v_fmac_f32_e32 v91, v94, v94
	v_fmac_f32_e32 v85, v84, v84
	v_add_f32_e32 v82, v90, v83
	v_add_f32_e32 v83, v91, v85
	v_add_f32_e32 v90, v82, v83
	global_store_dwordx4 v[88:89], v[72:75], off
	s_waitcnt vmcnt(15)
	v_mov_b64_e32 v[76:77], v[208:209]
	v_mov_b64_e32 v[78:79], v[210:211]
	v_lshlrev_b32_e32 v82, 16, v76
	v_and_b32_e32 v83, 0xffff0000, v76
	v_lshlrev_b32_e32 v76, 16, v77
	v_and_b32_e32 v77, 0xffff0000, v77
	v_lshlrev_b32_e32 v84, 16, v78
	v_and_b32_e32 v85, 0xffff0000, v78
	v_lshlrev_b32_e32 v78, 16, v79
	v_and_b32_e32 v79, 0xffff0000, v79
	v_pk_add_f32 v[70:71], v[70:71], v[76:77]
	v_pk_add_f32 v[68:69], v[68:69], v[82:83]
	v_pk_add_f32 v[76:77], v[66:67], v[78:79]
	v_pk_add_f32 v[78:79], v[64:65], v[84:85]
	v_mul_f32_e32 v64, v69, v69
	v_mul_f32_e32 v65, v71, v71
	v_mul_f32_e32 v66, v79, v79
	v_mul_f32_e32 v67, v77, v77
	v_fmac_f32_e32 v64, v68, v68
	v_fmac_f32_e32 v65, v70, v70
	v_fmac_f32_e32 v66, v78, v78
	v_fmac_f32_e32 v67, v76, v76
	v_add_f32_e32 v64, v64, v65
	v_add_f32_e32 v65, v66, v67
	v_add_f32_e32 v64, v64, v65
	v_add_f32_e32 v64, v90, v64
	ds_bpermute_b32 v65, v120, v64
	v_cvt_pk_bf16_f32 v66, v68, v69
	v_cvt_pk_bf16_f32 v67, v70, v71
	v_lshl_add_u64 v[70:71], s[20:21], 0, v[86:87]
	v_cvt_pk_bf16_f32 v68, v78, v79
	s_waitcnt lgkmcnt(0)
	v_add_f32_e32 v64, v64, v65
	ds_bpermute_b32 v65, v114, v64
	v_cvt_pk_bf16_f32 v69, v76, v77
	global_store_dwordx4 v[70:71], v[66:69], off
	s_and_saveexec_b64 s[36:37], s[8:9]
	s_cbranch_execz .LBB0_534
	s_waitcnt lgkmcnt(0)
	v_add_f32_e32 v66, v64, v65
	v_lshlrev_b64 v[64:65], 7, v[80:81]
	v_lshl_add_u64 v[64:65], s[14:15], 0, v[64:65]
	v_lshl_add_u64 v[64:65], s[34:35], 2, v[64:65]
	s_lshl_b32 s16, s59, 2
	v_lshl_add_u64 v[64:65], v[64:65], 0, s[16:17]
	global_store_dword v[64:65], v66, off
.LBB0_534:
	s_or_b64 exec, exec, s[36:37]
	v_add_u32_e32 v64, 0x80, v146
	s_waitcnt lgkmcnt(0)
	v_ashrrev_i32_e32 v65, 31, v64
	v_lshlrev_b64 v[66:67], 11, v[64:65]
	v_lshl_add_u64 v[66:67], v[66:67], 0, v[144:145]
	v_lshlrev_b64 v[70:71], 1, v[66:67]
	v_lshl_add_u64 v[66:67], s[22:23], 0, v[70:71]
	v_lshl_add_u64 v[72:73], s[20:21], 0, v[70:71]
	v_or_b32_e32 v70, 0x100, v70
	v_lshl_add_u64 v[74:75], s[22:23], 0, v[70:71]
	s_waitcnt vmcnt(15)
	v_mov_b64_e32 v[66:67], v[212:213]
	v_mov_b64_e32 v[68:69], v[214:215]
	v_lshlrev_b32_e32 v76, 16, v66
	v_and_b32_e32 v77, 0xffff0000, v66
	v_lshlrev_b32_e32 v66, 16, v67
	v_and_b32_e32 v67, 0xffff0000, v67
	v_lshlrev_b32_e32 v78, 16, v68
	v_and_b32_e32 v79, 0xffff0000, v68
	v_lshlrev_b32_e32 v68, 16, v69
	v_and_b32_e32 v69, 0xffff0000, v69
	v_pk_add_f32 v[66:67], v[62:63], v[66:67]
	v_pk_add_f32 v[76:77], v[60:61], v[76:77]
	v_pk_add_f32 v[68:69], v[58:59], v[68:69]
	v_pk_add_f32 v[78:79], v[56:57], v[78:79]
	v_cvt_pk_bf16_f32 v56, v76, v77
	v_cvt_pk_bf16_f32 v57, v66, v67
	v_mul_f32_e32 v67, v67, v67
	v_cvt_pk_bf16_f32 v58, v78, v79
	v_cvt_pk_bf16_f32 v59, v68, v69
	v_mul_f32_e32 v74, v77, v77
	v_mul_f32_e32 v75, v79, v79
	v_mul_f32_e32 v69, v69, v69
	v_fmac_f32_e32 v74, v76, v76
	v_fmac_f32_e32 v67, v66, v66
	v_fmac_f32_e32 v75, v78, v78
	v_fmac_f32_e32 v69, v68, v68
	v_add_f32_e32 v66, v74, v67
	v_add_f32_e32 v67, v75, v69
	v_add_f32_e32 v74, v66, v67
	global_store_dwordx4 v[72:73], v[56:59], off
	s_waitcnt vmcnt(15)
	v_mov_b64_e32 v[60:61], v[180:181]
	v_mov_b64_e32 v[62:63], v[182:183]
	v_lshlrev_b32_e32 v66, 16, v60
	v_and_b32_e32 v67, 0xffff0000, v60
	v_lshlrev_b32_e32 v60, 16, v61
	v_and_b32_e32 v61, 0xffff0000, v61
	v_lshlrev_b32_e32 v68, 16, v62
	v_and_b32_e32 v69, 0xffff0000, v62
	v_lshlrev_b32_e32 v62, 16, v63
	v_and_b32_e32 v63, 0xffff0000, v63
	v_pk_add_f32 v[54:55], v[54:55], v[60:61]
	v_pk_add_f32 v[52:53], v[52:53], v[66:67]
	v_pk_add_f32 v[60:61], v[50:51], v[62:63]
	v_pk_add_f32 v[62:63], v[48:49], v[68:69]
	v_mul_f32_e32 v48, v53, v53
	v_mul_f32_e32 v49, v55, v55
	v_mul_f32_e32 v50, v63, v63
	v_mul_f32_e32 v51, v61, v61
	v_fmac_f32_e32 v48, v52, v52
	v_fmac_f32_e32 v49, v54, v54
	v_fmac_f32_e32 v50, v62, v62
	v_fmac_f32_e32 v51, v60, v60
	v_add_f32_e32 v48, v48, v49
	v_add_f32_e32 v49, v50, v51
	v_add_f32_e32 v48, v48, v49
	v_add_f32_e32 v48, v74, v48
	ds_bpermute_b32 v49, v120, v48
	v_cvt_pk_bf16_f32 v50, v52, v53
	v_cvt_pk_bf16_f32 v51, v54, v55
	v_lshl_add_u64 v[54:55], s[20:21], 0, v[70:71]
	v_cvt_pk_bf16_f32 v52, v62, v63
	s_waitcnt lgkmcnt(0)
	v_add_f32_e32 v48, v48, v49
	ds_bpermute_b32 v49, v114, v48
	v_cvt_pk_bf16_f32 v53, v60, v61
	global_store_dwordx4 v[54:55], v[50:53], off
	s_and_saveexec_b64 s[36:37], s[8:9]
	s_cbranch_execz .LBB0_536
	s_waitcnt lgkmcnt(0)
	v_add_f32_e32 v50, v48, v49
	v_lshlrev_b64 v[48:49], 7, v[64:65]
	v_lshl_add_u64 v[48:49], s[14:15], 0, v[48:49]
	v_lshl_add_u64 v[48:49], s[34:35], 2, v[48:49]
	s_lshl_b32 s16, s59, 2
	v_lshl_add_u64 v[48:49], v[48:49], 0, s[16:17]
	global_store_dword v[48:49], v50, off
.LBB0_536:
	s_or_b64 exec, exec, s[36:37]
	v_add_u32_e32 v48, 0x90, v146
	s_waitcnt lgkmcnt(0)
	v_ashrrev_i32_e32 v49, 31, v48
	v_lshlrev_b64 v[50:51], 11, v[48:49]
	v_lshl_add_u64 v[50:51], v[50:51], 0, v[144:145]
	v_lshlrev_b64 v[54:55], 1, v[50:51]
	v_lshl_add_u64 v[50:51], s[22:23], 0, v[54:55]
	v_lshl_add_u64 v[56:57], s[20:21], 0, v[54:55]
	v_or_b32_e32 v54, 0x100, v54
	v_lshl_add_u64 v[58:59], s[22:23], 0, v[54:55]
	s_waitcnt vmcnt(14)
	v_mov_b64_e32 v[50:51], v[184:185]
	v_mov_b64_e32 v[52:53], v[186:187]
	v_lshlrev_b32_e32 v60, 16, v50
	v_and_b32_e32 v61, 0xffff0000, v50
	v_lshlrev_b32_e32 v50, 16, v51
	v_and_b32_e32 v51, 0xffff0000, v51
	v_lshlrev_b32_e32 v62, 16, v52
	v_and_b32_e32 v63, 0xffff0000, v52
	v_lshlrev_b32_e32 v52, 16, v53
	v_and_b32_e32 v53, 0xffff0000, v53
	v_pk_add_f32 v[50:51], v[46:47], v[50:51]
	v_pk_add_f32 v[60:61], v[44:45], v[60:61]
	v_pk_add_f32 v[52:53], v[42:43], v[52:53]
	v_pk_add_f32 v[62:63], v[40:41], v[62:63]
	v_cvt_pk_bf16_f32 v40, v60, v61
	v_cvt_pk_bf16_f32 v41, v50, v51
	v_mul_f32_e32 v51, v51, v51
	v_cvt_pk_bf16_f32 v42, v62, v63
	v_cvt_pk_bf16_f32 v43, v52, v53
	v_mul_f32_e32 v58, v61, v61
	v_mul_f32_e32 v59, v63, v63
	v_mul_f32_e32 v53, v53, v53
	v_fmac_f32_e32 v58, v60, v60
	v_fmac_f32_e32 v51, v50, v50
	v_fmac_f32_e32 v59, v62, v62
	v_fmac_f32_e32 v53, v52, v52
	v_add_f32_e32 v50, v58, v51
	v_add_f32_e32 v51, v59, v53
	v_add_f32_e32 v58, v50, v51
	global_store_dwordx4 v[56:57], v[40:43], off
	s_waitcnt vmcnt(13)
	v_mov_b64_e32 v[44:45], v[188:189]
	v_mov_b64_e32 v[46:47], v[190:191]
	v_lshlrev_b32_e32 v50, 16, v44
	v_and_b32_e32 v51, 0xffff0000, v44
	v_lshlrev_b32_e32 v44, 16, v45
	v_and_b32_e32 v45, 0xffff0000, v45
	v_lshlrev_b32_e32 v52, 16, v46
	v_and_b32_e32 v53, 0xffff0000, v46
	v_lshlrev_b32_e32 v46, 16, v47
	v_and_b32_e32 v47, 0xffff0000, v47
	v_pk_add_f32 v[38:39], v[38:39], v[44:45]
	v_pk_add_f32 v[36:37], v[36:37], v[50:51]
	v_pk_add_f32 v[44:45], v[34:35], v[46:47]
	v_pk_add_f32 v[46:47], v[32:33], v[52:53]
	v_mul_f32_e32 v32, v37, v37
	v_mul_f32_e32 v33, v39, v39
	v_mul_f32_e32 v34, v47, v47
	v_mul_f32_e32 v35, v45, v45
	v_fmac_f32_e32 v32, v36, v36
	v_fmac_f32_e32 v33, v38, v38
	v_fmac_f32_e32 v34, v46, v46
	v_fmac_f32_e32 v35, v44, v44
	v_add_f32_e32 v32, v32, v33
	v_add_f32_e32 v33, v34, v35
	v_add_f32_e32 v32, v32, v33
	v_add_f32_e32 v32, v58, v32
	ds_bpermute_b32 v33, v120, v32
	v_cvt_pk_bf16_f32 v34, v36, v37
	v_cvt_pk_bf16_f32 v35, v38, v39
	v_lshl_add_u64 v[38:39], s[20:21], 0, v[54:55]
	v_cvt_pk_bf16_f32 v36, v46, v47
	s_waitcnt lgkmcnt(0)
	v_add_f32_e32 v32, v32, v33
	ds_bpermute_b32 v33, v114, v32
	v_cvt_pk_bf16_f32 v37, v44, v45
	global_store_dwordx4 v[38:39], v[34:37], off
	s_and_saveexec_b64 s[36:37], s[8:9]
	s_cbranch_execz .LBB0_538
	s_waitcnt lgkmcnt(0)
	v_add_f32_e32 v34, v32, v33
	v_lshlrev_b64 v[32:33], 7, v[48:49]
	v_lshl_add_u64 v[32:33], s[14:15], 0, v[32:33]
	v_lshl_add_u64 v[32:33], s[34:35], 2, v[32:33]
	s_lshl_b32 s16, s59, 2
	v_lshl_add_u64 v[32:33], v[32:33], 0, s[16:17]
	global_store_dword v[32:33], v34, off
.LBB0_538:
	s_or_b64 exec, exec, s[36:37]
	v_add_u32_e32 v32, 0xa0, v146
	s_waitcnt lgkmcnt(0)
	v_ashrrev_i32_e32 v33, 31, v32
	v_lshlrev_b64 v[34:35], 11, v[32:33]
	v_lshl_add_u64 v[34:35], v[34:35], 0, v[144:145]
	v_lshlrev_b64 v[38:39], 1, v[34:35]
	v_lshl_add_u64 v[34:35], s[22:23], 0, v[38:39]
	v_lshl_add_u64 v[40:41], s[20:21], 0, v[38:39]
	v_or_b32_e32 v38, 0x100, v38
	v_lshl_add_u64 v[42:43], s[22:23], 0, v[38:39]
	s_waitcnt vmcnt(12)
	v_mov_b64_e32 v[34:35], v[192:193]
	v_mov_b64_e32 v[36:37], v[194:195]
	v_lshlrev_b32_e32 v44, 16, v34
	v_and_b32_e32 v45, 0xffff0000, v34
	v_lshlrev_b32_e32 v34, 16, v35
	v_and_b32_e32 v35, 0xffff0000, v35
	v_lshlrev_b32_e32 v46, 16, v36
	v_and_b32_e32 v47, 0xffff0000, v36
	v_lshlrev_b32_e32 v36, 16, v37
	v_and_b32_e32 v37, 0xffff0000, v37
	v_pk_add_f32 v[34:35], v[30:31], v[34:35]
	v_pk_add_f32 v[44:45], v[28:29], v[44:45]
	v_pk_add_f32 v[36:37], v[26:27], v[36:37]
	v_pk_add_f32 v[46:47], v[24:25], v[46:47]
	v_cvt_pk_bf16_f32 v24, v44, v45
	v_cvt_pk_bf16_f32 v25, v34, v35
	v_mul_f32_e32 v35, v35, v35
	v_cvt_pk_bf16_f32 v26, v46, v47
	v_cvt_pk_bf16_f32 v27, v36, v37
	v_mul_f32_e32 v42, v45, v45
	v_mul_f32_e32 v43, v47, v47
	v_mul_f32_e32 v37, v37, v37
	v_fmac_f32_e32 v42, v44, v44
	v_fmac_f32_e32 v35, v34, v34
	v_fmac_f32_e32 v43, v46, v46
	v_fmac_f32_e32 v37, v36, v36
	v_add_f32_e32 v34, v42, v35
	v_add_f32_e32 v35, v43, v37
	v_add_f32_e32 v42, v34, v35
	global_store_dwordx4 v[40:41], v[24:27], off
	s_waitcnt vmcnt(11)
	v_mov_b64_e32 v[28:29], v[196:197]
	v_mov_b64_e32 v[30:31], v[198:199]
	v_lshlrev_b32_e32 v34, 16, v28
	v_and_b32_e32 v35, 0xffff0000, v28
	v_lshlrev_b32_e32 v28, 16, v29
	v_and_b32_e32 v29, 0xffff0000, v29
	v_lshlrev_b32_e32 v36, 16, v30
	v_and_b32_e32 v37, 0xffff0000, v30
	v_lshlrev_b32_e32 v30, 16, v31
	v_and_b32_e32 v31, 0xffff0000, v31
	v_pk_add_f32 v[22:23], v[22:23], v[28:29]
	v_pk_add_f32 v[20:21], v[20:21], v[34:35]
	v_pk_add_f32 v[28:29], v[18:19], v[30:31]
	v_pk_add_f32 v[30:31], v[16:17], v[36:37]
	v_mul_f32_e32 v16, v21, v21
	v_mul_f32_e32 v17, v23, v23
	v_mul_f32_e32 v18, v31, v31
	v_mul_f32_e32 v19, v29, v29
	v_fmac_f32_e32 v16, v20, v20
	v_fmac_f32_e32 v17, v22, v22
	v_fmac_f32_e32 v18, v30, v30
	v_fmac_f32_e32 v19, v28, v28
	v_add_f32_e32 v16, v16, v17
	v_add_f32_e32 v17, v18, v19
	v_add_f32_e32 v16, v16, v17
	v_add_f32_e32 v16, v42, v16
	ds_bpermute_b32 v17, v120, v16
	v_cvt_pk_bf16_f32 v18, v20, v21
	v_cvt_pk_bf16_f32 v19, v22, v23
	v_lshl_add_u64 v[22:23], s[20:21], 0, v[38:39]
	v_cvt_pk_bf16_f32 v20, v30, v31
	s_waitcnt lgkmcnt(0)
	v_add_f32_e32 v16, v16, v17
	ds_bpermute_b32 v17, v114, v16
	v_cvt_pk_bf16_f32 v21, v28, v29
	global_store_dwordx4 v[22:23], v[18:21], off
	s_and_saveexec_b64 s[36:37], s[8:9]
	s_cbranch_execz .LBB0_540
	s_waitcnt lgkmcnt(0)
	v_add_f32_e32 v18, v16, v17
	v_lshlrev_b64 v[16:17], 7, v[32:33]
	v_lshl_add_u64 v[16:17], s[14:15], 0, v[16:17]
	v_lshl_add_u64 v[16:17], s[34:35], 2, v[16:17]
	s_lshl_b32 s16, s59, 2
	v_lshl_add_u64 v[16:17], v[16:17], 0, s[16:17]
	global_store_dword v[16:17], v18, off
.LBB0_540:
	s_or_b64 exec, exec, s[36:37]
	v_add_u32_e32 v16, 0xb0, v146
	s_waitcnt lgkmcnt(0)
	v_ashrrev_i32_e32 v17, 31, v16
	v_lshlrev_b64 v[18:19], 11, v[16:17]
	v_lshl_add_u64 v[18:19], v[18:19], 0, v[144:145]
	v_lshlrev_b64 v[22:23], 1, v[18:19]
	v_lshl_add_u64 v[18:19], s[22:23], 0, v[22:23]
	v_lshl_add_u64 v[24:25], s[20:21], 0, v[22:23]
	v_or_b32_e32 v22, 0x100, v22
	v_lshl_add_u64 v[26:27], s[22:23], 0, v[22:23]
	s_waitcnt vmcnt(10)
	v_mov_b64_e32 v[18:19], v[200:201]
	v_mov_b64_e32 v[20:21], v[202:203]
	v_lshlrev_b32_e32 v28, 16, v18
	v_and_b32_e32 v29, 0xffff0000, v18
	v_lshlrev_b32_e32 v18, 16, v19
	v_and_b32_e32 v19, 0xffff0000, v19
	v_lshlrev_b32_e32 v30, 16, v20
	v_and_b32_e32 v31, 0xffff0000, v20
	v_lshlrev_b32_e32 v20, 16, v21
	v_and_b32_e32 v21, 0xffff0000, v21
	v_pk_add_f32 v[18:19], v[14:15], v[18:19]
	v_pk_add_f32 v[28:29], v[12:13], v[28:29]
	v_pk_add_f32 v[20:21], v[10:11], v[20:21]
	v_pk_add_f32 v[30:31], v[8:9], v[30:31]
	v_cvt_pk_bf16_f32 v8, v28, v29
	v_cvt_pk_bf16_f32 v9, v18, v19
	v_mul_f32_e32 v19, v19, v19
	v_cvt_pk_bf16_f32 v10, v30, v31
	v_cvt_pk_bf16_f32 v11, v20, v21
	v_mul_f32_e32 v26, v29, v29
	v_mul_f32_e32 v27, v31, v31
	v_mul_f32_e32 v21, v21, v21
	v_fmac_f32_e32 v26, v28, v28
	v_fmac_f32_e32 v19, v18, v18
	v_fmac_f32_e32 v27, v30, v30
	v_fmac_f32_e32 v21, v20, v20
	v_add_f32_e32 v18, v26, v19
	v_add_f32_e32 v19, v27, v21
	v_add_f32_e32 v26, v18, v19
	global_store_dwordx4 v[24:25], v[8:11], off
	s_waitcnt vmcnt(9)
	v_mov_b64_e32 v[12:13], v[204:205]
	v_mov_b64_e32 v[14:15], v[206:207]
	v_lshlrev_b32_e32 v18, 16, v12
	v_and_b32_e32 v19, 0xffff0000, v12
	v_lshlrev_b32_e32 v12, 16, v13
	v_and_b32_e32 v13, 0xffff0000, v13
	v_lshlrev_b32_e32 v20, 16, v14
	v_and_b32_e32 v21, 0xffff0000, v14
	v_lshlrev_b32_e32 v14, 16, v15
	v_and_b32_e32 v15, 0xffff0000, v15
	v_pk_add_f32 v[6:7], v[6:7], v[12:13]
	v_pk_add_f32 v[4:5], v[4:5], v[18:19]
	v_pk_add_f32 v[12:13], v[2:3], v[14:15]
	v_pk_add_f32 v[14:15], v[0:1], v[20:21]
	v_mul_f32_e32 v0, v5, v5
	v_mul_f32_e32 v1, v7, v7
	v_mul_f32_e32 v2, v15, v15
	v_mul_f32_e32 v3, v13, v13
	v_fmac_f32_e32 v0, v4, v4
	v_fmac_f32_e32 v1, v6, v6
	v_fmac_f32_e32 v2, v14, v14
	v_fmac_f32_e32 v3, v12, v12
	v_add_f32_e32 v0, v0, v1
	v_add_f32_e32 v1, v2, v3
	v_add_f32_e32 v0, v0, v1
	v_add_f32_e32 v0, v26, v0
	ds_bpermute_b32 v1, v120, v0
	v_cvt_pk_bf16_f32 v2, v4, v5
	v_cvt_pk_bf16_f32 v3, v6, v7
	v_lshl_add_u64 v[6:7], s[20:21], 0, v[22:23]
	v_cvt_pk_bf16_f32 v4, v14, v15
	s_waitcnt lgkmcnt(0)
	v_add_f32_e32 v0, v0, v1
	ds_bpermute_b32 v1, v114, v0
	v_cvt_pk_bf16_f32 v5, v12, v13
	global_store_dwordx4 v[6:7], v[2:5], off
	s_and_saveexec_b64 s[36:37], s[8:9]
	s_cbranch_execz .LBB0_542
	s_waitcnt lgkmcnt(0)
	v_add_f32_e32 v2, v0, v1
	v_lshlrev_b64 v[0:1], 7, v[16:17]
	v_lshl_add_u64 v[0:1], s[14:15], 0, v[0:1]
	v_lshl_add_u64 v[0:1], s[34:35], 2, v[0:1]
	s_lshl_b32 s16, s59, 2
	v_lshl_add_u64 v[0:1], v[0:1], 0, s[16:17]
	global_store_dword v[0:1], v2, off

.LBB0_952:
	ds_read_b128 v[144:147], v151
	ds_read_b128 v[156:159], v151 offset:1024
	ds_read_b128 v[160:163], v151 offset:2048
	ds_read_b128 v[164:167], v151 offset:3072
	ds_read_b128 v[168:171], v152
	ds_read_b128 v[172:175], v152 offset:1024
	ds_read_b128 v[176:179], v152 offset:2048
	ds_read_b128 v[180:183], v152 offset:3072
	s_add_u32 s54, s52, 0xfff80080
	s_addc_u32 s55, s53, -1
	s_cmp_eq_u32 s68, 28
	s_cselect_b32 s57, s27, s55
	s_cselect_b32 s56, s37, s54
	s_cselect_b32 s55, s25, s67
	s_cselect_b32 s54, s46, s47
	v_lshl_add_u64 v[216:217], s[52:53], 0, v[138:139]
	s_add_i32 m0, s59, 0xc000
	ds_read_b128 v[184:187], v153
	ds_read_b128 v[188:191], v153 offset:1024
	ds_read_b128 v[192:195], v153 offset:2048
	ds_read_b128 v[196:199], v153 offset:3072
	ds_read_b128 v[200:203], v153 offset:4096
	ds_read_b128 v[204:207], v153 offset:5120
	ds_read_b128 v[208:211], v153 offset:6144
	ds_read_b128 v[212:215], v153 offset:7168
	global_load_lds_dwordx4 v[216:217], off
	v_lshl_add_u64 v[216:217], s[52:53], 0, v[136:137]
	s_add_i32 m0, s59, 0xe000
	s_nop 0
	global_load_lds_dwordx4 v[216:217], off
	s_waitcnt vmcnt(8)
	s_waitcnt lgkmcnt(0)
	s_barrier
	s_setprio 1
	s_waitcnt lgkmcnt(0)
	v_mfma_f32_16x16x32_bf16 v[116:119], v[144:147], v[184:187], v[116:119]
	v_mfma_f32_16x16x32_bf16 v[112:115], v[160:163], v[184:187], v[112:115]
	v_mfma_f32_16x16x32_bf16 v[104:107], v[144:147], v[192:195], v[104:107]
	v_mfma_f32_16x16x32_bf16 v[96:99], v[160:163], v[192:195], v[96:99]
	v_mfma_f32_16x16x32_bf16 v[88:91], v[144:147], v[200:203], v[88:91]
	v_mfma_f32_16x16x32_bf16 v[80:83], v[160:163], v[200:203], v[80:83]
	v_mfma_f32_16x16x32_bf16 v[72:75], v[144:147], v[208:211], v[72:75]
	v_mfma_f32_16x16x32_bf16 v[64:67], v[160:163], v[208:211], v[64:67]
	v_mfma_f32_16x16x32_bf16 v[116:119], v[156:159], v[188:191], v[116:119]
	v_mfma_f32_16x16x32_bf16 v[112:115], v[164:167], v[188:191], v[112:115]
	v_mfma_f32_16x16x32_bf16 v[104:107], v[156:159], v[196:199], v[104:107]
	v_mfma_f32_16x16x32_bf16 v[96:99], v[164:167], v[196:199], v[96:99]
	v_mfma_f32_16x16x32_bf16 v[88:91], v[156:159], v[204:207], v[88:91]
	v_mfma_f32_16x16x32_bf16 v[80:83], v[164:167], v[204:207], v[80:83]
	v_mfma_f32_16x16x32_bf16 v[72:75], v[156:159], v[212:215], v[72:75]
	v_mfma_f32_16x16x32_bf16 v[64:67], v[164:167], v[212:215], v[64:67]
	s_setprio 0
	s_setprio 1
	v_mfma_f32_16x16x32_bf16 v[124:127], v[168:171], v[184:187], v[124:127]
	v_mfma_f32_16x16x32_bf16 v[120:123], v[176:179], v[184:187], v[120:123]
	v_mfma_f32_16x16x32_bf16 v[108:111], v[168:171], v[192:195], v[108:111]
	v_mfma_f32_16x16x32_bf16 v[100:103], v[176:179], v[192:195], v[100:103]
	v_mfma_f32_16x16x32_bf16 v[92:95], v[168:171], v[200:203], v[92:95]
	v_mfma_f32_16x16x32_bf16 v[84:87], v[176:179], v[200:203], v[84:87]
	v_mfma_f32_16x16x32_bf16 v[76:79], v[168:171], v[208:211], v[76:79]
	v_mfma_f32_16x16x32_bf16 v[68:71], v[176:179], v[208:211], v[68:71]
	v_mfma_f32_16x16x32_bf16 v[124:127], v[172:175], v[188:191], v[124:127]
	v_mfma_f32_16x16x32_bf16 v[120:123], v[180:183], v[188:191], v[120:123]
	v_mfma_f32_16x16x32_bf16 v[108:111], v[172:175], v[196:199], v[108:111]
	v_mfma_f32_16x16x32_bf16 v[100:103], v[180:183], v[196:199], v[100:103]
	v_mfma_f32_16x16x32_bf16 v[92:95], v[172:175], v[204:207], v[92:95]
	v_mfma_f32_16x16x32_bf16 v[84:87], v[180:183], v[204:207], v[84:87]
	v_mfma_f32_16x16x32_bf16 v[76:79], v[172:175], v[212:215], v[76:79]
	v_mfma_f32_16x16x32_bf16 v[68:71], v[180:183], v[212:215], v[68:71]
	s_setprio 0
	s_barrier
	s_add_i32 s69, s64, s58
	v_lshl_add_u64 v[216:217], s[54:55], 0, v[130:131]
	s_mov_b32 m0, s69
	ds_read_b128 v[184:187], v153 offset:16384
	ds_read_b128 v[188:191], v153 offset:17408
	ds_read_b128 v[192:195], v153 offset:18432
	ds_read_b128 v[196:199], v153 offset:19456
	ds_read_b128 v[200:203], v153 offset:20480
	ds_read_b128 v[204:207], v153 offset:21504
	ds_read_b128 v[208:211], v153 offset:22528
	ds_read_b128 v[212:215], v153 offset:23552
	global_load_lds_dwordx4 v[216:217], off
	s_add_i32 m0, s69, 0x2000
	s_add_u32 s70, s54, 0x80000
	v_lshl_add_u64 v[218:219], s[54:55], 0, v[134:135]
	s_addc_u32 s71, s55, 0
	s_add_i32 s69, s65, s58
	global_load_lds_dwordx4 v[218:219], off
	v_lshl_add_u64 v[220:221], s[70:71], 0, v[130:131]
	s_mov_b32 m0, s69
	v_lshl_add_u64 v[222:223], s[56:57], 0, v[132:133]
	global_load_lds_dwordx4 v[220:221], off
	v_lshl_add_u64 v[220:221], s[70:71], 0, v[134:135]
	s_add_i32 m0, s69, 0x2000
	s_nop 0
	global_load_lds_dwordx4 v[220:221], off
	v_lshl_add_u64 v[220:221], s[56:57], 0, v[128:129]
	s_mov_b32 m0, s59
	s_nop 0
	global_load_lds_dwordx4 v[220:221], off
	s_mov_b32 m0, s50
	s_nop 0
	global_load_lds_dwordx4 v[222:223], off
	s_waitcnt vmcnt(8)
	s_waitcnt lgkmcnt(0)
	s_barrier
	s_setprio 1
	s_waitcnt lgkmcnt(0)
	v_mfma_f32_16x16x32_bf16 v[56:59], v[144:147], v[184:187], v[56:59]
	v_mfma_f32_16x16x32_bf16 v[48:51], v[160:163], v[184:187], v[48:51]
	v_mfma_f32_16x16x32_bf16 v[40:43], v[144:147], v[192:195], v[40:43]
	v_mfma_f32_16x16x32_bf16 v[32:35], v[160:163], v[192:195], v[32:35]
	v_mfma_f32_16x16x32_bf16 v[24:27], v[144:147], v[200:203], v[24:27]
	v_mfma_f32_16x16x32_bf16 v[16:19], v[160:163], v[200:203], v[16:19]
	v_mfma_f32_16x16x32_bf16 v[8:11], v[144:147], v[208:211], v[8:11]
	v_mfma_f32_16x16x32_bf16 v[0:3], v[160:163], v[208:211], v[0:3]
	v_mfma_f32_16x16x32_bf16 v[56:59], v[156:159], v[188:191], v[56:59]
	v_mfma_f32_16x16x32_bf16 v[48:51], v[164:167], v[188:191], v[48:51]
	v_mfma_f32_16x16x32_bf16 v[40:43], v[156:159], v[196:199], v[40:43]
	v_mfma_f32_16x16x32_bf16 v[32:35], v[164:167], v[196:199], v[32:35]
	v_mfma_f32_16x16x32_bf16 v[24:27], v[156:159], v[204:207], v[24:27]
	v_mfma_f32_16x16x32_bf16 v[16:19], v[164:167], v[204:207], v[16:19]
	v_mfma_f32_16x16x32_bf16 v[8:11], v[156:159], v[212:215], v[8:11]
	v_mfma_f32_16x16x32_bf16 v[0:3], v[164:167], v[212:215], v[0:3]
	s_setprio 0
	s_setprio 1
	v_mfma_f32_16x16x32_bf16 v[60:63], v[168:171], v[184:187], v[60:63]
	v_mfma_f32_16x16x32_bf16 v[52:55], v[176:179], v[184:187], v[52:55]
	v_mfma_f32_16x16x32_bf16 v[44:47], v[168:171], v[192:195], v[44:47]
	v_mfma_f32_16x16x32_bf16 v[36:39], v[176:179], v[192:195], v[36:39]
	v_mfma_f32_16x16x32_bf16 v[28:31], v[168:171], v[200:203], v[28:31]
	v_mfma_f32_16x16x32_bf16 v[20:23], v[176:179], v[200:203], v[20:23]
	v_mfma_f32_16x16x32_bf16 v[12:15], v[168:171], v[208:211], v[12:15]
	v_mfma_f32_16x16x32_bf16 v[4:7], v[176:179], v[208:211], v[4:7]
	v_mfma_f32_16x16x32_bf16 v[60:63], v[172:175], v[188:191], v[60:63]
	v_mfma_f32_16x16x32_bf16 v[52:55], v[180:183], v[188:191], v[52:55]
	v_mfma_f32_16x16x32_bf16 v[44:47], v[172:175], v[196:199], v[44:47]
	v_mfma_f32_16x16x32_bf16 v[36:39], v[180:183], v[196:199], v[36:39]
	v_mfma_f32_16x16x32_bf16 v[28:31], v[172:175], v[204:207], v[28:31]
	v_mfma_f32_16x16x32_bf16 v[20:23], v[180:183], v[204:207], v[20:23]
	v_mfma_f32_16x16x32_bf16 v[12:15], v[172:175], v[212:215], v[12:15]
	v_mfma_f32_16x16x32_bf16 v[4:7], v[180:183], v[212:215], v[4:7]
	s_setprio 0
	s_barrier
	s_add_i32 s69, 0, 0x18000
	v_add_u32_e32 v155, s69, v149
	s_add_i32 s70, 0, 0x1c000
	ds_read_b128 v[144:147], v155
	ds_read_b128 v[156:159], v155 offset:1024
	ds_read_b128 v[160:163], v155 offset:2048
	ds_read_b128 v[164:167], v155 offset:3072
	v_add_u32_e32 v155, s70, v149
	ds_read_b128 v[168:171], v155
	ds_read_b128 v[172:175], v155 offset:1024
	ds_read_b128 v[176:179], v155 offset:2048
	ds_read_b128 v[180:183], v155 offset:3072
	s_add_u32 s56, s56, 0x80000
	s_addc_u32 s57, s57, 0
	s_mov_b32 m0, s51
	v_lshl_add_u64 v[224:225], s[56:57], 0, v[128:129]
	ds_read_b128 v[184:187], v153 offset:32768
	ds_read_b128 v[188:191], v153 offset:33792
	ds_read_b128 v[192:195], v153 offset:34816
	ds_read_b128 v[196:199], v153 offset:35840
	ds_read_b128 v[200:203], v153 offset:36864
	ds_read_b128 v[204:207], v153 offset:37888
	ds_read_b128 v[208:211], v153 offset:38912
	ds_read_b128 v[212:215], v153 offset:39936
	global_load_lds_dwordx4 v[224:225], off
	v_lshl_add_u64 v[224:225], s[56:57], 0, v[132:133]
	s_mov_b32 m0, s60
	s_nop 0
	global_load_lds_dwordx4 v[224:225], off
	s_waitcnt vmcnt(8)
	s_waitcnt lgkmcnt(0)
	s_barrier
	s_setprio 1
	s_waitcnt lgkmcnt(0)
	v_mfma_f32_16x16x32_bf16 v[116:119], v[144:147], v[184:187], v[116:119]
	v_mfma_f32_16x16x32_bf16 v[112:115], v[160:163], v[184:187], v[112:115]
	v_mfma_f32_16x16x32_bf16 v[104:107], v[144:147], v[192:195], v[104:107]
	v_mfma_f32_16x16x32_bf16 v[96:99], v[160:163], v[192:195], v[96:99]
	v_mfma_f32_16x16x32_bf16 v[88:91], v[144:147], v[200:203], v[88:91]
	v_mfma_f32_16x16x32_bf16 v[80:83], v[160:163], v[200:203], v[80:83]
	v_mfma_f32_16x16x32_bf16 v[72:75], v[144:147], v[208:211], v[72:75]
	v_mfma_f32_16x16x32_bf16 v[64:67], v[160:163], v[208:211], v[64:67]
	v_mfma_f32_16x16x32_bf16 v[116:119], v[156:159], v[188:191], v[116:119]
	v_mfma_f32_16x16x32_bf16 v[112:115], v[164:167], v[188:191], v[112:115]
	v_mfma_f32_16x16x32_bf16 v[104:107], v[156:159], v[196:199], v[104:107]
	v_mfma_f32_16x16x32_bf16 v[96:99], v[164:167], v[196:199], v[96:99]
	v_mfma_f32_16x16x32_bf16 v[88:91], v[156:159], v[204:207], v[88:91]
	v_mfma_f32_16x16x32_bf16 v[80:83], v[164:167], v[204:207], v[80:83]
	v_mfma_f32_16x16x32_bf16 v[72:75], v[156:159], v[212:215], v[72:75]
	v_mfma_f32_16x16x32_bf16 v[64:67], v[164:167], v[212:215], v[64:67]
	s_setprio 0
	s_setprio 1
	v_mfma_f32_16x16x32_bf16 v[124:127], v[168:171], v[184:187], v[124:127]
	v_mfma_f32_16x16x32_bf16 v[120:123], v[176:179], v[184:187], v[120:123]
	v_mfma_f32_16x16x32_bf16 v[108:111], v[168:171], v[192:195], v[108:111]
	v_mfma_f32_16x16x32_bf16 v[100:103], v[176:179], v[192:195], v[100:103]
	v_mfma_f32_16x16x32_bf16 v[92:95], v[168:171], v[200:203], v[92:95]
	v_mfma_f32_16x16x32_bf16 v[84:87], v[176:179], v[200:203], v[84:87]
	v_mfma_f32_16x16x32_bf16 v[76:79], v[168:171], v[208:211], v[76:79]
	v_mfma_f32_16x16x32_bf16 v[68:71], v[176:179], v[208:211], v[68:71]
	v_mfma_f32_16x16x32_bf16 v[124:127], v[172:175], v[188:191], v[124:127]
	v_mfma_f32_16x16x32_bf16 v[120:123], v[180:183], v[188:191], v[120:123]
	v_mfma_f32_16x16x32_bf16 v[108:111], v[172:175], v[196:199], v[108:111]
	v_mfma_f32_16x16x32_bf16 v[100:103], v[180:183], v[196:199], v[100:103]
	v_mfma_f32_16x16x32_bf16 v[92:95], v[172:175], v[204:207], v[92:95]
	v_mfma_f32_16x16x32_bf16 v[84:87], v[180:183], v[204:207], v[84:87]
	v_mfma_f32_16x16x32_bf16 v[76:79], v[172:175], v[212:215], v[76:79]
	v_mfma_f32_16x16x32_bf16 v[68:71], v[180:183], v[212:215], v[68:71]
	s_setprio 0
	s_barrier
	s_add_i32 s56, s69, s58
	v_lshl_add_u64 v[216:217], v[216:217], 0, s[20:21]
	s_mov_b32 m0, s56
	ds_read_b128 v[184:187], v153 offset:49152
	ds_read_b128 v[188:191], v153 offset:50176
	ds_read_b128 v[192:195], v153 offset:51200
	ds_read_b128 v[196:199], v153 offset:52224
	ds_read_b128 v[200:203], v153 offset:53248
	ds_read_b128 v[204:207], v153 offset:54272
	ds_read_b128 v[208:211], v153 offset:55296
	ds_read_b128 v[212:215], v153 offset:56320
	global_load_lds_dwordx4 v[216:217], off
	s_add_i32 m0, s56, 0x2000
	s_add_u32 s54, s54, 0x80080
	v_lshl_add_u64 v[216:217], v[218:219], 0, s[20:21]
	s_addc_u32 s55, s55, 0
	s_add_i32 s56, s70, s58
	global_load_lds_dwordx4 v[216:217], off
	v_lshl_add_u64 v[216:217], s[54:55], 0, v[130:131]
	s_mov_b32 m0, s56
	s_nop 0
	global_load_lds_dwordx4 v[216:217], off
	v_lshl_add_u64 v[216:217], s[54:55], 0, v[134:135]
	s_add_i32 m0, s56, 0x2000
	s_nop 0
	global_load_lds_dwordx4 v[216:217], off
	v_lshl_add_u64 v[216:217], v[220:221], 0, s[20:21]
	s_mov_b32 m0, s62
	s_nop 0
	global_load_lds_dwordx4 v[216:217], off
	v_lshl_add_u64 v[216:217], v[222:223], 0, s[20:21]
	s_mov_b32 m0, s63
	s_nop 0
	global_load_lds_dwordx4 v[216:217], off
	s_waitcnt vmcnt(8)
	s_waitcnt lgkmcnt(0)
	s_barrier
	s_setprio 1
	s_waitcnt lgkmcnt(0)
	v_mfma_f32_16x16x32_bf16 v[56:59], v[144:147], v[184:187], v[56:59]
	v_mfma_f32_16x16x32_bf16 v[48:51], v[160:163], v[184:187], v[48:51]
	v_mfma_f32_16x16x32_bf16 v[40:43], v[144:147], v[192:195], v[40:43]
	v_mfma_f32_16x16x32_bf16 v[32:35], v[160:163], v[192:195], v[32:35]
	v_mfma_f32_16x16x32_bf16 v[24:27], v[144:147], v[200:203], v[24:27]
	v_mfma_f32_16x16x32_bf16 v[16:19], v[160:163], v[200:203], v[16:19]
	v_mfma_f32_16x16x32_bf16 v[8:11], v[144:147], v[208:211], v[8:11]
	v_mfma_f32_16x16x32_bf16 v[0:3], v[160:163], v[208:211], v[0:3]
	v_mfma_f32_16x16x32_bf16 v[56:59], v[156:159], v[188:191], v[56:59]
	v_mfma_f32_16x16x32_bf16 v[48:51], v[164:167], v[188:191], v[48:51]
	v_mfma_f32_16x16x32_bf16 v[40:43], v[156:159], v[196:199], v[40:43]
	v_mfma_f32_16x16x32_bf16 v[32:35], v[164:167], v[196:199], v[32:35]
	v_mfma_f32_16x16x32_bf16 v[24:27], v[156:159], v[204:207], v[24:27]
	v_mfma_f32_16x16x32_bf16 v[16:19], v[164:167], v[204:207], v[16:19]
	v_mfma_f32_16x16x32_bf16 v[8:11], v[156:159], v[212:215], v[8:11]
	v_mfma_f32_16x16x32_bf16 v[0:3], v[164:167], v[212:215], v[0:3]
	s_setprio 0
	s_setprio 1
	v_mfma_f32_16x16x32_bf16 v[60:63], v[168:171], v[184:187], v[60:63]
	v_mfma_f32_16x16x32_bf16 v[52:55], v[176:179], v[184:187], v[52:55]
	v_mfma_f32_16x16x32_bf16 v[44:47], v[168:171], v[192:195], v[44:47]
	v_mfma_f32_16x16x32_bf16 v[36:39], v[176:179], v[192:195], v[36:39]
	v_mfma_f32_16x16x32_bf16 v[28:31], v[168:171], v[200:203], v[28:31]
	v_mfma_f32_16x16x32_bf16 v[20:23], v[176:179], v[200:203], v[20:23]
	v_mfma_f32_16x16x32_bf16 v[12:15], v[168:171], v[208:211], v[12:15]
	v_mfma_f32_16x16x32_bf16 v[4:7], v[176:179], v[208:211], v[4:7]
	v_mfma_f32_16x16x32_bf16 v[60:63], v[172:175], v[188:191], v[60:63]
	v_mfma_f32_16x16x32_bf16 v[52:55], v[180:183], v[188:191], v[52:55]
	v_mfma_f32_16x16x32_bf16 v[44:47], v[172:175], v[196:199], v[44:47]
	v_mfma_f32_16x16x32_bf16 v[36:39], v[180:183], v[196:199], v[36:39]
	v_mfma_f32_16x16x32_bf16 v[28:31], v[172:175], v[204:207], v[28:31]
	v_mfma_f32_16x16x32_bf16 v[20:23], v[180:183], v[204:207], v[20:23]
	v_mfma_f32_16x16x32_bf16 v[12:15], v[172:175], v[212:215], v[12:15]
	v_mfma_f32_16x16x32_bf16 v[4:7], v[180:183], v[212:215], v[4:7]
	s_setprio 0
	s_barrier
	s_add_i32 s68, s68, 2
	s_add_u32 s47, s47, 0x100
	s_addc_u32 s67, s67, 0
	s_add_u32 s52, s52, 0x100
	s_addc_u32 s53, s53, 0
	s_cmp_gt_u32 s68, 29
	s_cbranch_scc0 .LBB0_952
	v_lshl_add_u32 v168, s36, 8, v148
	v_mov_b32_e32 v171, 0
	v_lshl_or_b32 v174, s12, 7, v150
	v_lshlrev_b32_e32 v174, 1, v174
	v_lshl_add_u32 v174, v168, 12, v174
	v_mov_b32_e32 v175, v174
	global_load_dwordx4 v[176:179], v175, s[16:17]
	v_add_u32_e32 v175, 0x10000, v174
	global_load_dwordx4 v[180:183], v175, s[16:17]
	v_add_u32_e32 v175, 0x20000, v174
	global_load_dwordx4 v[184:187], v175, s[16:17]
	v_add_u32_e32 v175, 0x30000, v174
	global_load_dwordx4 v[188:191], v175, s[16:17]
	v_add_u32_e32 v175, 0x80000, v174
	global_load_dwordx4 v[192:195], v175, s[16:17]
	v_add_u32_e32 v175, 0x90000, v174
	global_load_dwordx4 v[196:199], v175, s[16:17]
	v_add_u32_e32 v175, 0xa0000, v174
	global_load_dwordx4 v[200:203], v175, s[16:17]
	v_add_u32_e32 v175, 0xb0000, v174
	global_load_dwordx4 v[204:207], v175, s[16:17]
	s_and_b64 vcc, exec, s[22:23]
	s_cbranch_vccz .LBB0_955
	s_barrier
.LBB0_955:
	v_lshl_add_u32 v146, s36, 8, v148
	v_lshl_or_b32 v144, s12, 7, v150
	v_ashrrev_i32_e32 v147, 31, v146
	v_ashrrev_i32_e32 v145, 31, v144
	v_lshlrev_b64 v[156:157], 11, v[146:147]
	v_lshl_add_u64 v[156:157], v[156:157], 0, v[144:145]
	v_lshlrev_b64 v[160:161], 1, v[156:157]
	v_lshl_add_u64 v[156:157], s[16:17], 0, v[160:161]
	v_mul_f32_e32 v125, 0xbfb8aa3b, v125
	v_mul_f32_e32 v124, 0xbfb8aa3b, v124
	v_mul_f32_e32 v120, 0xbfb8aa3b, v120
	v_exp_f32_e32 v125, v125
	v_mul_f32_e32 v126, 0xbfb8aa3b, v126
	v_exp_f32_e32 v124, v124
	v_exp_f32_e32 v164, v120
	v_mul_f32_e32 v127, 0xbfb8aa3b, v127
	v_and_b32_e32 v162, 64, v154
	v_exp_f32_e32 v126, v126
	v_xor_b32_e32 v155, 16, v154
	v_exp_f32_e32 v127, v127
	v_add_u32_e32 v162, 64, v162
	v_mul_f32_e32 v121, 0xbfb8aa3b, v121
	v_cmp_lt_i32_e32 vcc, v155, v162
	v_add_f32_e32 v125, 1.0, v125
	v_mul_f32_e32 v122, 0xbfb8aa3b, v122
	v_exp_f32_e32 v121, v121
	v_cndmask_b32_e32 v120, v154, v155, vcc
	v_add_f32_e32 v124, 1.0, v124
	v_add_f32_e32 v155, 1.0, v164
	v_rcp_f32_e32 v125, v125
	v_mul_f32_e32 v123, 0xbfb8aa3b, v123
	v_exp_f32_e32 v122, v122
	v_add_f32_e32 v126, 1.0, v126
	v_rcp_f32_e32 v124, v124
	v_rcp_f32_e32 v155, v155
	v_exp_f32_e32 v123, v123
	v_add_f32_e32 v127, 1.0, v127
	v_rcp_f32_e32 v126, v126
	v_rcp_f32_e32 v127, v127
	v_add_f32_e32 v121, 1.0, v121
	v_add_f32_e32 v122, 1.0, v122
	v_rcp_f32_e32 v121, v121
	v_add_f32_e32 v123, 1.0, v123
	v_rcp_f32_e32 v122, v122
	v_rcp_f32_e32 v123, v123
	v_lshlrev_b32_e32 v120, 2, v120
	v_xor_b32_e32 v163, 32, v154
	v_cmp_lt_i32_e32 vcc, v163, v162
	s_lshl_b32 s36, s12, 2
	s_ashr_i32 s37, s36, 31
	s_waitcnt vmcnt(7)
	v_mov_b64_e32 v[156:157], v[176:177]
	v_mov_b64_e32 v[158:159], v[178:179]
	v_lshlrev_b32_e32 v164, 16, v156
	v_and_b32_e32 v156, 0xffff0000, v156
	v_lshlrev_b32_e32 v166, 16, v158
	v_fmac_f32_e32 v156, v117, v125
	v_lshlrev_b32_e32 v165, 16, v157
	v_fmac_f32_e32 v164, v116, v124
	v_fmac_f32_e32 v166, v112, v155
	v_mul_f32_e32 v112, v156, v156
	v_and_b32_e32 v157, 0xffff0000, v157
	v_fmac_f32_e32 v165, v118, v126
	v_fmac_f32_e32 v112, v164, v164
	v_fmac_f32_e32 v157, v119, v127
	v_fmac_f32_e32 v112, v165, v165
	v_and_b32_e32 v158, 0xffff0000, v158
	v_fmac_f32_e32 v112, v157, v157
	v_lshlrev_b32_e32 v167, 16, v159
	v_fmac_f32_e32 v158, v113, v121
	v_fmac_f32_e32 v112, v166, v166
	v_and_b32_e32 v159, 0xffff0000, v159
	v_fmac_f32_e32 v167, v114, v122
	v_fmac_f32_e32 v112, v158, v158
	v_fmac_f32_e32 v159, v115, v123
	v_fmac_f32_e32 v112, v167, v167
	v_fmac_f32_e32 v112, v159, v159
	ds_bpermute_b32 v113, v120, v112
	v_cndmask_b32_e32 v114, v154, v163, vcc
	v_lshlrev_b32_e32 v114, 2, v114
	v_lshl_add_u64 v[122:123], s[18:19], 0, v[160:161]
	v_cvt_pk_bf16_f32 v116, v164, v156
	s_waitcnt lgkmcnt(0)
	v_add_f32_e32 v112, v112, v113
	ds_bpermute_b32 v113, v114, v112
	v_cvt_pk_bf16_f32 v117, v165, v157
	v_cvt_pk_bf16_f32 v118, v166, v158
	v_cvt_pk_bf16_f32 v119, v167, v159
	global_store_dwordx4 v[122:123], v[116:119], off
	s_and_saveexec_b64 s[52:53], s[6:7]
	s_cbranch_execz .LBB0_957
	s_waitcnt lgkmcnt(0)
	v_add_f32_e32 v115, v112, v113
	v_lshlrev_b64 v[112:113], 8, v[146:147]
	v_lshl_add_u64 v[112:113], s[10:11], 0, v[112:113]
	v_lshl_add_u64 v[112:113], s[36:37], 2, v[112:113]
	s_lshl_b32 s12, s61, 2
	v_lshl_add_u64 v[112:113], v[112:113], 0, s[12:13]
	global_store_dword v[112:113], v115, off
.LBB0_957:
	s_or_b64 exec, exec, s[52:53]
	v_or_b32_e32 v112, 16, v146
	s_waitcnt lgkmcnt(0)
	v_ashrrev_i32_e32 v113, 31, v112
	v_lshlrev_b64 v[116:117], 11, v[112:113]
	v_lshl_add_u64 v[116:117], v[116:117], 0, v[144:145]
	v_lshlrev_b64 v[122:123], 1, v[116:117]
	v_lshl_add_u64 v[116:117], s[16:17], 0, v[122:123]
	v_mul_f32_e32 v109, 0xbfb8aa3b, v109
	v_mul_f32_e32 v108, 0xbfb8aa3b, v108
	v_mul_f32_e32 v100, 0xbfb8aa3b, v100
	v_exp_f32_e32 v109, v109
	v_mul_f32_e32 v110, 0xbfb8aa3b, v110
	v_exp_f32_e32 v108, v108
	v_exp_f32_e32 v100, v100
	v_mul_f32_e32 v111, 0xbfb8aa3b, v111
	v_exp_f32_e32 v110, v110
	v_exp_f32_e32 v111, v111
	v_mul_f32_e32 v101, 0xbfb8aa3b, v101
	v_add_f32_e32 v109, 1.0, v109
	v_mul_f32_e32 v102, 0xbfb8aa3b, v102
	v_exp_f32_e32 v101, v101
	v_add_f32_e32 v108, 1.0, v108
	v_add_f32_e32 v100, 1.0, v100
	v_rcp_f32_e32 v109, v109
	v_mul_f32_e32 v103, 0xbfb8aa3b, v103
	v_exp_f32_e32 v102, v102
	v_add_f32_e32 v110, 1.0, v110
	v_rcp_f32_e32 v108, v108
	v_rcp_f32_e32 v100, v100
	v_exp_f32_e32 v103, v103
	v_add_f32_e32 v111, 1.0, v111
	v_rcp_f32_e32 v110, v110
	v_rcp_f32_e32 v111, v111
	v_add_f32_e32 v101, 1.0, v101
	v_add_f32_e32 v102, 1.0, v102
	v_rcp_f32_e32 v101, v101
	v_add_f32_e32 v103, 1.0, v103
	v_rcp_f32_e32 v102, v102
	v_rcp_f32_e32 v103, v103
	s_waitcnt vmcnt(7)
	v_mov_b64_e32 v[116:117], v[180:181]
	v_mov_b64_e32 v[118:119], v[182:183]
	v_lshlrev_b32_e32 v115, 16, v116
	v_and_b32_e32 v116, 0xffff0000, v116
	v_lshlrev_b32_e32 v124, 16, v118
	v_fmac_f32_e32 v116, v105, v109
	v_lshlrev_b32_e32 v121, 16, v117
	v_fmac_f32_e32 v115, v104, v108
	v_fmac_f32_e32 v124, v96, v100
	v_mul_f32_e32 v96, v116, v116
	v_and_b32_e32 v117, 0xffff0000, v117
	v_fmac_f32_e32 v121, v106, v110
	v_fmac_f32_e32 v96, v115, v115
	v_fmac_f32_e32 v117, v107, v111
	v_fmac_f32_e32 v96, v121, v121
	v_and_b32_e32 v118, 0xffff0000, v118
	v_fmac_f32_e32 v96, v117, v117
	v_lshlrev_b32_e32 v125, 16, v119
	v_fmac_f32_e32 v118, v97, v101
	v_fmac_f32_e32 v96, v124, v124
	v_and_b32_e32 v119, 0xffff0000, v119
	v_fmac_f32_e32 v125, v98, v102
	v_fmac_f32_e32 v96, v118, v118
	v_fmac_f32_e32 v96, v125, v125
	v_fmac_f32_e32 v119, v99, v103
	v_fmac_f32_e32 v96, v119, v119
	ds_bpermute_b32 v97, v120, v96
	v_lshl_add_u64 v[102:103], s[18:19], 0, v[122:123]
	v_cvt_pk_bf16_f32 v98, v115, v116
	v_cvt_pk_bf16_f32 v99, v121, v117
	v_cvt_pk_bf16_f32 v100, v124, v118
	s_waitcnt lgkmcnt(0)
	v_add_f32_e32 v96, v96, v97
	ds_bpermute_b32 v97, v114, v96
	v_cvt_pk_bf16_f32 v101, v125, v119
	global_store_dwordx4 v[102:103], v[98:101], off
	s_and_saveexec_b64 s[52:53], s[6:7]
	s_cbranch_execz .LBB0_959
	s_waitcnt lgkmcnt(0)
	v_add_f32_e32 v98, v96, v97
	v_lshlrev_b64 v[96:97], 8, v[112:113]
	v_lshl_add_u64 v[96:97], s[10:11], 0, v[96:97]
	v_lshl_add_u64 v[96:97], s[36:37], 2, v[96:97]
	s_lshl_b32 s12, s61, 2
	v_lshl_add_u64 v[96:97], v[96:97], 0, s[12:13]
	global_store_dword v[96:97], v98, off
.LBB0_959:
	s_or_b64 exec, exec, s[52:53]
	v_or_b32_e32 v96, 32, v146
	s_waitcnt lgkmcnt(0)
	v_ashrrev_i32_e32 v97, 31, v96
	v_lshlrev_b64 v[98:99], 11, v[96:97]
	v_lshl_add_u64 v[98:99], v[98:99], 0, v[144:145]
	v_lshlrev_b64 v[102:103], 1, v[98:99]
	v_lshl_add_u64 v[98:99], s[16:17], 0, v[102:103]
	v_mul_f32_e32 v93, 0xbfb8aa3b, v93
	v_mul_f32_e32 v92, 0xbfb8aa3b, v92
	v_mul_f32_e32 v84, 0xbfb8aa3b, v84
	v_exp_f32_e32 v93, v93
	v_mul_f32_e32 v94, 0xbfb8aa3b, v94
	v_exp_f32_e32 v92, v92
	v_exp_f32_e32 v84, v84
	v_mul_f32_e32 v95, 0xbfb8aa3b, v95
	v_exp_f32_e32 v94, v94
	v_exp_f32_e32 v95, v95
	v_mul_f32_e32 v85, 0xbfb8aa3b, v85
	v_add_f32_e32 v93, 1.0, v93
	v_mul_f32_e32 v86, 0xbfb8aa3b, v86
	v_exp_f32_e32 v85, v85
	v_add_f32_e32 v92, 1.0, v92
	v_add_f32_e32 v84, 1.0, v84
	v_rcp_f32_e32 v93, v93
	v_mul_f32_e32 v87, 0xbfb8aa3b, v87
	v_exp_f32_e32 v86, v86
	v_add_f32_e32 v94, 1.0, v94
	v_rcp_f32_e32 v92, v92
	v_rcp_f32_e32 v84, v84
	v_exp_f32_e32 v87, v87
	v_add_f32_e32 v95, 1.0, v95
	v_rcp_f32_e32 v94, v94
	v_rcp_f32_e32 v95, v95
	v_add_f32_e32 v85, 1.0, v85
	v_add_f32_e32 v86, 1.0, v86
	v_rcp_f32_e32 v85, v85
	v_add_f32_e32 v87, 1.0, v87
	v_rcp_f32_e32 v86, v86
	v_rcp_f32_e32 v87, v87
	s_waitcnt vmcnt(7)
	v_mov_b64_e32 v[98:99], v[184:185]
	v_mov_b64_e32 v[100:101], v[186:187]
	v_lshlrev_b32_e32 v104, 16, v98
	v_and_b32_e32 v98, 0xffff0000, v98
	v_lshlrev_b32_e32 v106, 16, v100
	v_fmac_f32_e32 v98, v89, v93
	v_lshlrev_b32_e32 v105, 16, v99
	v_fmac_f32_e32 v104, v88, v92
	v_fmac_f32_e32 v106, v80, v84
	v_mul_f32_e32 v80, v98, v98
	v_and_b32_e32 v99, 0xffff0000, v99
	v_fmac_f32_e32 v105, v90, v94
	v_fmac_f32_e32 v80, v104, v104
	v_fmac_f32_e32 v99, v91, v95
	v_fmac_f32_e32 v80, v105, v105
	v_and_b32_e32 v100, 0xffff0000, v100
	v_fmac_f32_e32 v80, v99, v99
	v_lshlrev_b32_e32 v107, 16, v101
	v_fmac_f32_e32 v100, v81, v85
	v_fmac_f32_e32 v80, v106, v106
	v_and_b32_e32 v101, 0xffff0000, v101
	v_fmac_f32_e32 v107, v82, v86
	v_fmac_f32_e32 v80, v100, v100
	v_fmac_f32_e32 v80, v107, v107
	v_fmac_f32_e32 v101, v83, v87
	v_fmac_f32_e32 v80, v101, v101
	ds_bpermute_b32 v81, v120, v80
	v_lshl_add_u64 v[86:87], s[18:19], 0, v[102:103]
	v_cvt_pk_bf16_f32 v82, v104, v98
	v_cvt_pk_bf16_f32 v83, v105, v99
	v_cvt_pk_bf16_f32 v84, v106, v100
	s_waitcnt lgkmcnt(0)
	v_add_f32_e32 v80, v80, v81
	ds_bpermute_b32 v81, v114, v80
	v_cvt_pk_bf16_f32 v85, v107, v101
	global_store_dwordx4 v[86:87], v[82:85], off
	s_and_saveexec_b64 s[52:53], s[6:7]
	s_cbranch_execz .LBB0_961
	s_waitcnt lgkmcnt(0)
	v_add_f32_e32 v82, v80, v81
	v_lshlrev_b64 v[80:81], 8, v[96:97]
	v_lshl_add_u64 v[80:81], s[10:11], 0, v[80:81]
	v_lshl_add_u64 v[80:81], s[36:37], 2, v[80:81]
	s_lshl_b32 s12, s61, 2
	v_lshl_add_u64 v[80:81], v[80:81], 0, s[12:13]
	global_store_dword v[80:81], v82, off
.LBB0_961:
	s_or_b64 exec, exec, s[52:53]
	v_or_b32_e32 v80, 48, v146
	s_waitcnt lgkmcnt(0)
	v_ashrrev_i32_e32 v81, 31, v80
	v_lshlrev_b64 v[82:83], 11, v[80:81]
	v_lshl_add_u64 v[82:83], v[82:83], 0, v[144:145]
	v_lshlrev_b64 v[86:87], 1, v[82:83]
	v_lshl_add_u64 v[82:83], s[16:17], 0, v[86:87]
	v_mul_f32_e32 v77, 0xbfb8aa3b, v77
	v_mul_f32_e32 v76, 0xbfb8aa3b, v76
	v_mul_f32_e32 v68, 0xbfb8aa3b, v68
	v_exp_f32_e32 v77, v77
	v_mul_f32_e32 v78, 0xbfb8aa3b, v78
	v_exp_f32_e32 v76, v76
	v_exp_f32_e32 v68, v68
	v_mul_f32_e32 v79, 0xbfb8aa3b, v79
	v_exp_f32_e32 v78, v78
	v_exp_f32_e32 v79, v79
	v_mul_f32_e32 v69, 0xbfb8aa3b, v69
	v_add_f32_e32 v77, 1.0, v77
	v_mul_f32_e32 v70, 0xbfb8aa3b, v70
	v_exp_f32_e32 v69, v69
	v_add_f32_e32 v76, 1.0, v76
	v_add_f32_e32 v68, 1.0, v68
	v_rcp_f32_e32 v77, v77
	v_mul_f32_e32 v71, 0xbfb8aa3b, v71
	v_exp_f32_e32 v70, v70
	v_add_f32_e32 v78, 1.0, v78
	v_rcp_f32_e32 v76, v76
	v_rcp_f32_e32 v68, v68
	v_exp_f32_e32 v71, v71
	v_add_f32_e32 v79, 1.0, v79
	v_rcp_f32_e32 v78, v78
	v_rcp_f32_e32 v79, v79
	v_add_f32_e32 v69, 1.0, v69
	v_add_f32_e32 v70, 1.0, v70
	v_rcp_f32_e32 v69, v69
	v_add_f32_e32 v71, 1.0, v71
	v_rcp_f32_e32 v70, v70
	v_rcp_f32_e32 v71, v71
	s_waitcnt vmcnt(7)
	v_mov_b64_e32 v[82:83], v[188:189]
	v_mov_b64_e32 v[84:85], v[190:191]
	v_lshlrev_b32_e32 v88, 16, v82
	v_and_b32_e32 v82, 0xffff0000, v82
	v_lshlrev_b32_e32 v90, 16, v84
	v_fmac_f32_e32 v82, v73, v77
	v_lshlrev_b32_e32 v89, 16, v83
	v_fmac_f32_e32 v88, v72, v76
	v_fmac_f32_e32 v90, v64, v68
	v_mul_f32_e32 v64, v82, v82
	v_and_b32_e32 v83, 0xffff0000, v83
	v_fmac_f32_e32 v89, v74, v78
	v_fmac_f32_e32 v64, v88, v88
	v_fmac_f32_e32 v83, v75, v79
	v_fmac_f32_e32 v64, v89, v89
	v_and_b32_e32 v84, 0xffff0000, v84
	v_fmac_f32_e32 v64, v83, v83
	v_lshlrev_b32_e32 v91, 16, v85
	v_fmac_f32_e32 v84, v65, v69
	v_fmac_f32_e32 v64, v90, v90
	v_and_b32_e32 v85, 0xffff0000, v85
	v_fmac_f32_e32 v91, v66, v70
	v_fmac_f32_e32 v64, v84, v84
	v_fmac_f32_e32 v64, v91, v91
	v_fmac_f32_e32 v85, v67, v71
	v_fmac_f32_e32 v64, v85, v85
	ds_bpermute_b32 v65, v120, v64
	v_lshl_add_u64 v[70:71], s[18:19], 0, v[86:87]
	v_cvt_pk_bf16_f32 v66, v88, v82
	v_cvt_pk_bf16_f32 v67, v89, v83
	v_cvt_pk_bf16_f32 v68, v90, v84
	s_waitcnt lgkmcnt(0)
	v_add_f32_e32 v64, v64, v65
	ds_bpermute_b32 v65, v114, v64
	v_cvt_pk_bf16_f32 v69, v91, v85
	global_store_dwordx4 v[70:71], v[66:69], off
	s_and_saveexec_b64 s[52:53], s[6:7]
	s_cbranch_execz .LBB0_963
	s_waitcnt lgkmcnt(0)
	v_add_f32_e32 v66, v64, v65
	v_lshlrev_b64 v[64:65], 8, v[80:81]
	v_lshl_add_u64 v[64:65], s[10:11], 0, v[64:65]
	v_lshl_add_u64 v[64:65], s[36:37], 2, v[64:65]
	s_lshl_b32 s12, s61, 2
	v_lshl_add_u64 v[64:65], v[64:65], 0, s[12:13]
	global_store_dword v[64:65], v66, off
.LBB0_963:
	s_or_b64 exec, exec, s[52:53]
	v_add_u32_e32 v64, 0x80, v146
	s_waitcnt lgkmcnt(0)
	v_ashrrev_i32_e32 v65, 31, v64
	v_lshlrev_b64 v[66:67], 11, v[64:65]
	v_lshl_add_u64 v[66:67], v[66:67], 0, v[144:145]
	v_lshlrev_b64 v[70:71], 1, v[66:67]
	v_lshl_add_u64 v[66:67], s[16:17], 0, v[70:71]
	v_mul_f32_e32 v61, 0xbfb8aa3b, v61
	v_mul_f32_e32 v60, 0xbfb8aa3b, v60
	v_mul_f32_e32 v52, 0xbfb8aa3b, v52
	v_exp_f32_e32 v61, v61
	v_mul_f32_e32 v62, 0xbfb8aa3b, v62
	v_exp_f32_e32 v60, v60
	v_exp_f32_e32 v52, v52
	v_mul_f32_e32 v63, 0xbfb8aa3b, v63
	v_exp_f32_e32 v62, v62
	v_exp_f32_e32 v63, v63
	v_mul_f32_e32 v53, 0xbfb8aa3b, v53
	v_add_f32_e32 v61, 1.0, v61
	v_mul_f32_e32 v54, 0xbfb8aa3b, v54
	v_exp_f32_e32 v53, v53
	v_add_f32_e32 v60, 1.0, v60
	v_add_f32_e32 v52, 1.0, v52
	v_rcp_f32_e32 v61, v61
	v_mul_f32_e32 v55, 0xbfb8aa3b, v55
	v_exp_f32_e32 v54, v54
	v_add_f32_e32 v62, 1.0, v62
	v_rcp_f32_e32 v60, v60
	v_rcp_f32_e32 v52, v52
	v_exp_f32_e32 v55, v55
	v_add_f32_e32 v63, 1.0, v63
	v_rcp_f32_e32 v62, v62
	v_rcp_f32_e32 v63, v63
	v_add_f32_e32 v53, 1.0, v53
	v_add_f32_e32 v54, 1.0, v54
	v_rcp_f32_e32 v53, v53
	v_add_f32_e32 v55, 1.0, v55
	v_rcp_f32_e32 v54, v54
	v_rcp_f32_e32 v55, v55
	s_waitcnt vmcnt(7)
	v_mov_b64_e32 v[66:67], v[192:193]
	v_mov_b64_e32 v[68:69], v[194:195]
	v_lshlrev_b32_e32 v72, 16, v66
	v_and_b32_e32 v66, 0xffff0000, v66
	v_lshlrev_b32_e32 v74, 16, v68
	v_fmac_f32_e32 v66, v57, v61
	v_lshlrev_b32_e32 v73, 16, v67
	v_fmac_f32_e32 v72, v56, v60
	v_fmac_f32_e32 v74, v48, v52
	v_mul_f32_e32 v48, v66, v66
	v_and_b32_e32 v67, 0xffff0000, v67
	v_fmac_f32_e32 v73, v58, v62
	v_fmac_f32_e32 v48, v72, v72
	v_fmac_f32_e32 v67, v59, v63
	v_fmac_f32_e32 v48, v73, v73
	v_and_b32_e32 v68, 0xffff0000, v68
	v_fmac_f32_e32 v48, v67, v67
	v_lshlrev_b32_e32 v75, 16, v69
	v_fmac_f32_e32 v68, v49, v53
	v_fmac_f32_e32 v48, v74, v74
	v_and_b32_e32 v69, 0xffff0000, v69
	v_fmac_f32_e32 v75, v50, v54
	v_fmac_f32_e32 v48, v68, v68
	v_fmac_f32_e32 v48, v75, v75
	v_fmac_f32_e32 v69, v51, v55
	v_fmac_f32_e32 v48, v69, v69
	ds_bpermute_b32 v49, v120, v48
	v_lshl_add_u64 v[54:55], s[18:19], 0, v[70:71]
	v_cvt_pk_bf16_f32 v50, v72, v66
	v_cvt_pk_bf16_f32 v51, v73, v67
	v_cvt_pk_bf16_f32 v52, v74, v68
	s_waitcnt lgkmcnt(0)
	v_add_f32_e32 v48, v48, v49
	ds_bpermute_b32 v49, v114, v48
	v_cvt_pk_bf16_f32 v53, v75, v69
	global_store_dwordx4 v[54:55], v[50:53], off
	s_and_saveexec_b64 s[52:53], s[6:7]
	s_cbranch_execz .LBB0_965
	s_waitcnt lgkmcnt(0)
	v_add_f32_e32 v50, v48, v49
	v_lshlrev_b64 v[48:49], 8, v[64:65]
	v_lshl_add_u64 v[48:49], s[10:11], 0, v[48:49]
	v_lshl_add_u64 v[48:49], s[36:37], 2, v[48:49]
	s_lshl_b32 s12, s61, 2
	v_lshl_add_u64 v[48:49], v[48:49], 0, s[12:13]
	global_store_dword v[48:49], v50, off
.LBB0_965:
	s_or_b64 exec, exec, s[52:53]
	v_add_u32_e32 v48, 0x90, v146
	s_waitcnt lgkmcnt(0)
	v_ashrrev_i32_e32 v49, 31, v48
	v_lshlrev_b64 v[50:51], 11, v[48:49]
	v_lshl_add_u64 v[50:51], v[50:51], 0, v[144:145]
	v_lshlrev_b64 v[54:55], 1, v[50:51]
	v_lshl_add_u64 v[50:51], s[16:17], 0, v[54:55]
	v_mul_f32_e32 v45, 0xbfb8aa3b, v45
	v_mul_f32_e32 v44, 0xbfb8aa3b, v44
	v_mul_f32_e32 v36, 0xbfb8aa3b, v36
	v_exp_f32_e32 v45, v45
	v_mul_f32_e32 v46, 0xbfb8aa3b, v46
	v_exp_f32_e32 v44, v44
	v_exp_f32_e32 v36, v36
	v_mul_f32_e32 v47, 0xbfb8aa3b, v47
	v_exp_f32_e32 v46, v46
	v_exp_f32_e32 v47, v47
	v_mul_f32_e32 v37, 0xbfb8aa3b, v37
	v_add_f32_e32 v45, 1.0, v45
	v_mul_f32_e32 v38, 0xbfb8aa3b, v38
	v_exp_f32_e32 v37, v37
	v_add_f32_e32 v44, 1.0, v44
	v_add_f32_e32 v36, 1.0, v36
	v_rcp_f32_e32 v45, v45
	v_mul_f32_e32 v39, 0xbfb8aa3b, v39
	v_exp_f32_e32 v38, v38
	v_add_f32_e32 v46, 1.0, v46
	v_rcp_f32_e32 v44, v44
	v_rcp_f32_e32 v36, v36
	v_exp_f32_e32 v39, v39
	v_add_f32_e32 v47, 1.0, v47
	v_rcp_f32_e32 v46, v46
	v_rcp_f32_e32 v47, v47
	v_add_f32_e32 v37, 1.0, v37
	v_add_f32_e32 v38, 1.0, v38
	v_rcp_f32_e32 v37, v37
	v_add_f32_e32 v39, 1.0, v39
	v_rcp_f32_e32 v38, v38
	v_rcp_f32_e32 v39, v39
	s_waitcnt vmcnt(7)
	v_mov_b64_e32 v[50:51], v[196:197]
	v_mov_b64_e32 v[52:53], v[198:199]
	v_lshlrev_b32_e32 v56, 16, v50
	v_and_b32_e32 v50, 0xffff0000, v50
	v_lshlrev_b32_e32 v58, 16, v52
	v_fmac_f32_e32 v50, v41, v45
	v_lshlrev_b32_e32 v57, 16, v51
	v_fmac_f32_e32 v56, v40, v44
	v_fmac_f32_e32 v58, v32, v36
	v_mul_f32_e32 v32, v50, v50
	v_and_b32_e32 v51, 0xffff0000, v51
	v_fmac_f32_e32 v57, v42, v46
	v_fmac_f32_e32 v32, v56, v56
	v_fmac_f32_e32 v51, v43, v47
	v_fmac_f32_e32 v32, v57, v57
	v_and_b32_e32 v52, 0xffff0000, v52
	v_fmac_f32_e32 v32, v51, v51
	v_lshlrev_b32_e32 v59, 16, v53
	v_fmac_f32_e32 v52, v33, v37
	v_fmac_f32_e32 v32, v58, v58
	v_and_b32_e32 v53, 0xffff0000, v53
	v_fmac_f32_e32 v59, v34, v38
	v_fmac_f32_e32 v32, v52, v52
	v_fmac_f32_e32 v32, v59, v59
	v_fmac_f32_e32 v53, v35, v39
	v_fmac_f32_e32 v32, v53, v53
	ds_bpermute_b32 v33, v120, v32
	v_lshl_add_u64 v[38:39], s[18:19], 0, v[54:55]
	v_cvt_pk_bf16_f32 v34, v56, v50
	v_cvt_pk_bf16_f32 v35, v57, v51
	v_cvt_pk_bf16_f32 v36, v58, v52
	s_waitcnt lgkmcnt(0)
	v_add_f32_e32 v32, v32, v33
	ds_bpermute_b32 v33, v114, v32
	v_cvt_pk_bf16_f32 v37, v59, v53
	global_store_dwordx4 v[38:39], v[34:37], off
	s_and_saveexec_b64 s[52:53], s[6:7]
	s_cbranch_execz .LBB0_967
	s_waitcnt lgkmcnt(0)
	v_add_f32_e32 v34, v32, v33
	v_lshlrev_b64 v[32:33], 8, v[48:49]
	v_lshl_add_u64 v[32:33], s[10:11], 0, v[32:33]
	v_lshl_add_u64 v[32:33], s[36:37], 2, v[32:33]
	s_lshl_b32 s12, s61, 2
	v_lshl_add_u64 v[32:33], v[32:33], 0, s[12:13]
	global_store_dword v[32:33], v34, off
.LBB0_967:
	s_or_b64 exec, exec, s[52:53]
	v_add_u32_e32 v32, 0xa0, v146
	s_waitcnt lgkmcnt(0)
	v_ashrrev_i32_e32 v33, 31, v32
	v_lshlrev_b64 v[34:35], 11, v[32:33]
	v_lshl_add_u64 v[34:35], v[34:35], 0, v[144:145]
	v_lshlrev_b64 v[38:39], 1, v[34:35]
	v_lshl_add_u64 v[34:35], s[16:17], 0, v[38:39]
	v_mul_f32_e32 v29, 0xbfb8aa3b, v29
	v_mul_f32_e32 v28, 0xbfb8aa3b, v28
	v_mul_f32_e32 v20, 0xbfb8aa3b, v20
	v_exp_f32_e32 v29, v29
	v_mul_f32_e32 v30, 0xbfb8aa3b, v30
	v_exp_f32_e32 v28, v28
	v_exp_f32_e32 v20, v20
	v_mul_f32_e32 v31, 0xbfb8aa3b, v31
	v_exp_f32_e32 v30, v30
	v_exp_f32_e32 v31, v31
	v_mul_f32_e32 v21, 0xbfb8aa3b, v21
	v_add_f32_e32 v29, 1.0, v29
	v_mul_f32_e32 v22, 0xbfb8aa3b, v22
	v_exp_f32_e32 v21, v21
	v_add_f32_e32 v28, 1.0, v28
	v_add_f32_e32 v20, 1.0, v20
	v_rcp_f32_e32 v29, v29
	v_mul_f32_e32 v23, 0xbfb8aa3b, v23
	v_exp_f32_e32 v22, v22
	v_add_f32_e32 v30, 1.0, v30
	v_rcp_f32_e32 v28, v28
	v_rcp_f32_e32 v20, v20
	v_exp_f32_e32 v23, v23
	v_add_f32_e32 v31, 1.0, v31
	v_rcp_f32_e32 v30, v30
	v_rcp_f32_e32 v31, v31
	v_add_f32_e32 v21, 1.0, v21
	v_add_f32_e32 v22, 1.0, v22
	v_rcp_f32_e32 v21, v21
	v_add_f32_e32 v23, 1.0, v23
	v_rcp_f32_e32 v22, v22
	v_rcp_f32_e32 v23, v23
	s_waitcnt vmcnt(7)
	v_mov_b64_e32 v[34:35], v[200:201]
	v_mov_b64_e32 v[36:37], v[202:203]
	v_lshlrev_b32_e32 v40, 16, v34
	v_and_b32_e32 v34, 0xffff0000, v34
	v_lshlrev_b32_e32 v42, 16, v36
	v_fmac_f32_e32 v34, v25, v29
	v_lshlrev_b32_e32 v41, 16, v35
	v_fmac_f32_e32 v40, v24, v28
	v_fmac_f32_e32 v42, v16, v20
	v_mul_f32_e32 v16, v34, v34
	v_and_b32_e32 v35, 0xffff0000, v35
	v_fmac_f32_e32 v41, v26, v30
	v_fmac_f32_e32 v16, v40, v40
	v_fmac_f32_e32 v35, v27, v31
	v_fmac_f32_e32 v16, v41, v41
	v_and_b32_e32 v36, 0xffff0000, v36
	v_fmac_f32_e32 v16, v35, v35
	v_lshlrev_b32_e32 v43, 16, v37
	v_fmac_f32_e32 v36, v17, v21
	v_fmac_f32_e32 v16, v42, v42
	v_and_b32_e32 v37, 0xffff0000, v37
	v_fmac_f32_e32 v43, v18, v22
	v_fmac_f32_e32 v16, v36, v36
	v_fmac_f32_e32 v16, v43, v43
	v_fmac_f32_e32 v37, v19, v23
	v_fmac_f32_e32 v16, v37, v37
	ds_bpermute_b32 v17, v120, v16
	v_lshl_add_u64 v[22:23], s[18:19], 0, v[38:39]
	v_cvt_pk_bf16_f32 v18, v40, v34
	v_cvt_pk_bf16_f32 v19, v41, v35
	v_cvt_pk_bf16_f32 v20, v42, v36
	s_waitcnt lgkmcnt(0)
	v_add_f32_e32 v16, v16, v17
	ds_bpermute_b32 v17, v114, v16
	v_cvt_pk_bf16_f32 v21, v43, v37
	global_store_dwordx4 v[22:23], v[18:21], off
	s_and_saveexec_b64 s[52:53], s[6:7]
	s_cbranch_execz .LBB0_969
	s_waitcnt lgkmcnt(0)
	v_add_f32_e32 v18, v16, v17
	v_lshlrev_b64 v[16:17], 8, v[32:33]
	v_lshl_add_u64 v[16:17], s[10:11], 0, v[16:17]
	v_lshl_add_u64 v[16:17], s[36:37], 2, v[16:17]
	s_lshl_b32 s12, s61, 2
	v_lshl_add_u64 v[16:17], v[16:17], 0, s[12:13]
	global_store_dword v[16:17], v18, off
.LBB0_969:
	s_or_b64 exec, exec, s[52:53]
	v_add_u32_e32 v16, 0xb0, v146
	s_waitcnt lgkmcnt(0)
	v_ashrrev_i32_e32 v17, 31, v16
	v_lshlrev_b64 v[18:19], 11, v[16:17]
	v_lshl_add_u64 v[18:19], v[18:19], 0, v[144:145]
	v_lshlrev_b64 v[22:23], 1, v[18:19]
	v_lshl_add_u64 v[18:19], s[16:17], 0, v[22:23]
	v_mul_f32_e32 v13, 0xbfb8aa3b, v13
	v_mul_f32_e32 v12, 0xbfb8aa3b, v12
	v_mul_f32_e32 v4, 0xbfb8aa3b, v4
	v_exp_f32_e32 v13, v13
	v_mul_f32_e32 v14, 0xbfb8aa3b, v14
	v_exp_f32_e32 v12, v12
	v_exp_f32_e32 v4, v4
	v_mul_f32_e32 v15, 0xbfb8aa3b, v15
	v_exp_f32_e32 v14, v14
	v_exp_f32_e32 v15, v15
	v_mul_f32_e32 v5, 0xbfb8aa3b, v5
	v_add_f32_e32 v13, 1.0, v13
	v_mul_f32_e32 v6, 0xbfb8aa3b, v6
	v_exp_f32_e32 v5, v5
	v_add_f32_e32 v12, 1.0, v12
	v_add_f32_e32 v4, 1.0, v4
	v_rcp_f32_e32 v13, v13
	v_mul_f32_e32 v7, 0xbfb8aa3b, v7
	v_exp_f32_e32 v6, v6
	v_add_f32_e32 v14, 1.0, v14
	v_rcp_f32_e32 v12, v12
	v_rcp_f32_e32 v4, v4
	v_exp_f32_e32 v7, v7
	v_add_f32_e32 v15, 1.0, v15
	v_rcp_f32_e32 v14, v14
	v_rcp_f32_e32 v15, v15
	v_add_f32_e32 v5, 1.0, v5
	v_add_f32_e32 v6, 1.0, v6
	v_rcp_f32_e32 v5, v5
	v_add_f32_e32 v7, 1.0, v7
	v_rcp_f32_e32 v6, v6
	v_rcp_f32_e32 v7, v7
	s_waitcnt vmcnt(7)
	v_mov_b64_e32 v[18:19], v[204:205]
	v_mov_b64_e32 v[20:21], v[206:207]
	v_lshlrev_b32_e32 v24, 16, v18
	v_and_b32_e32 v18, 0xffff0000, v18
	v_lshlrev_b32_e32 v26, 16, v20
	v_fmac_f32_e32 v18, v9, v13
	v_lshlrev_b32_e32 v25, 16, v19
	v_fmac_f32_e32 v24, v8, v12
	v_fmac_f32_e32 v26, v0, v4
	v_mul_f32_e32 v0, v18, v18
	v_and_b32_e32 v19, 0xffff0000, v19
	v_fmac_f32_e32 v25, v10, v14
	v_fmac_f32_e32 v0, v24, v24
	v_fmac_f32_e32 v19, v11, v15
	v_fmac_f32_e32 v0, v25, v25
	v_and_b32_e32 v20, 0xffff0000, v20
	v_fmac_f32_e32 v0, v19, v19
	v_lshlrev_b32_e32 v27, 16, v21
	v_fmac_f32_e32 v20, v1, v5
	v_fmac_f32_e32 v0, v26, v26
	v_and_b32_e32 v21, 0xffff0000, v21
	v_fmac_f32_e32 v27, v2, v6
	v_fmac_f32_e32 v0, v20, v20
	v_fmac_f32_e32 v0, v27, v27
	v_fmac_f32_e32 v21, v3, v7
	v_fmac_f32_e32 v0, v21, v21
	ds_bpermute_b32 v1, v120, v0
	v_lshl_add_u64 v[6:7], s[18:19], 0, v[22:23]
	v_cvt_pk_bf16_f32 v2, v24, v18
	v_cvt_pk_bf16_f32 v3, v25, v19
	v_cvt_pk_bf16_f32 v4, v26, v20
	s_waitcnt lgkmcnt(0)
	v_add_f32_e32 v0, v0, v1
	ds_bpermute_b32 v1, v114, v0
	v_cvt_pk_bf16_f32 v5, v27, v21
	global_store_dwordx4 v[6:7], v[2:5], off
	s_and_saveexec_b64 s[52:53], s[6:7]
	s_cbranch_execz .LBB0_971
	s_waitcnt lgkmcnt(0)
	v_add_f32_e32 v2, v0, v1
	v_lshlrev_b64 v[0:1], 8, v[16:17]
	v_lshl_add_u64 v[0:1], s[10:11], 0, v[0:1]
	v_lshl_add_u64 v[0:1], s[36:37], 2, v[0:1]
	s_lshl_b32 s12, s61, 2
	v_lshl_add_u64 v[0:1], v[0:1], 0, s[12:13]
	global_store_dword v[0:1], v2, off

.LBB0_1137:
	ds_read_b128 v[144:147], v151
	ds_read_b128 v[156:159], v151 offset:1024
	ds_read_b128 v[160:163], v151 offset:2048
	ds_read_b128 v[164:167], v151 offset:3072
	ds_read_b128 v[168:171], v152
	ds_read_b128 v[172:175], v152 offset:1024
	ds_read_b128 v[176:179], v152 offset:2048
	ds_read_b128 v[180:183], v152 offset:3072
	s_add_u32 s34, s30, 0x100
	s_addc_u32 s35, s31, 0
	s_cmpk_eq_i32 s66, 0x54
	s_cselect_b32 s49, s11, s35
	s_cselect_b32 s48, s10, s34
	s_cselect_b32 s37, s27, s47
	s_cselect_b32 s36, s26, s46
	v_lshl_add_u64 v[216:217], s[30:31], 0, v[138:139]
	s_add_i32 m0, s53, 0xc000
	ds_read_b128 v[184:187], v153
	ds_read_b128 v[188:191], v153 offset:1024
	ds_read_b128 v[192:195], v153 offset:2048
	ds_read_b128 v[196:199], v153 offset:3072
	ds_read_b128 v[200:203], v153 offset:4096
	ds_read_b128 v[204:207], v153 offset:5120
	ds_read_b128 v[208:211], v153 offset:6144
	ds_read_b128 v[212:215], v153 offset:7168
	global_load_lds_dwordx4 v[216:217], off
	v_lshl_add_u64 v[216:217], s[30:31], 0, v[136:137]
	s_add_i32 m0, s53, 0xe000
	s_nop 0
	global_load_lds_dwordx4 v[216:217], off
	s_waitcnt vmcnt(8)
	s_waitcnt lgkmcnt(0)
	s_barrier
	s_setprio 1
	s_waitcnt lgkmcnt(0)
	v_mfma_f32_16x16x32_bf16 v[124:127], v[144:147], v[184:187], v[124:127]
	v_mfma_f32_16x16x32_bf16 v[120:123], v[160:163], v[184:187], v[120:123]
	v_mfma_f32_16x16x32_bf16 v[108:111], v[144:147], v[192:195], v[108:111]
	v_mfma_f32_16x16x32_bf16 v[104:107], v[160:163], v[192:195], v[104:107]
	v_mfma_f32_16x16x32_bf16 v[92:95], v[144:147], v[200:203], v[92:95]
	v_mfma_f32_16x16x32_bf16 v[88:91], v[160:163], v[200:203], v[88:91]
	v_mfma_f32_16x16x32_bf16 v[76:79], v[144:147], v[208:211], v[76:79]
	v_mfma_f32_16x16x32_bf16 v[72:75], v[160:163], v[208:211], v[72:75]
	v_mfma_f32_16x16x32_bf16 v[124:127], v[156:159], v[188:191], v[124:127]
	v_mfma_f32_16x16x32_bf16 v[120:123], v[164:167], v[188:191], v[120:123]
	v_mfma_f32_16x16x32_bf16 v[108:111], v[156:159], v[196:199], v[108:111]
	v_mfma_f32_16x16x32_bf16 v[104:107], v[164:167], v[196:199], v[104:107]
	v_mfma_f32_16x16x32_bf16 v[92:95], v[156:159], v[204:207], v[92:95]
	v_mfma_f32_16x16x32_bf16 v[88:91], v[164:167], v[204:207], v[88:91]
	v_mfma_f32_16x16x32_bf16 v[76:79], v[156:159], v[212:215], v[76:79]
	v_mfma_f32_16x16x32_bf16 v[72:75], v[164:167], v[212:215], v[72:75]
	s_setprio 0
	s_setprio 1
	v_mfma_f32_16x16x32_bf16 v[116:119], v[168:171], v[184:187], v[116:119]
	v_mfma_f32_16x16x32_bf16 v[112:115], v[176:179], v[184:187], v[112:115]
	v_mfma_f32_16x16x32_bf16 v[100:103], v[168:171], v[192:195], v[100:103]
	v_mfma_f32_16x16x32_bf16 v[96:99], v[176:179], v[192:195], v[96:99]
	v_mfma_f32_16x16x32_bf16 v[84:87], v[168:171], v[200:203], v[84:87]
	v_mfma_f32_16x16x32_bf16 v[80:83], v[176:179], v[200:203], v[80:83]
	v_mfma_f32_16x16x32_bf16 v[68:71], v[168:171], v[208:211], v[68:71]
	v_mfma_f32_16x16x32_bf16 v[64:67], v[176:179], v[208:211], v[64:67]
	v_mfma_f32_16x16x32_bf16 v[116:119], v[172:175], v[188:191], v[116:119]
	v_mfma_f32_16x16x32_bf16 v[112:115], v[180:183], v[188:191], v[112:115]
	v_mfma_f32_16x16x32_bf16 v[100:103], v[172:175], v[196:199], v[100:103]
	v_mfma_f32_16x16x32_bf16 v[96:99], v[180:183], v[196:199], v[96:99]
	v_mfma_f32_16x16x32_bf16 v[84:87], v[172:175], v[204:207], v[84:87]
	v_mfma_f32_16x16x32_bf16 v[80:83], v[180:183], v[204:207], v[80:83]
	v_mfma_f32_16x16x32_bf16 v[68:71], v[172:175], v[212:215], v[68:71]
	v_mfma_f32_16x16x32_bf16 v[64:67], v[180:183], v[212:215], v[64:67]
	s_setprio 0
	s_barrier
	s_add_i32 s30, s60, s52
	v_lshl_add_u64 v[216:217], s[36:37], 0, v[130:131]
	s_mov_b32 m0, s30
	ds_read_b128 v[184:187], v153 offset:16384
	ds_read_b128 v[188:191], v153 offset:17408
	ds_read_b128 v[192:195], v153 offset:18432
	ds_read_b128 v[196:199], v153 offset:19456
	ds_read_b128 v[200:203], v153 offset:20480
	ds_read_b128 v[204:207], v153 offset:21504
	ds_read_b128 v[208:211], v153 offset:22528
	ds_read_b128 v[212:215], v153 offset:23552
	global_load_lds_dwordx4 v[216:217], off
	s_add_i32 m0, s30, 0x2000
	s_add_u32 s30, s36, 0x160000
	v_lshl_add_u64 v[218:219], s[36:37], 0, v[134:135]
	s_addc_u32 s31, s37, 0
	s_add_i32 s67, s61, s52
	global_load_lds_dwordx4 v[218:219], off
	v_lshl_add_u64 v[220:221], s[30:31], 0, v[130:131]
	s_mov_b32 m0, s67
	v_lshl_add_u64 v[222:223], s[48:49], 0, v[132:133]
	global_load_lds_dwordx4 v[220:221], off
	v_lshl_add_u64 v[220:221], s[30:31], 0, v[134:135]
	s_add_i32 m0, s67, 0x2000
	s_nop 0
	global_load_lds_dwordx4 v[220:221], off
	v_lshl_add_u64 v[220:221], s[48:49], 0, v[128:129]
	s_mov_b32 m0, s53
	s_nop 0
	global_load_lds_dwordx4 v[220:221], off
	s_mov_b32 m0, s54
	s_nop 0
	global_load_lds_dwordx4 v[222:223], off
	s_waitcnt vmcnt(8)
	s_waitcnt lgkmcnt(0)
	s_barrier
	s_setprio 1
	s_waitcnt lgkmcnt(0)
	v_mfma_f32_16x16x32_bf16 v[60:63], v[144:147], v[184:187], v[60:63]
	v_mfma_f32_16x16x32_bf16 v[56:59], v[160:163], v[184:187], v[56:59]
	v_mfma_f32_16x16x32_bf16 v[44:47], v[144:147], v[192:195], v[44:47]
	v_mfma_f32_16x16x32_bf16 v[40:43], v[160:163], v[192:195], v[40:43]
	v_mfma_f32_16x16x32_bf16 v[28:31], v[144:147], v[200:203], v[28:31]
	v_mfma_f32_16x16x32_bf16 v[24:27], v[160:163], v[200:203], v[24:27]
	v_mfma_f32_16x16x32_bf16 v[12:15], v[144:147], v[208:211], v[12:15]
	v_mfma_f32_16x16x32_bf16 v[8:11], v[160:163], v[208:211], v[8:11]
	v_mfma_f32_16x16x32_bf16 v[60:63], v[156:159], v[188:191], v[60:63]
	v_mfma_f32_16x16x32_bf16 v[56:59], v[164:167], v[188:191], v[56:59]
	v_mfma_f32_16x16x32_bf16 v[44:47], v[156:159], v[196:199], v[44:47]
	v_mfma_f32_16x16x32_bf16 v[40:43], v[164:167], v[196:199], v[40:43]
	v_mfma_f32_16x16x32_bf16 v[28:31], v[156:159], v[204:207], v[28:31]
	v_mfma_f32_16x16x32_bf16 v[24:27], v[164:167], v[204:207], v[24:27]
	v_mfma_f32_16x16x32_bf16 v[12:15], v[156:159], v[212:215], v[12:15]
	v_mfma_f32_16x16x32_bf16 v[8:11], v[164:167], v[212:215], v[8:11]
	s_setprio 0
	s_setprio 1
	v_mfma_f32_16x16x32_bf16 v[52:55], v[168:171], v[184:187], v[52:55]
	v_mfma_f32_16x16x32_bf16 v[48:51], v[176:179], v[184:187], v[48:51]
	v_mfma_f32_16x16x32_bf16 v[36:39], v[168:171], v[192:195], v[36:39]
	v_mfma_f32_16x16x32_bf16 v[32:35], v[176:179], v[192:195], v[32:35]
	v_mfma_f32_16x16x32_bf16 v[20:23], v[168:171], v[200:203], v[20:23]
	v_mfma_f32_16x16x32_bf16 v[16:19], v[176:179], v[200:203], v[16:19]
	v_mfma_f32_16x16x32_bf16 v[4:7], v[168:171], v[208:211], v[4:7]
	v_mfma_f32_16x16x32_bf16 v[0:3], v[176:179], v[208:211], v[0:3]
	v_mfma_f32_16x16x32_bf16 v[52:55], v[172:175], v[188:191], v[52:55]
	v_mfma_f32_16x16x32_bf16 v[48:51], v[180:183], v[188:191], v[48:51]
	v_mfma_f32_16x16x32_bf16 v[36:39], v[172:175], v[196:199], v[36:39]
	v_mfma_f32_16x16x32_bf16 v[32:35], v[180:183], v[196:199], v[32:35]
	v_mfma_f32_16x16x32_bf16 v[20:23], v[172:175], v[204:207], v[20:23]
	v_mfma_f32_16x16x32_bf16 v[16:19], v[180:183], v[204:207], v[16:19]
	v_mfma_f32_16x16x32_bf16 v[4:7], v[172:175], v[212:215], v[4:7]
	v_mfma_f32_16x16x32_bf16 v[0:3], v[180:183], v[212:215], v[0:3]
	s_setprio 0
	s_barrier
	s_add_i32 s67, 0, 0x18000
	v_add_u32_e32 v155, s67, v149
	s_add_i32 s68, 0, 0x1c000
	ds_read_b128 v[144:147], v155
	ds_read_b128 v[156:159], v155 offset:1024
	ds_read_b128 v[160:163], v155 offset:2048
	ds_read_b128 v[164:167], v155 offset:3072
	v_add_u32_e32 v155, s68, v149
	ds_read_b128 v[168:171], v155
	ds_read_b128 v[172:175], v155 offset:1024
	ds_read_b128 v[176:179], v155 offset:2048
	ds_read_b128 v[180:183], v155 offset:3072
	s_add_u32 s30, s48, 0x160000
	s_addc_u32 s31, s49, 0
	s_mov_b32 m0, s55
	v_lshl_add_u64 v[224:225], s[30:31], 0, v[128:129]
	ds_read_b128 v[184:187], v153 offset:32768
	ds_read_b128 v[188:191], v153 offset:33792
	ds_read_b128 v[192:195], v153 offset:34816
	ds_read_b128 v[196:199], v153 offset:35840
	ds_read_b128 v[200:203], v153 offset:36864
	ds_read_b128 v[204:207], v153 offset:37888
	ds_read_b128 v[208:211], v153 offset:38912
	ds_read_b128 v[212:215], v153 offset:39936
	global_load_lds_dwordx4 v[224:225], off
	v_lshl_add_u64 v[224:225], s[30:31], 0, v[132:133]
	s_mov_b32 m0, s56
	s_nop 0
	global_load_lds_dwordx4 v[224:225], off
	s_waitcnt vmcnt(8)
	s_waitcnt lgkmcnt(0)
	s_barrier
	s_setprio 1
	s_waitcnt lgkmcnt(0)
	v_mfma_f32_16x16x32_bf16 v[124:127], v[144:147], v[184:187], v[124:127]
	v_mfma_f32_16x16x32_bf16 v[120:123], v[160:163], v[184:187], v[120:123]
	v_mfma_f32_16x16x32_bf16 v[108:111], v[144:147], v[192:195], v[108:111]
	v_mfma_f32_16x16x32_bf16 v[104:107], v[160:163], v[192:195], v[104:107]
	v_mfma_f32_16x16x32_bf16 v[92:95], v[144:147], v[200:203], v[92:95]
	v_mfma_f32_16x16x32_bf16 v[88:91], v[160:163], v[200:203], v[88:91]
	v_mfma_f32_16x16x32_bf16 v[76:79], v[144:147], v[208:211], v[76:79]
	v_mfma_f32_16x16x32_bf16 v[72:75], v[160:163], v[208:211], v[72:75]
	v_mfma_f32_16x16x32_bf16 v[124:127], v[156:159], v[188:191], v[124:127]
	v_mfma_f32_16x16x32_bf16 v[120:123], v[164:167], v[188:191], v[120:123]
	v_mfma_f32_16x16x32_bf16 v[108:111], v[156:159], v[196:199], v[108:111]
	v_mfma_f32_16x16x32_bf16 v[104:107], v[164:167], v[196:199], v[104:107]
	v_mfma_f32_16x16x32_bf16 v[92:95], v[156:159], v[204:207], v[92:95]
	v_mfma_f32_16x16x32_bf16 v[88:91], v[164:167], v[204:207], v[88:91]
	v_mfma_f32_16x16x32_bf16 v[76:79], v[156:159], v[212:215], v[76:79]
	v_mfma_f32_16x16x32_bf16 v[72:75], v[164:167], v[212:215], v[72:75]
	s_setprio 0
	s_setprio 1
	v_mfma_f32_16x16x32_bf16 v[116:119], v[168:171], v[184:187], v[116:119]
	v_mfma_f32_16x16x32_bf16 v[112:115], v[176:179], v[184:187], v[112:115]
	v_mfma_f32_16x16x32_bf16 v[100:103], v[168:171], v[192:195], v[100:103]
	v_mfma_f32_16x16x32_bf16 v[96:99], v[176:179], v[192:195], v[96:99]
	v_mfma_f32_16x16x32_bf16 v[84:87], v[168:171], v[200:203], v[84:87]
	v_mfma_f32_16x16x32_bf16 v[80:83], v[176:179], v[200:203], v[80:83]
	v_mfma_f32_16x16x32_bf16 v[68:71], v[168:171], v[208:211], v[68:71]
	v_mfma_f32_16x16x32_bf16 v[64:67], v[176:179], v[208:211], v[64:67]
	v_mfma_f32_16x16x32_bf16 v[116:119], v[172:175], v[188:191], v[116:119]
	v_mfma_f32_16x16x32_bf16 v[112:115], v[180:183], v[188:191], v[112:115]
	v_mfma_f32_16x16x32_bf16 v[100:103], v[172:175], v[196:199], v[100:103]
	v_mfma_f32_16x16x32_bf16 v[96:99], v[180:183], v[196:199], v[96:99]
	v_mfma_f32_16x16x32_bf16 v[84:87], v[172:175], v[204:207], v[84:87]
	v_mfma_f32_16x16x32_bf16 v[80:83], v[180:183], v[204:207], v[80:83]
	v_mfma_f32_16x16x32_bf16 v[68:71], v[172:175], v[212:215], v[68:71]
	v_mfma_f32_16x16x32_bf16 v[64:67], v[180:183], v[212:215], v[64:67]
	s_setprio 0
	s_barrier
	s_add_i32 s30, s67, s52
	v_lshl_add_u64 v[216:217], v[216:217], 0, s[22:23]
	s_mov_b32 m0, s30
	ds_read_b128 v[184:187], v153 offset:49152
	ds_read_b128 v[188:191], v153 offset:50176
	ds_read_b128 v[192:195], v153 offset:51200
	ds_read_b128 v[196:199], v153 offset:52224
	ds_read_b128 v[200:203], v153 offset:53248
	ds_read_b128 v[204:207], v153 offset:54272
	ds_read_b128 v[208:211], v153 offset:55296
	ds_read_b128 v[212:215], v153 offset:56320
	global_load_lds_dwordx4 v[216:217], off
	s_add_i32 m0, s30, 0x2000
	s_add_u32 s30, s36, 0x160080
	v_lshl_add_u64 v[216:217], v[218:219], 0, s[22:23]
	s_addc_u32 s31, s37, 0
	s_add_i32 s36, s68, s52
	global_load_lds_dwordx4 v[216:217], off
	v_lshl_add_u64 v[216:217], s[30:31], 0, v[130:131]
	s_mov_b32 m0, s36
	s_nop 0
	global_load_lds_dwordx4 v[216:217], off
	v_lshl_add_u64 v[216:217], s[30:31], 0, v[134:135]
	s_add_i32 m0, s36, 0x2000
	s_nop 0
	global_load_lds_dwordx4 v[216:217], off
	v_lshl_add_u64 v[216:217], v[220:221], 0, s[22:23]
	s_mov_b32 m0, s58
	s_nop 0
	global_load_lds_dwordx4 v[216:217], off
	v_lshl_add_u64 v[216:217], v[222:223], 0, s[22:23]
	s_mov_b32 m0, s59
	s_nop 0
	global_load_lds_dwordx4 v[216:217], off
	s_waitcnt vmcnt(8)
	s_waitcnt lgkmcnt(0)
	s_barrier
	s_setprio 1
	s_waitcnt lgkmcnt(0)
	v_mfma_f32_16x16x32_bf16 v[60:63], v[144:147], v[184:187], v[60:63]
	v_mfma_f32_16x16x32_bf16 v[56:59], v[160:163], v[184:187], v[56:59]
	v_mfma_f32_16x16x32_bf16 v[44:47], v[144:147], v[192:195], v[44:47]
	v_mfma_f32_16x16x32_bf16 v[40:43], v[160:163], v[192:195], v[40:43]
	v_mfma_f32_16x16x32_bf16 v[28:31], v[144:147], v[200:203], v[28:31]
	v_mfma_f32_16x16x32_bf16 v[24:27], v[160:163], v[200:203], v[24:27]
	v_mfma_f32_16x16x32_bf16 v[12:15], v[144:147], v[208:211], v[12:15]
	v_mfma_f32_16x16x32_bf16 v[8:11], v[160:163], v[208:211], v[8:11]
	v_mfma_f32_16x16x32_bf16 v[60:63], v[156:159], v[188:191], v[60:63]
	v_mfma_f32_16x16x32_bf16 v[56:59], v[164:167], v[188:191], v[56:59]
	v_mfma_f32_16x16x32_bf16 v[44:47], v[156:159], v[196:199], v[44:47]
	v_mfma_f32_16x16x32_bf16 v[40:43], v[164:167], v[196:199], v[40:43]
	v_mfma_f32_16x16x32_bf16 v[28:31], v[156:159], v[204:207], v[28:31]
	v_mfma_f32_16x16x32_bf16 v[24:27], v[164:167], v[204:207], v[24:27]
	v_mfma_f32_16x16x32_bf16 v[12:15], v[156:159], v[212:215], v[12:15]
	v_mfma_f32_16x16x32_bf16 v[8:11], v[164:167], v[212:215], v[8:11]
	s_setprio 0
	s_setprio 1
	v_mfma_f32_16x16x32_bf16 v[52:55], v[168:171], v[184:187], v[52:55]
	v_mfma_f32_16x16x32_bf16 v[48:51], v[176:179], v[184:187], v[48:51]
	v_mfma_f32_16x16x32_bf16 v[36:39], v[168:171], v[192:195], v[36:39]
	v_mfma_f32_16x16x32_bf16 v[32:35], v[176:179], v[192:195], v[32:35]
	v_mfma_f32_16x16x32_bf16 v[20:23], v[168:171], v[200:203], v[20:23]
	v_mfma_f32_16x16x32_bf16 v[16:19], v[176:179], v[200:203], v[16:19]
	v_mfma_f32_16x16x32_bf16 v[4:7], v[168:171], v[208:211], v[4:7]
	v_mfma_f32_16x16x32_bf16 v[0:3], v[176:179], v[208:211], v[0:3]
	v_mfma_f32_16x16x32_bf16 v[52:55], v[172:175], v[188:191], v[52:55]
	v_mfma_f32_16x16x32_bf16 v[48:51], v[180:183], v[188:191], v[48:51]
	v_mfma_f32_16x16x32_bf16 v[36:39], v[172:175], v[196:199], v[36:39]
	v_mfma_f32_16x16x32_bf16 v[32:35], v[180:183], v[196:199], v[32:35]
	v_mfma_f32_16x16x32_bf16 v[20:23], v[172:175], v[204:207], v[20:23]
	v_mfma_f32_16x16x32_bf16 v[16:19], v[180:183], v[204:207], v[16:19]
	v_mfma_f32_16x16x32_bf16 v[4:7], v[172:175], v[212:215], v[4:7]
	v_mfma_f32_16x16x32_bf16 v[0:3], v[180:183], v[212:215], v[0:3]
	s_setprio 0
	s_barrier
	s_add_i32 s66, s66, 2
	s_add_u32 s46, s46, 0x100
	s_addc_u32 s47, s47, 0
	s_cmpk_gt_u32 s66, 0x55
	s_mov_b64 s[30:31], s[34:35]
	s_cbranch_scc0 .LBB0_1137
	v_lshl_add_u32 v172, s65, 8, v148
	v_mov_b32_e32 v175, 0
	v_lshl_or_b32 v178, s12, 8, v150
	v_lshlrev_b32_e32 v178, 1, v178
	v_lshl_add_u32 v178, v172, 12, v178
	v_mov_b32_e32 v179, v178
	global_load_dwordx4 v[180:183], v179, s[18:19]
	global_load_dwordx4 v[184:187], v179, s[18:19] offset:256
	v_add_u32_e32 v179, 0x10000, v178
	global_load_dwordx4 v[188:191], v179, s[18:19]
	global_load_dwordx4 v[192:195], v179, s[18:19] offset:256
	v_add_u32_e32 v179, 0x20000, v178
	global_load_dwordx4 v[196:199], v179, s[18:19]
	global_load_dwordx4 v[200:203], v179, s[18:19] offset:256
	v_add_u32_e32 v179, 0x30000, v178
	global_load_dwordx4 v[204:207], v179, s[18:19]
	global_load_dwordx4 v[208:211], v179, s[18:19] offset:256
	v_add_u32_e32 v179, 0x80000, v178
	global_load_dwordx4 v[212:215], v179, s[18:19]
	s_and_b64 vcc, exec, s[24:25]
	s_cbranch_vccz .LBB0_1140
	s_barrier
.LBB0_1140:
	v_lshl_add_u32 v146, s65, 8, v148
	v_lshl_or_b32 v144, s12, 8, v150
	v_ashrrev_i32_e32 v147, 31, v146
	v_ashrrev_i32_e32 v145, 31, v144
	v_lshlrev_b64 v[156:157], 11, v[146:147]
	v_lshl_add_u64 v[156:157], v[156:157], 0, v[144:145]
	v_lshlrev_b64 v[160:161], 1, v[156:157]
	v_lshl_add_u64 v[156:157], s[18:19], 0, v[160:161]
	v_lshl_add_u64 v[162:163], s[16:17], 0, v[160:161]
	v_or_b32_e32 v160, 0x100, v160
	v_lshl_add_u64 v[164:165], s[18:19], 0, v[160:161]
	v_xor_b32_e32 v155, 32, v154
	s_lshl_b32 s30, s12, 2
	s_ashr_i32 s31, s30, 31
	s_waitcnt vmcnt(8)
	v_mov_b64_e32 v[156:157], v[180:181]
	v_mov_b64_e32 v[158:159], v[182:183]
	global_load_dwordx4 v[180:183], v179, s[18:19] offset:256
	v_lshlrev_b32_e32 v166, 16, v156
	v_and_b32_e32 v167, 0xffff0000, v156
	v_lshlrev_b32_e32 v156, 16, v157
	v_and_b32_e32 v157, 0xffff0000, v157
	v_lshlrev_b32_e32 v168, 16, v158
	v_and_b32_e32 v169, 0xffff0000, v158
	v_lshlrev_b32_e32 v158, 16, v159
	v_and_b32_e32 v159, 0xffff0000, v159
	v_pk_add_f32 v[126:127], v[126:127], v[156:157]
	v_pk_add_f32 v[166:167], v[124:125], v[166:167]
	v_pk_add_f32 v[170:171], v[122:123], v[158:159]
	v_pk_add_f32 v[168:169], v[120:121], v[168:169]
	v_cvt_pk_bf16_f32 v122, v166, v167
	v_cvt_pk_bf16_f32 v123, v126, v127
	v_mul_f32_e32 v127, v127, v127
	v_cvt_pk_bf16_f32 v124, v168, v169
	v_cvt_pk_bf16_f32 v125, v170, v171
	v_mul_f32_e32 v164, v167, v167
	v_mul_f32_e32 v165, v169, v169
	v_mul_f32_e32 v167, v171, v171
	v_fmac_f32_e32 v164, v166, v166
	v_fmac_f32_e32 v127, v126, v126
	v_fmac_f32_e32 v165, v168, v168
	v_fmac_f32_e32 v167, v170, v170
	v_add_f32_e32 v126, v164, v127
	v_add_f32_e32 v127, v165, v167
	v_add_f32_e32 v166, v126, v127
	v_and_b32_e32 v121, 64, v154
	v_xor_b32_e32 v120, 16, v154
	v_add_u32_e32 v121, 64, v121
	v_cmp_lt_i32_e32 vcc, v120, v121
	global_store_dwordx4 v[162:163], v[122:125], off
	s_waitcnt vmcnt(9)
	v_mov_b64_e32 v[156:157], v[184:185]
	v_mov_b64_e32 v[158:159], v[186:187]
	v_add_u32_e32 v179, 0x90000, v178
	global_load_dwordx4 v[184:187], v179, s[18:19]
	v_lshlrev_b32_e32 v126, 16, v156
	v_and_b32_e32 v127, 0xffff0000, v156
	v_lshlrev_b32_e32 v156, 16, v157
	v_and_b32_e32 v157, 0xffff0000, v157
	v_lshlrev_b32_e32 v164, 16, v158
	v_and_b32_e32 v165, 0xffff0000, v158
	v_lshlrev_b32_e32 v158, 16, v159
	v_and_b32_e32 v159, 0xffff0000, v159
	v_pk_add_f32 v[118:119], v[118:119], v[156:157]
	v_pk_add_f32 v[116:117], v[116:117], v[126:127]
	v_pk_add_f32 v[126:127], v[114:115], v[158:159]
	v_pk_add_f32 v[156:157], v[112:113], v[164:165]
	v_mul_f32_e32 v112, v117, v117
	v_mul_f32_e32 v113, v119, v119
	v_mul_f32_e32 v114, v157, v157
	v_mul_f32_e32 v115, v127, v127
	v_fmac_f32_e32 v112, v116, v116
	v_fmac_f32_e32 v113, v118, v118
	v_fmac_f32_e32 v114, v156, v156
	v_fmac_f32_e32 v115, v126, v126
	v_add_f32_e32 v112, v112, v113
	v_add_f32_e32 v113, v114, v115
	v_cndmask_b32_e32 v120, v154, v120, vcc
	v_add_f32_e32 v112, v112, v113
	v_lshlrev_b32_e32 v120, 2, v120
	v_add_f32_e32 v112, v166, v112
	ds_bpermute_b32 v113, v120, v112
	v_cmp_lt_i32_e32 vcc, v155, v121
	v_lshl_add_u64 v[122:123], s[16:17], 0, v[160:161]
	v_cvt_pk_bf16_f32 v116, v116, v117
	v_cvt_pk_bf16_f32 v117, v118, v119
	s_waitcnt lgkmcnt(0)
	v_add_f32_e32 v112, v112, v113
	v_cndmask_b32_e32 v114, v154, v155, vcc
	v_lshlrev_b32_e32 v114, 2, v114
	ds_bpermute_b32 v113, v114, v112
	v_cvt_pk_bf16_f32 v118, v156, v157
	v_cvt_pk_bf16_f32 v119, v126, v127
	global_store_dwordx4 v[122:123], v[116:119], off
	s_and_saveexec_b64 s[34:35], s[6:7]
	s_cbranch_execz .LBB0_1142
	s_waitcnt lgkmcnt(0)
	v_add_f32_e32 v115, v112, v113
	v_lshlrev_b64 v[112:113], 7, v[146:147]
	v_lshl_add_u64 v[112:113], s[20:21], 0, v[112:113]
	v_lshl_add_u64 v[112:113], s[30:31], 2, v[112:113]
	s_lshl_b32 s12, s57, 2
	v_lshl_add_u64 v[112:113], v[112:113], 0, s[12:13]
	global_store_dword v[112:113], v115, off
.LBB0_1142:
	s_or_b64 exec, exec, s[34:35]
	v_or_b32_e32 v112, 16, v146
	s_waitcnt lgkmcnt(0)
	v_ashrrev_i32_e32 v113, 31, v112
	v_lshlrev_b64 v[116:117], 11, v[112:113]
	v_lshl_add_u64 v[116:117], v[116:117], 0, v[144:145]
	v_lshlrev_b64 v[122:123], 1, v[116:117]
	v_lshl_add_u64 v[116:117], s[18:19], 0, v[122:123]
	v_lshl_add_u64 v[124:125], s[16:17], 0, v[122:123]
	v_or_b32_e32 v122, 0x100, v122
	v_lshl_add_u64 v[126:127], s[18:19], 0, v[122:123]
	s_waitcnt vmcnt(10)
	v_mov_b64_e32 v[116:117], v[188:189]
	v_mov_b64_e32 v[118:119], v[190:191]
	global_load_dwordx4 v[188:191], v179, s[18:19] offset:256
	v_lshlrev_b32_e32 v156, 16, v116
	v_and_b32_e32 v157, 0xffff0000, v116
	v_lshlrev_b32_e32 v116, 16, v117
	v_and_b32_e32 v117, 0xffff0000, v117
	v_lshlrev_b32_e32 v158, 16, v118
	v_and_b32_e32 v159, 0xffff0000, v118
	v_lshlrev_b32_e32 v118, 16, v119
	v_and_b32_e32 v119, 0xffff0000, v119
	v_pk_add_f32 v[116:117], v[110:111], v[116:117]
	v_pk_add_f32 v[156:157], v[108:109], v[156:157]
	v_pk_add_f32 v[118:119], v[106:107], v[118:119]
	v_pk_add_f32 v[158:159], v[104:105], v[158:159]
	v_cvt_pk_bf16_f32 v104, v156, v157
	v_cvt_pk_bf16_f32 v105, v116, v117
	v_mul_f32_e32 v115, v157, v157
	v_cvt_pk_bf16_f32 v106, v158, v159
	v_cvt_pk_bf16_f32 v107, v118, v119
	v_mul_f32_e32 v117, v117, v117
	v_mul_f32_e32 v121, v159, v159
	v_mul_f32_e32 v119, v119, v119
	v_fmac_f32_e32 v115, v156, v156
	v_fmac_f32_e32 v117, v116, v116
	v_fmac_f32_e32 v121, v158, v158
	v_fmac_f32_e32 v119, v118, v118
	v_add_f32_e32 v115, v115, v117
	v_add_f32_e32 v116, v121, v119
	v_add_f32_e32 v115, v115, v116
	global_store_dwordx4 v[124:125], v[104:107], off
	s_waitcnt vmcnt(11)
	v_mov_b64_e32 v[108:109], v[192:193]
	v_mov_b64_e32 v[110:111], v[194:195]
	v_add_u32_e32 v179, 0xa0000, v178
	global_load_dwordx4 v[192:195], v179, s[18:19]
	v_lshlrev_b32_e32 v116, 16, v108
	v_and_b32_e32 v117, 0xffff0000, v108
	v_lshlrev_b32_e32 v108, 16, v109
	v_and_b32_e32 v109, 0xffff0000, v109
	v_lshlrev_b32_e32 v118, 16, v110
	v_and_b32_e32 v119, 0xffff0000, v110
	v_lshlrev_b32_e32 v110, 16, v111
	v_and_b32_e32 v111, 0xffff0000, v111
	v_pk_add_f32 v[102:103], v[102:103], v[108:109]
	v_pk_add_f32 v[100:101], v[100:101], v[116:117]
	v_pk_add_f32 v[108:109], v[98:99], v[110:111]
	v_pk_add_f32 v[110:111], v[96:97], v[118:119]
	v_mul_f32_e32 v96, v101, v101
	v_mul_f32_e32 v97, v103, v103
	v_mul_f32_e32 v98, v111, v111
	v_mul_f32_e32 v99, v109, v109
	v_fmac_f32_e32 v96, v100, v100
	v_fmac_f32_e32 v97, v102, v102
	v_fmac_f32_e32 v98, v110, v110
	v_fmac_f32_e32 v99, v108, v108
	v_add_f32_e32 v96, v96, v97
	v_add_f32_e32 v97, v98, v99
	v_add_f32_e32 v96, v96, v97
	v_add_f32_e32 v96, v115, v96
	ds_bpermute_b32 v97, v120, v96
	v_cvt_pk_bf16_f32 v98, v100, v101
	v_cvt_pk_bf16_f32 v99, v102, v103
	v_lshl_add_u64 v[102:103], s[16:17], 0, v[122:123]
	v_cvt_pk_bf16_f32 v100, v110, v111
	s_waitcnt lgkmcnt(0)
	v_add_f32_e32 v96, v96, v97
	ds_bpermute_b32 v97, v114, v96
	v_cvt_pk_bf16_f32 v101, v108, v109
	global_store_dwordx4 v[102:103], v[98:101], off
	s_and_saveexec_b64 s[34:35], s[6:7]
	s_cbranch_execz .LBB0_1144
	s_waitcnt lgkmcnt(0)
	v_add_f32_e32 v98, v96, v97
	v_lshlrev_b64 v[96:97], 7, v[112:113]
	v_lshl_add_u64 v[96:97], s[20:21], 0, v[96:97]
	v_lshl_add_u64 v[96:97], s[30:31], 2, v[96:97]
	s_lshl_b32 s12, s57, 2
	v_lshl_add_u64 v[96:97], v[96:97], 0, s[12:13]
	global_store_dword v[96:97], v98, off
.LBB0_1144:
	s_or_b64 exec, exec, s[34:35]
	v_or_b32_e32 v96, 32, v146
	s_waitcnt lgkmcnt(0)
	v_ashrrev_i32_e32 v97, 31, v96
	v_lshlrev_b64 v[98:99], 11, v[96:97]
	v_lshl_add_u64 v[98:99], v[98:99], 0, v[144:145]
	v_lshlrev_b64 v[102:103], 1, v[98:99]
	v_lshl_add_u64 v[98:99], s[18:19], 0, v[102:103]
	v_lshl_add_u64 v[104:105], s[16:17], 0, v[102:103]
	v_or_b32_e32 v102, 0x100, v102
	v_lshl_add_u64 v[106:107], s[18:19], 0, v[102:103]
	s_waitcnt vmcnt(12)
	v_mov_b64_e32 v[98:99], v[196:197]
	v_mov_b64_e32 v[100:101], v[198:199]
	global_load_dwordx4 v[196:199], v179, s[18:19] offset:256
	v_lshlrev_b32_e32 v108, 16, v98
	v_and_b32_e32 v109, 0xffff0000, v98
	v_lshlrev_b32_e32 v98, 16, v99
	v_and_b32_e32 v99, 0xffff0000, v99
	v_lshlrev_b32_e32 v110, 16, v100
	v_and_b32_e32 v111, 0xffff0000, v100
	v_lshlrev_b32_e32 v100, 16, v101
	v_and_b32_e32 v101, 0xffff0000, v101
	v_pk_add_f32 v[98:99], v[94:95], v[98:99]
	v_pk_add_f32 v[108:109], v[92:93], v[108:109]
	v_pk_add_f32 v[100:101], v[90:91], v[100:101]
	v_pk_add_f32 v[110:111], v[88:89], v[110:111]
	v_cvt_pk_bf16_f32 v88, v108, v109
	v_cvt_pk_bf16_f32 v89, v98, v99
	v_mul_f32_e32 v99, v99, v99
	v_cvt_pk_bf16_f32 v90, v110, v111
	v_cvt_pk_bf16_f32 v91, v100, v101
	v_mul_f32_e32 v106, v109, v109
	v_mul_f32_e32 v107, v111, v111
	v_mul_f32_e32 v101, v101, v101
	v_fmac_f32_e32 v106, v108, v108
	v_fmac_f32_e32 v99, v98, v98
	v_fmac_f32_e32 v107, v110, v110
	v_fmac_f32_e32 v101, v100, v100
	v_add_f32_e32 v98, v106, v99
	v_add_f32_e32 v99, v107, v101
	v_add_f32_e32 v106, v98, v99
	global_store_dwordx4 v[104:105], v[88:91], off
	s_waitcnt vmcnt(13)
	v_mov_b64_e32 v[92:93], v[200:201]
	v_mov_b64_e32 v[94:95], v[202:203]
	v_add_u32_e32 v179, 0xb0000, v178
	global_load_dwordx4 v[200:203], v179, s[18:19]
	v_lshlrev_b32_e32 v98, 16, v92
	v_and_b32_e32 v99, 0xffff0000, v92
	v_lshlrev_b32_e32 v92, 16, v93
	v_and_b32_e32 v93, 0xffff0000, v93
	v_lshlrev_b32_e32 v100, 16, v94
	v_and_b32_e32 v101, 0xffff0000, v94
	v_lshlrev_b32_e32 v94, 16, v95
	v_and_b32_e32 v95, 0xffff0000, v95
	v_pk_add_f32 v[86:87], v[86:87], v[92:93]
	v_pk_add_f32 v[84:85], v[84:85], v[98:99]
	v_pk_add_f32 v[92:93], v[82:83], v[94:95]
	v_pk_add_f32 v[94:95], v[80:81], v[100:101]
	v_mul_f32_e32 v80, v85, v85
	v_mul_f32_e32 v81, v87, v87
	v_mul_f32_e32 v82, v95, v95
	v_mul_f32_e32 v83, v93, v93
	v_fmac_f32_e32 v80, v84, v84
	v_fmac_f32_e32 v81, v86, v86
	v_fmac_f32_e32 v82, v94, v94
	v_fmac_f32_e32 v83, v92, v92
	v_add_f32_e32 v80, v80, v81
	v_add_f32_e32 v81, v82, v83
	v_add_f32_e32 v80, v80, v81
	v_add_f32_e32 v80, v106, v80
	ds_bpermute_b32 v81, v120, v80
	v_cvt_pk_bf16_f32 v82, v84, v85
	v_cvt_pk_bf16_f32 v83, v86, v87
	v_lshl_add_u64 v[86:87], s[16:17], 0, v[102:103]
	v_cvt_pk_bf16_f32 v84, v94, v95
	s_waitcnt lgkmcnt(0)
	v_add_f32_e32 v80, v80, v81
	ds_bpermute_b32 v81, v114, v80
	v_cvt_pk_bf16_f32 v85, v92, v93
	global_store_dwordx4 v[86:87], v[82:85], off
	s_and_saveexec_b64 s[34:35], s[6:7]
	s_cbranch_execz .LBB0_1146
	s_waitcnt lgkmcnt(0)
	v_add_f32_e32 v82, v80, v81
	v_lshlrev_b64 v[80:81], 7, v[96:97]
	v_lshl_add_u64 v[80:81], s[20:21], 0, v[80:81]
	v_lshl_add_u64 v[80:81], s[30:31], 2, v[80:81]
	s_lshl_b32 s12, s57, 2
	v_lshl_add_u64 v[80:81], v[80:81], 0, s[12:13]
	global_store_dword v[80:81], v82, off
.LBB0_1146:
	s_or_b64 exec, exec, s[34:35]
	v_or_b32_e32 v80, 48, v146
	s_waitcnt lgkmcnt(0)
	v_ashrrev_i32_e32 v81, 31, v80
	v_lshlrev_b64 v[82:83], 11, v[80:81]
	v_lshl_add_u64 v[82:83], v[82:83], 0, v[144:145]
	v_lshlrev_b64 v[86:87], 1, v[82:83]
	v_lshl_add_u64 v[82:83], s[18:19], 0, v[86:87]
	v_lshl_add_u64 v[88:89], s[16:17], 0, v[86:87]
	v_or_b32_e32 v86, 0x100, v86
	v_lshl_add_u64 v[90:91], s[18:19], 0, v[86:87]
	s_waitcnt vmcnt(14)
	v_mov_b64_e32 v[82:83], v[204:205]
	v_mov_b64_e32 v[84:85], v[206:207]
	global_load_dwordx4 v[204:207], v179, s[18:19] offset:256
	v_lshlrev_b32_e32 v92, 16, v82
	v_and_b32_e32 v93, 0xffff0000, v82
	v_lshlrev_b32_e32 v82, 16, v83
	v_and_b32_e32 v83, 0xffff0000, v83
	v_lshlrev_b32_e32 v94, 16, v84
	v_and_b32_e32 v95, 0xffff0000, v84
	v_lshlrev_b32_e32 v84, 16, v85
	v_and_b32_e32 v85, 0xffff0000, v85
	v_pk_add_f32 v[82:83], v[78:79], v[82:83]
	v_pk_add_f32 v[92:93], v[76:77], v[92:93]
	v_pk_add_f32 v[84:85], v[74:75], v[84:85]
	v_pk_add_f32 v[94:95], v[72:73], v[94:95]
	v_cvt_pk_bf16_f32 v72, v92, v93
	v_cvt_pk_bf16_f32 v73, v82, v83
	v_mul_f32_e32 v83, v83, v83
	v_cvt_pk_bf16_f32 v74, v94, v95
	v_cvt_pk_bf16_f32 v75, v84, v85
	v_mul_f32_e32 v90, v93, v93
	v_mul_f32_e32 v91, v95, v95
	v_mul_f32_e32 v85, v85, v85
	v_fmac_f32_e32 v90, v92, v92
	v_fmac_f32_e32 v83, v82, v82
	v_fmac_f32_e32 v91, v94, v94
	v_fmac_f32_e32 v85, v84, v84
	v_add_f32_e32 v82, v90, v83
	v_add_f32_e32 v83, v91, v85
	v_add_f32_e32 v90, v82, v83
	global_store_dwordx4 v[88:89], v[72:75], off
	s_waitcnt vmcnt(15)
	v_mov_b64_e32 v[76:77], v[208:209]
	v_mov_b64_e32 v[78:79], v[210:211]
	v_lshlrev_b32_e32 v82, 16, v76
	v_and_b32_e32 v83, 0xffff0000, v76
	v_lshlrev_b32_e32 v76, 16, v77
	v_and_b32_e32 v77, 0xffff0000, v77
	v_lshlrev_b32_e32 v84, 16, v78
	v_and_b32_e32 v85, 0xffff0000, v78
	v_lshlrev_b32_e32 v78, 16, v79
	v_and_b32_e32 v79, 0xffff0000, v79
	v_pk_add_f32 v[70:71], v[70:71], v[76:77]
	v_pk_add_f32 v[68:69], v[68:69], v[82:83]
	v_pk_add_f32 v[76:77], v[66:67], v[78:79]
	v_pk_add_f32 v[78:79], v[64:65], v[84:85]
	v_mul_f32_e32 v64, v69, v69
	v_mul_f32_e32 v65, v71, v71
	v_mul_f32_e32 v66, v79, v79
	v_mul_f32_e32 v67, v77, v77
	v_fmac_f32_e32 v64, v68, v68
	v_fmac_f32_e32 v65, v70, v70
	v_fmac_f32_e32 v66, v78, v78
	v_fmac_f32_e32 v67, v76, v76
	v_add_f32_e32 v64, v64, v65
	v_add_f32_e32 v65, v66, v67
	v_add_f32_e32 v64, v64, v65
	v_add_f32_e32 v64, v90, v64
	ds_bpermute_b32 v65, v120, v64
	v_cvt_pk_bf16_f32 v66, v68, v69
	v_cvt_pk_bf16_f32 v67, v70, v71
	v_lshl_add_u64 v[70:71], s[16:17], 0, v[86:87]
	v_cvt_pk_bf16_f32 v68, v78, v79
	s_waitcnt lgkmcnt(0)
	v_add_f32_e32 v64, v64, v65
	ds_bpermute_b32 v65, v114, v64
	v_cvt_pk_bf16_f32 v69, v76, v77
	global_store_dwordx4 v[70:71], v[66:69], off
	s_and_saveexec_b64 s[34:35], s[6:7]
	s_cbranch_execz .LBB0_1148
	s_waitcnt lgkmcnt(0)
	v_add_f32_e32 v66, v64, v65
	v_lshlrev_b64 v[64:65], 7, v[80:81]
	v_lshl_add_u64 v[64:65], s[20:21], 0, v[64:65]
	v_lshl_add_u64 v[64:65], s[30:31], 2, v[64:65]
	s_lshl_b32 s12, s57, 2
	v_lshl_add_u64 v[64:65], v[64:65], 0, s[12:13]
	global_store_dword v[64:65], v66, off
.LBB0_1148:
	s_or_b64 exec, exec, s[34:35]
	v_add_u32_e32 v64, 0x80, v146
	s_waitcnt lgkmcnt(0)
	v_ashrrev_i32_e32 v65, 31, v64
	v_lshlrev_b64 v[66:67], 11, v[64:65]
	v_lshl_add_u64 v[66:67], v[66:67], 0, v[144:145]
	v_lshlrev_b64 v[70:71], 1, v[66:67]
	v_lshl_add_u64 v[66:67], s[18:19], 0, v[70:71]
	v_lshl_add_u64 v[72:73], s[16:17], 0, v[70:71]
	v_or_b32_e32 v70, 0x100, v70
	v_lshl_add_u64 v[74:75], s[18:19], 0, v[70:71]
	s_waitcnt vmcnt(15)
	v_mov_b64_e32 v[66:67], v[212:213]
	v_mov_b64_e32 v[68:69], v[214:215]
	v_lshlrev_b32_e32 v76, 16, v66
	v_and_b32_e32 v77, 0xffff0000, v66
	v_lshlrev_b32_e32 v66, 16, v67
	v_and_b32_e32 v67, 0xffff0000, v67
	v_lshlrev_b32_e32 v78, 16, v68
	v_and_b32_e32 v79, 0xffff0000, v68
	v_lshlrev_b32_e32 v68, 16, v69
	v_and_b32_e32 v69, 0xffff0000, v69
	v_pk_add_f32 v[66:67], v[62:63], v[66:67]
	v_pk_add_f32 v[76:77], v[60:61], v[76:77]
	v_pk_add_f32 v[68:69], v[58:59], v[68:69]
	v_pk_add_f32 v[78:79], v[56:57], v[78:79]
	v_cvt_pk_bf16_f32 v56, v76, v77
	v_cvt_pk_bf16_f32 v57, v66, v67
	v_mul_f32_e32 v67, v67, v67
	v_cvt_pk_bf16_f32 v58, v78, v79
	v_cvt_pk_bf16_f32 v59, v68, v69
	v_mul_f32_e32 v74, v77, v77
	v_mul_f32_e32 v75, v79, v79
	v_mul_f32_e32 v69, v69, v69
	v_fmac_f32_e32 v74, v76, v76
	v_fmac_f32_e32 v67, v66, v66
	v_fmac_f32_e32 v75, v78, v78
	v_fmac_f32_e32 v69, v68, v68
	v_add_f32_e32 v66, v74, v67
	v_add_f32_e32 v67, v75, v69
	v_add_f32_e32 v74, v66, v67
	global_store_dwordx4 v[72:73], v[56:59], off
	s_waitcnt vmcnt(15)
	v_mov_b64_e32 v[60:61], v[180:181]
	v_mov_b64_e32 v[62:63], v[182:183]
	v_lshlrev_b32_e32 v66, 16, v60
	v_and_b32_e32 v67, 0xffff0000, v60
	v_lshlrev_b32_e32 v60, 16, v61
	v_and_b32_e32 v61, 0xffff0000, v61
	v_lshlrev_b32_e32 v68, 16, v62
	v_and_b32_e32 v69, 0xffff0000, v62
	v_lshlrev_b32_e32 v62, 16, v63
	v_and_b32_e32 v63, 0xffff0000, v63
	v_pk_add_f32 v[54:55], v[54:55], v[60:61]
	v_pk_add_f32 v[52:53], v[52:53], v[66:67]
	v_pk_add_f32 v[60:61], v[50:51], v[62:63]
	v_pk_add_f32 v[62:63], v[48:49], v[68:69]
	v_mul_f32_e32 v48, v53, v53
	v_mul_f32_e32 v49, v55, v55
	v_mul_f32_e32 v50, v63, v63
	v_mul_f32_e32 v51, v61, v61
	v_fmac_f32_e32 v48, v52, v52
	v_fmac_f32_e32 v49, v54, v54
	v_fmac_f32_e32 v50, v62, v62
	v_fmac_f32_e32 v51, v60, v60
	v_add_f32_e32 v48, v48, v49
	v_add_f32_e32 v49, v50, v51
	v_add_f32_e32 v48, v48, v49
	v_add_f32_e32 v48, v74, v48
	ds_bpermute_b32 v49, v120, v48
	v_cvt_pk_bf16_f32 v50, v52, v53
	v_cvt_pk_bf16_f32 v51, v54, v55
	v_lshl_add_u64 v[54:55], s[16:17], 0, v[70:71]
	v_cvt_pk_bf16_f32 v52, v62, v63
	s_waitcnt lgkmcnt(0)
	v_add_f32_e32 v48, v48, v49
	ds_bpermute_b32 v49, v114, v48
	v_cvt_pk_bf16_f32 v53, v60, v61
	global_store_dwordx4 v[54:55], v[50:53], off
	s_and_saveexec_b64 s[34:35], s[6:7]
	s_cbranch_execz .LBB0_1150
	s_waitcnt lgkmcnt(0)
	v_add_f32_e32 v50, v48, v49
	v_lshlrev_b64 v[48:49], 7, v[64:65]
	v_lshl_add_u64 v[48:49], s[20:21], 0, v[48:49]
	v_lshl_add_u64 v[48:49], s[30:31], 2, v[48:49]
	s_lshl_b32 s12, s57, 2
	v_lshl_add_u64 v[48:49], v[48:49], 0, s[12:13]
	global_store_dword v[48:49], v50, off
.LBB0_1150:
	s_or_b64 exec, exec, s[34:35]
	v_add_u32_e32 v48, 0x90, v146
	s_waitcnt lgkmcnt(0)
	v_ashrrev_i32_e32 v49, 31, v48
	v_lshlrev_b64 v[50:51], 11, v[48:49]
	v_lshl_add_u64 v[50:51], v[50:51], 0, v[144:145]
	v_lshlrev_b64 v[54:55], 1, v[50:51]
	v_lshl_add_u64 v[50:51], s[18:19], 0, v[54:55]
	v_lshl_add_u64 v[56:57], s[16:17], 0, v[54:55]
	v_or_b32_e32 v54, 0x100, v54
	v_lshl_add_u64 v[58:59], s[18:19], 0, v[54:55]
	s_waitcnt vmcnt(14)
	v_mov_b64_e32 v[50:51], v[184:185]
	v_mov_b64_e32 v[52:53], v[186:187]
	v_lshlrev_b32_e32 v60, 16, v50
	v_and_b32_e32 v61, 0xffff0000, v50
	v_lshlrev_b32_e32 v50, 16, v51
	v_and_b32_e32 v51, 0xffff0000, v51
	v_lshlrev_b32_e32 v62, 16, v52
	v_and_b32_e32 v63, 0xffff0000, v52
	v_lshlrev_b32_e32 v52, 16, v53
	v_and_b32_e32 v53, 0xffff0000, v53
	v_pk_add_f32 v[50:51], v[46:47], v[50:51]
	v_pk_add_f32 v[60:61], v[44:45], v[60:61]
	v_pk_add_f32 v[52:53], v[42:43], v[52:53]
	v_pk_add_f32 v[62:63], v[40:41], v[62:63]
	v_cvt_pk_bf16_f32 v40, v60, v61
	v_cvt_pk_bf16_f32 v41, v50, v51
	v_mul_f32_e32 v51, v51, v51
	v_cvt_pk_bf16_f32 v42, v62, v63
	v_cvt_pk_bf16_f32 v43, v52, v53
	v_mul_f32_e32 v58, v61, v61
	v_mul_f32_e32 v59, v63, v63
	v_mul_f32_e32 v53, v53, v53
	v_fmac_f32_e32 v58, v60, v60
	v_fmac_f32_e32 v51, v50, v50
	v_fmac_f32_e32 v59, v62, v62
	v_fmac_f32_e32 v53, v52, v52
	v_add_f32_e32 v50, v58, v51
	v_add_f32_e32 v51, v59, v53
	v_add_f32_e32 v58, v50, v51
	global_store_dwordx4 v[56:57], v[40:43], off
	s_waitcnt vmcnt(13)
	v_mov_b64_e32 v[44:45], v[188:189]
	v_mov_b64_e32 v[46:47], v[190:191]
	v_lshlrev_b32_e32 v50, 16, v44
	v_and_b32_e32 v51, 0xffff0000, v44
	v_lshlrev_b32_e32 v44, 16, v45
	v_and_b32_e32 v45, 0xffff0000, v45
	v_lshlrev_b32_e32 v52, 16, v46
	v_and_b32_e32 v53, 0xffff0000, v46
	v_lshlrev_b32_e32 v46, 16, v47
	v_and_b32_e32 v47, 0xffff0000, v47
	v_pk_add_f32 v[38:39], v[38:39], v[44:45]
	v_pk_add_f32 v[36:37], v[36:37], v[50:51]
	v_pk_add_f32 v[44:45], v[34:35], v[46:47]
	v_pk_add_f32 v[46:47], v[32:33], v[52:53]
	v_mul_f32_e32 v32, v37, v37
	v_mul_f32_e32 v33, v39, v39
	v_mul_f32_e32 v34, v47, v47
	v_mul_f32_e32 v35, v45, v45
	v_fmac_f32_e32 v32, v36, v36
	v_fmac_f32_e32 v33, v38, v38
	v_fmac_f32_e32 v34, v46, v46
	v_fmac_f32_e32 v35, v44, v44
	v_add_f32_e32 v32, v32, v33
	v_add_f32_e32 v33, v34, v35
	v_add_f32_e32 v32, v32, v33
	v_add_f32_e32 v32, v58, v32
	ds_bpermute_b32 v33, v120, v32
	v_cvt_pk_bf16_f32 v34, v36, v37
	v_cvt_pk_bf16_f32 v35, v38, v39
	v_lshl_add_u64 v[38:39], s[16:17], 0, v[54:55]
	v_cvt_pk_bf16_f32 v36, v46, v47
	s_waitcnt lgkmcnt(0)
	v_add_f32_e32 v32, v32, v33
	ds_bpermute_b32 v33, v114, v32
	v_cvt_pk_bf16_f32 v37, v44, v45
	global_store_dwordx4 v[38:39], v[34:37], off
	s_and_saveexec_b64 s[34:35], s[6:7]
	s_cbranch_execz .LBB0_1152
	s_waitcnt lgkmcnt(0)
	v_add_f32_e32 v34, v32, v33
	v_lshlrev_b64 v[32:33], 7, v[48:49]
	v_lshl_add_u64 v[32:33], s[20:21], 0, v[32:33]
	v_lshl_add_u64 v[32:33], s[30:31], 2, v[32:33]
	s_lshl_b32 s12, s57, 2
	v_lshl_add_u64 v[32:33], v[32:33], 0, s[12:13]
	global_store_dword v[32:33], v34, off
.LBB0_1152:
	s_or_b64 exec, exec, s[34:35]
	v_add_u32_e32 v32, 0xa0, v146
	s_waitcnt lgkmcnt(0)
	v_ashrrev_i32_e32 v33, 31, v32
	v_lshlrev_b64 v[34:35], 11, v[32:33]
	v_lshl_add_u64 v[34:35], v[34:35], 0, v[144:145]
	v_lshlrev_b64 v[38:39], 1, v[34:35]
	v_lshl_add_u64 v[34:35], s[18:19], 0, v[38:39]
	v_lshl_add_u64 v[40:41], s[16:17], 0, v[38:39]
	v_or_b32_e32 v38, 0x100, v38
	v_lshl_add_u64 v[42:43], s[18:19], 0, v[38:39]
	s_waitcnt vmcnt(12)
	v_mov_b64_e32 v[34:35], v[192:193]
	v_mov_b64_e32 v[36:37], v[194:195]
	v_lshlrev_b32_e32 v44, 16, v34
	v_and_b32_e32 v45, 0xffff0000, v34
	v_lshlrev_b32_e32 v34, 16, v35
	v_and_b32_e32 v35, 0xffff0000, v35
	v_lshlrev_b32_e32 v46, 16, v36
	v_and_b32_e32 v47, 0xffff0000, v36
	v_lshlrev_b32_e32 v36, 16, v37
	v_and_b32_e32 v37, 0xffff0000, v37
	v_pk_add_f32 v[34:35], v[30:31], v[34:35]
	v_pk_add_f32 v[44:45], v[28:29], v[44:45]
	v_pk_add_f32 v[36:37], v[26:27], v[36:37]
	v_pk_add_f32 v[46:47], v[24:25], v[46:47]
	v_cvt_pk_bf16_f32 v24, v44, v45
	v_cvt_pk_bf16_f32 v25, v34, v35
	v_mul_f32_e32 v35, v35, v35
	v_cvt_pk_bf16_f32 v26, v46, v47
	v_cvt_pk_bf16_f32 v27, v36, v37
	v_mul_f32_e32 v42, v45, v45
	v_mul_f32_e32 v43, v47, v47
	v_mul_f32_e32 v37, v37, v37
	v_fmac_f32_e32 v42, v44, v44
	v_fmac_f32_e32 v35, v34, v34
	v_fmac_f32_e32 v43, v46, v46
	v_fmac_f32_e32 v37, v36, v36
	v_add_f32_e32 v34, v42, v35
	v_add_f32_e32 v35, v43, v37
	v_add_f32_e32 v42, v34, v35
	global_store_dwordx4 v[40:41], v[24:27], off
	s_waitcnt vmcnt(11)
	v_mov_b64_e32 v[28:29], v[196:197]
	v_mov_b64_e32 v[30:31], v[198:199]
	v_lshlrev_b32_e32 v34, 16, v28
	v_and_b32_e32 v35, 0xffff0000, v28
	v_lshlrev_b32_e32 v28, 16, v29
	v_and_b32_e32 v29, 0xffff0000, v29
	v_lshlrev_b32_e32 v36, 16, v30
	v_and_b32_e32 v37, 0xffff0000, v30
	v_lshlrev_b32_e32 v30, 16, v31
	v_and_b32_e32 v31, 0xffff0000, v31
	v_pk_add_f32 v[22:23], v[22:23], v[28:29]
	v_pk_add_f32 v[20:21], v[20:21], v[34:35]
	v_pk_add_f32 v[28:29], v[18:19], v[30:31]
	v_pk_add_f32 v[30:31], v[16:17], v[36:37]
	v_mul_f32_e32 v16, v21, v21
	v_mul_f32_e32 v17, v23, v23
	v_mul_f32_e32 v18, v31, v31
	v_mul_f32_e32 v19, v29, v29
	v_fmac_f32_e32 v16, v20, v20
	v_fmac_f32_e32 v17, v22, v22
	v_fmac_f32_e32 v18, v30, v30
	v_fmac_f32_e32 v19, v28, v28
	v_add_f32_e32 v16, v16, v17
	v_add_f32_e32 v17, v18, v19
	v_add_f32_e32 v16, v16, v17
	v_add_f32_e32 v16, v42, v16
	ds_bpermute_b32 v17, v120, v16
	v_cvt_pk_bf16_f32 v18, v20, v21
	v_cvt_pk_bf16_f32 v19, v22, v23
	v_lshl_add_u64 v[22:23], s[16:17], 0, v[38:39]
	v_cvt_pk_bf16_f32 v20, v30, v31
	s_waitcnt lgkmcnt(0)
	v_add_f32_e32 v16, v16, v17
	ds_bpermute_b32 v17, v114, v16
	v_cvt_pk_bf16_f32 v21, v28, v29
	global_store_dwordx4 v[22:23], v[18:21], off
	s_and_saveexec_b64 s[34:35], s[6:7]
	s_cbranch_execz .LBB0_1154
	s_waitcnt lgkmcnt(0)
	v_add_f32_e32 v18, v16, v17
	v_lshlrev_b64 v[16:17], 7, v[32:33]
	v_lshl_add_u64 v[16:17], s[20:21], 0, v[16:17]
	v_lshl_add_u64 v[16:17], s[30:31], 2, v[16:17]
	s_lshl_b32 s12, s57, 2
	v_lshl_add_u64 v[16:17], v[16:17], 0, s[12:13]
	global_store_dword v[16:17], v18, off
.LBB0_1154:
	s_or_b64 exec, exec, s[34:35]
	v_add_u32_e32 v16, 0xb0, v146
	s_waitcnt lgkmcnt(0)
	v_ashrrev_i32_e32 v17, 31, v16
	v_lshlrev_b64 v[18:19], 11, v[16:17]
	v_lshl_add_u64 v[18:19], v[18:19], 0, v[144:145]
	v_lshlrev_b64 v[22:23], 1, v[18:19]
	v_lshl_add_u64 v[18:19], s[18:19], 0, v[22:23]
	v_lshl_add_u64 v[24:25], s[16:17], 0, v[22:23]
	v_or_b32_e32 v22, 0x100, v22
	v_lshl_add_u64 v[26:27], s[18:19], 0, v[22:23]
	s_waitcnt vmcnt(10)
	v_mov_b64_e32 v[18:19], v[200:201]
	v_mov_b64_e32 v[20:21], v[202:203]
	v_lshlrev_b32_e32 v28, 16, v18
	v_and_b32_e32 v29, 0xffff0000, v18
	v_lshlrev_b32_e32 v18, 16, v19
	v_and_b32_e32 v19, 0xffff0000, v19
	v_lshlrev_b32_e32 v30, 16, v20
	v_and_b32_e32 v31, 0xffff0000, v20
	v_lshlrev_b32_e32 v20, 16, v21
	v_and_b32_e32 v21, 0xffff0000, v21
	v_pk_add_f32 v[18:19], v[14:15], v[18:19]
	v_pk_add_f32 v[28:29], v[12:13], v[28:29]
	v_pk_add_f32 v[20:21], v[10:11], v[20:21]
	v_pk_add_f32 v[30:31], v[8:9], v[30:31]
	v_cvt_pk_bf16_f32 v8, v28, v29
	v_cvt_pk_bf16_f32 v9, v18, v19
	v_mul_f32_e32 v19, v19, v19
	v_cvt_pk_bf16_f32 v10, v30, v31
	v_cvt_pk_bf16_f32 v11, v20, v21
	v_mul_f32_e32 v26, v29, v29
	v_mul_f32_e32 v27, v31, v31
	v_mul_f32_e32 v21, v21, v21
	v_fmac_f32_e32 v26, v28, v28
	v_fmac_f32_e32 v19, v18, v18
	v_fmac_f32_e32 v27, v30, v30
	v_fmac_f32_e32 v21, v20, v20
	v_add_f32_e32 v18, v26, v19
	v_add_f32_e32 v19, v27, v21
	v_add_f32_e32 v26, v18, v19
	global_store_dwordx4 v[24:25], v[8:11], off
	s_waitcnt vmcnt(9)
	v_mov_b64_e32 v[12:13], v[204:205]
	v_mov_b64_e32 v[14:15], v[206:207]
	v_lshlrev_b32_e32 v18, 16, v12
	v_and_b32_e32 v19, 0xffff0000, v12
	v_lshlrev_b32_e32 v12, 16, v13
	v_and_b32_e32 v13, 0xffff0000, v13
	v_lshlrev_b32_e32 v20, 16, v14
	v_and_b32_e32 v21, 0xffff0000, v14
	v_lshlrev_b32_e32 v14, 16, v15
	v_and_b32_e32 v15, 0xffff0000, v15
	v_pk_add_f32 v[6:7], v[6:7], v[12:13]
	v_pk_add_f32 v[4:5], v[4:5], v[18:19]
	v_pk_add_f32 v[12:13], v[2:3], v[14:15]
	v_pk_add_f32 v[14:15], v[0:1], v[20:21]
	v_mul_f32_e32 v0, v5, v5
	v_mul_f32_e32 v1, v7, v7
	v_mul_f32_e32 v2, v15, v15
	v_mul_f32_e32 v3, v13, v13
	v_fmac_f32_e32 v0, v4, v4
	v_fmac_f32_e32 v1, v6, v6
	v_fmac_f32_e32 v2, v14, v14
	v_fmac_f32_e32 v3, v12, v12
	v_add_f32_e32 v0, v0, v1
	v_add_f32_e32 v1, v2, v3
	v_add_f32_e32 v0, v0, v1
	v_add_f32_e32 v0, v26, v0
	ds_bpermute_b32 v1, v120, v0
	v_cvt_pk_bf16_f32 v2, v4, v5
	v_cvt_pk_bf16_f32 v3, v6, v7
	v_lshl_add_u64 v[6:7], s[16:17], 0, v[22:23]
	v_cvt_pk_bf16_f32 v4, v14, v15
	s_waitcnt lgkmcnt(0)
	v_add_f32_e32 v0, v0, v1
	ds_bpermute_b32 v1, v114, v0
	v_cvt_pk_bf16_f32 v5, v12, v13
	global_store_dwordx4 v[6:7], v[2:5], off
	s_and_saveexec_b64 s[34:35], s[6:7]
	s_cbranch_execz .LBB0_1156
	s_waitcnt lgkmcnt(0)
	v_add_f32_e32 v2, v0, v1
	v_lshlrev_b64 v[0:1], 7, v[16:17]
	v_lshl_add_u64 v[0:1], s[20:21], 0, v[0:1]
	v_lshl_add_u64 v[0:1], s[30:31], 2, v[0:1]
	s_lshl_b32 s12, s57, 2
	v_lshl_add_u64 v[0:1], v[0:1], 0, s[12:13]
	global_store_dword v[0:1], v2, off

	.amdhsa_kernel _Z6mk_fwd6Params
		.amdhsa_group_segment_fixed_size 0
		.amdhsa_private_segment_fixed_size 0
		.amdhsa_kernarg_size 488
		.amdhsa_user_sgpr_count 2
		.amdhsa_user_sgpr_dispatch_ptr 0
		.amdhsa_user_sgpr_queue_ptr 0
		.amdhsa_user_sgpr_kernarg_segment_ptr 1
		.amdhsa_user_sgpr_dispatch_id 0
		.amdhsa_user_sgpr_kernarg_preload_length 0
		.amdhsa_user_sgpr_kernarg_preload_offset 0
		.amdhsa_user_sgpr_private_segment_size 0
		.amdhsa_uses_dynamic_stack 0
		.amdhsa_enable_private_segment 0
		.amdhsa_system_sgpr_workgroup_id_x 1
		.amdhsa_system_sgpr_workgroup_id_y 0
		.amdhsa_system_sgpr_workgroup_id_z 0
		.amdhsa_system_sgpr_workgroup_info 0
		.amdhsa_system_vgpr_workitem_id 2
		.amdhsa_next_free_vgpr 256
		.amdhsa_next_free_sgpr 102
		.amdhsa_accum_offset 256
		.amdhsa_reserve_vcc 1
		.amdhsa_float_round_mode_32 0
		.amdhsa_float_round_mode_16_64 0
		.amdhsa_float_denorm_mode_32 3
		.amdhsa_float_denorm_mode_16_64 3
		.amdhsa_dx10_clamp 1
		.amdhsa_ieee_mode 1
		.amdhsa_fp16_overflow 0
		.amdhsa_tg_split 0
		.amdhsa_exception_fp_ieee_invalid_op 0
		.amdhsa_exception_fp_denorm_src 0
		.amdhsa_exception_fp_ieee_div_zero 0
		.amdhsa_exception_fp_ieee_overflow 0
		.amdhsa_exception_fp_ieee_underflow 0
		.amdhsa_exception_fp_ieee_inexact 0
		.amdhsa_exception_int_div_zero 0
	.end_amdhsa_kernel

amdhsa.kernels:
  - .agpr_count:     0
    .args:
      - .offset:         0
        .size:           232
        .value_kind:     by_value
      - .offset:         232
        .size:           4
        .value_kind:     hidden_block_count_x
      - .offset:         236
        .size:           4
        .value_kind:     hidden_block_count_y
      - .offset:         240
        .size:           4
        .value_kind:     hidden_block_count_z
      - .offset:         244
        .size:           2
        .value_kind:     hidden_group_size_x
      - .offset:         246
        .size:           2
        .value_kind:     hidden_group_size_y
      - .offset:         248
        .size:           2
        .value_kind:     hidden_group_size_z
      - .offset:         250
        .size:           2
        .value_kind:     hidden_remainder_x
      - .offset:         252
        .size:           2
        .value_kind:     hidden_remainder_y
      - .offset:         254
        .size:           2
        .value_kind:     hidden_remainder_z
      - .offset:         272
        .size:           8
        .value_kind:     hidden_global_offset_x
      - .offset:         280
        .size:           8
        .value_kind:     hidden_global_offset_y
      - .offset:         288
        .size:           8
        .value_kind:     hidden_global_offset_z
      - .offset:         296
        .size:           2
        .value_kind:     hidden_grid_dims
      - .offset:         320
        .size:           8
        .value_kind:     hidden_multigrid_sync_arg
      - .offset:         352
        .size:           4
        .value_kind:     hidden_dynamic_lds_size
    .group_segment_fixed_size: 0
    .kernarg_segment_align: 8
    .kernarg_segment_size: 488
    .language:       OpenCL C
    .language_version:
      - 2
      - 0
    .max_flat_workgroup_size: 512
    .name:           _Z6mk_fwd6Params
    .private_segment_fixed_size: 0
    .sgpr_count:     108
    .sgpr_spill_count: 13
    .symbol:         _Z6mk_fwd6Params.kd
    .uniform_work_group_size: 1
    .uses_dynamic_stack: false
    .vgpr_count:     256
    .vgpr_spill_count: 0
    .wavefront_size: 64
